# ret_sample S0 loads hoisted (+first item before ret_scan), ret_out gate tail hand-rewritten (batched LDS reads, DPP row sums, packed sigmoid), attention reductions via permlane swaps + single reciproc
# baseline (speedup 1.0000x reference)
; DEV bf16_t f2bf(float f) { return (bf16_t)(cvt_pk_bf16(f, 0.f) & 0xffffu); }
; DEV float bf2f(unsigned h) { return __uint_as_float(h << 16); }
; DEV float sigmoidf_(float x) { return 1.0f / (1.0f + __expf(-x)); }
; DEV void ret_out_item(const Params& p, int l, int item, unsigned char* smem) {
;     ...
;   float ss[4] = {0.f, 0.f, 0.f, 0.f};
; #pragma unroll
;   for (int j = 0; j < 4; ++j) {
;     const float qd = __expf(lg * (float)(w * 16 + fq * 4 + j + 1));
; #pragma unroll
;     for (int et = 0; et < 8; ++et) { const float o = a1[et][j] + qd * a2[et][j]; a1[et][j] = o; ss[j] += o * o; }
;   }
; #pragma unroll
;   for (int j = 0; j < 4; ++j) {
;     float v = ss[j];
;     v += __shfl_xor(v, 1); v += __shfl_xor(v, 2); v += __shfl_xor(v, 4); v += __shfl_xor(v, 8);
;     const float rstd = rsqrtf(v * (1.0f / 128.0f) + 1e-6f);
;     bf16_t* gp = Gs + (w * 16 + fq * 4 + j) * 136 + fr;
; #pragma unroll
;     for (int et = 0; et < 8; ++et) {
;       const float g = bf2f(gp[et * 16]);
;       gp[et * 16] = f2bf(g * sigmoidf_(g) * a1[et][j] * rstd);
.LBB0_84:
	s_or_b64 exec, exec, s[0:1]
	v_or_b32_e32 v77, v83, v80
	v_or_b32_e32 v64, 1, v77
	v_cvt_f32_i32_e32 v64, v64
	v_mov_b32_e32 v65, v8
	v_or_b32_e32 v8, 2, v77
	v_cvt_f32_i32_e32 v8, v8
	v_mul_f32_e32 v64, v90, v64
	v_mul_f32_e32 v64, 0x3fb8aa3b, v64
	v_exp_f32_e32 v74, v64
	v_mul_f32_e32 v8, v90, v8
	v_mul_f32_e32 v8, 0x3fb8aa3b, v8
	v_mov_b32_e32 v64, v12
	v_exp_f32_e32 v12, v8
	v_mov_b32_e32 v66, v60
	v_mov_b32_e32 v67, v56
	v_pk_fma_f32 v[88:89], v[64:65], v[74:75], v[66:67] op_sel_hi:[1,0,1]
	v_mov_b32_e32 v64, v20
	v_mov_b32_e32 v65, v16
	v_mov_b32_e32 v68, v48
	v_mov_b32_e32 v69, v40
	v_pk_fma_f32 v[86:87], v[64:65], v[74:75], v[68:69] op_sel_hi:[1,0,1]
	v_mov_b32_e32 v64, v28
	v_mov_b32_e32 v65, v24
	v_mov_b32_e32 v68, v52
	v_mov_b32_e32 v69, v44
	v_pk_fma_f32 v[84:85], v[64:65], v[74:75], v[68:69] op_sel_hi:[1,0,1]
	v_mov_b32_e32 v75, v12
	v_mov_b32_e32 v56, v61
	v_pk_fma_f32 v[60:61], v[4:5], v[74:75], v[36:37]
	v_pk_fma_f32 v[64:65], v[0:1], v[74:75], v[32:33]
	v_pk_mul_f32 v[0:1], v[60:61], v[60:61]
	v_mov_b32_e32 v8, v13
	v_pk_fma_f32 v[82:83], v[64:65], v[64:65], v[0:1]
	v_or_b32_e32 v0, 3, v77
	v_cvt_f32_i32_e32 v0, v0
	v_pk_fma_f32 v[56:57], v[8:9], v[12:13], v[56:57] op_sel_hi:[1,0,1]
	v_mov_b32_e32 v4, v14
	v_mov_b32_e32 v5, v10
	v_mul_f32_e32 v0, v90, v0
	v_mul_f32_e32 v0, 0x3fb8aa3b, v0
	v_exp_f32_e32 v0, v0
	v_mov_b32_e32 v8, v62
	v_mov_b32_e32 v9, v58
	v_mov_b32_e32 v24, v29
	v_pk_fma_f32 v[36:37], v[4:5], v[0:1], v[8:9] op_sel_hi:[1,0,1]
	v_mov_b32_e32 v4, v22
	v_mov_b32_e32 v5, v18
	v_mov_b32_e32 v8, v50
	v_mov_b32_e32 v9, v42
	v_pk_fma_f32 v[32:33], v[4:5], v[0:1], v[8:9] op_sel_hi:[1,0,1]
	v_mov_b32_e32 v4, v30
	v_mov_b32_e32 v5, v26
	v_mov_b32_e32 v8, v54
	v_mov_b32_e32 v9, v46
	v_pk_fma_f32 v[28:29], v[4:5], v[0:1], v[8:9] op_sel_hi:[1,0,1]
	v_add_u32_e32 v1, 4, v77
	v_cvt_f32_i32_e32 v1, v1
	v_mov_b32_e32 v18, v23
	v_and_b32_e32 v23, 64, v202
	v_xor_b32_e32 v22, 1, v202
	v_mul_f32_e32 v1, v90, v1
	v_mul_f32_e32 v1, 0x3fb8aa3b, v1
	v_exp_f32_e32 v14, v1
	v_add_u32_e32 v23, 64, v23
	v_cmp_lt_i32_e32 vcc, v22, v23
	v_mov_b32_e32 v26, v31
	v_mov_b32_e32 v1, v14
	v_cndmask_b32_e32 v22, v202, v22, vcc
	v_pk_fma_f32 v[8:9], v[2:3], v[0:1], v[34:35]
	v_lshlrev_b32_e32 v34, 2, v22
	v_xor_b32_e32 v22, 2, v202
	v_cmp_lt_i32_e32 vcc, v22, v23
	v_pk_fma_f32 v[6:7], v[6:7], v[0:1], v[38:39]
	v_mov_b32_e32 v16, v21
	v_cndmask_b32_e32 v22, v202, v22, vcc
	v_lshlrev_b32_e32 v31, 2, v22
	v_xor_b32_e32 v22, 4, v202
	v_cmp_lt_i32_e32 vcc, v22, v23
	v_mov_b32_e32 v40, v49
	v_mov_b32_e32 v44, v53
	v_cndmask_b32_e32 v22, v202, v22, vcc
	v_lshlrev_b32_e32 v30, 2, v22
	v_xor_b32_e32 v22, 8, v202
	v_cmp_lt_i32_e32 vcc, v22, v23
	v_pk_mul_f32 v[0:1], v[6:7], v[6:7]
	v_mov_b32_e32 v46, v55
	v_cndmask_b32_e32 v22, v202, v22, vcc
	s_movk_i32 s13, 0x110
	v_pk_fma_f32 v[48:49], v[16:17], v[12:13], v[40:41] op_sel_hi:[1,0,1]
	v_pk_fma_f32 v[40:41], v[24:25], v[12:13], v[44:45] op_sel_hi:[1,0,1]
	v_pk_fma_f32 v[24:25], v[8:9], v[8:9], v[0:1]
	v_pk_fma_f32 v[0:1], v[26:27], v[14:15], v[46:47] op_sel_hi:[1,0,1]
	v_lshlrev_b32_e32 v27, 2, v22
	v_lshlrev_b32_e32 v22, 1, v81
	v_mul_lo_u32 v23, v77, s13
	v_readlane_b32 s12, v248, 15
	v_mov_b32_e32 v42, v51
	v_pk_fma_f32 v[2:3], v[18:19], v[14:15], v[42:43] op_sel_hi:[1,0,1]
	v_add3_u32 v26, s12, v22, v23
	ds_read_u16 v96, v26
	ds_read_u16 v97, v26 offset:272
	ds_read_u16 v98, v26 offset:32
	ds_read_u16 v99, v26 offset:304
	ds_read_u16 v100, v26 offset:96
	ds_read_u16 v101, v26 offset:64
	ds_read_u16 v102, v26 offset:160
	ds_read_u16 v103, v26 offset:128
	ds_read_u16 v104, v26 offset:224
	ds_read_u16 v105, v26 offset:192
	ds_read_u16 v106, v26 offset:368
	ds_read_u16 v107, v26 offset:336
	ds_read_u16 v108, v26 offset:432
	ds_read_u16 v109, v26 offset:400
	ds_read_u16 v110, v26 offset:496
	ds_read_u16 v111, v26 offset:464
	ds_read_u16 v112, v26 offset:544
	ds_read_u16 v113, v26 offset:816
	ds_read_u16 v114, v26 offset:576
	ds_read_u16 v115, v26 offset:848
	ds_read_u16 v116, v26 offset:640
	ds_read_u16 v117, v26 offset:608
	ds_read_u16 v118, v26 offset:704
	ds_read_u16 v119, v26 offset:672
	ds_read_u16 v120, v26 offset:768
	ds_read_u16 v121, v26 offset:736
	ds_read_u16 v122, v26 offset:912
	ds_read_u16 v123, v26 offset:880
	ds_read_u16 v124, v26 offset:976
	ds_read_u16 v125, v26 offset:944
	ds_read_u16 v126, v26 offset:1040
	ds_read_u16 v127, v26 offset:1008
	v_pk_mul_f32 v[66:67], v[88:89], v[88:89]
	v_pk_mul_f32 v[72:73], v[56:57], v[56:57]
	v_pk_mul_f32 v[70:71], v[86:87], v[86:87]
	v_pk_mul_f32 v[74:75], v[48:49], v[48:49]
	v_pk_mul_f32 v[68:69], v[84:85], v[84:85]
	v_pk_mul_f32 v[44:45], v[40:41], v[40:41]
	v_pk_mul_f32 v[20:21], v[36:37], v[36:37]
	v_pk_mul_f32 v[16:17], v[32:33], v[32:33]
	v_pk_mul_f32 v[12:13], v[28:29], v[28:29]
	v_mov_b32_e32 v10, v15
	v_mov_b32_e32 v58, v63
	v_pk_fma_f32 v[4:5], v[10:11], v[14:15], v[58:59] op_sel_hi:[1,0,1]
	v_pk_mul_f32 v[18:19], v[2:3], v[2:3]
	v_pk_mul_f32 v[10:11], v[4:5], v[4:5]
	v_pk_mul_f32 v[14:15], v[0:1], v[0:1]
	v_ashrrev_i32_e32 v81, 31, v80
	s_lshl_b32 s6, s6, 1
	v_mov_b32_e32 v77, v169
	v_mov_b32_e32 v23, v66
	v_mov_b32_e32 v66, v73
	v_mov_b32_e32 v22, v72
	v_pk_add_f32 v[50:51], v[66:67], v[82:83] op_sel:[0,1] op_sel_hi:[1,0]
	s_nop 0
	v_pk_add_f32 v[22:23], v[22:23], v[50:51]
	v_mov_b32_e32 v50, v75
	v_mov_b32_e32 v51, v71
	v_pk_add_f32 v[22:23], v[50:51], v[22:23]
	v_mov_b32_e32 v75, v70
	v_pk_add_f32 v[22:23], v[74:75], v[22:23]
	v_mov_b32_e32 v50, v45
	v_mov_b32_e32 v51, v69
	v_pk_add_f32 v[22:23], v[50:51], v[22:23]
	v_mov_b32_e32 v45, v68
	v_pk_add_f32 v[22:23], v[44:45], v[22:23]
	v_mov_b32_e32 v39, v20
	v_mov_b32_e32 v20, v11
; DEV bf16_t f2bf(float f) { return (bf16_t)(cvt_pk_bf16(f, 0.f) & 0xffffu); }
; DEV float bf2f(unsigned h) { return __uint_as_float(h << 16); }
; DEV float sigmoidf_(float x) { return 1.0f / (1.0f + __expf(-x)); }
; DEV void ret_out_item(const Params& p, int l, int item, unsigned char* smem) {
;     ...
; #pragma unroll
;   for (int j = 0; j < 4; ++j) {
;     float v = ss[j];
;     v += __shfl_xor(v, 1); v += __shfl_xor(v, 2); v += __shfl_xor(v, 4); v += __shfl_xor(v, 8);
;     const float rstd = rsqrtf(v * (1.0f / 128.0f) + 1e-6f);
;     bf16_t* gp = Gs + (w * 16 + fq * 4 + j) * 136 + fr;
; #pragma unroll
;     for (int et = 0; et < 8; ++et) {
;       const float g = bf2f(gp[et * 16]);
;       gp[et * 16] = f2bf(g * sigmoidf_(g) * a1[et][j] * rstd);
;     }
	v_mov_b32_e32 v38, v10
	v_pk_add_f32 v[10:11], v[20:21], v[24:25] op_sel:[0,1] op_sel_hi:[1,0]
	v_mov_b32_e32 v20, v19
	v_pk_add_f32 v[10:11], v[38:39], v[10:11]
	v_mov_b32_e32 v21, v17
	v_pk_add_f32 v[10:11], v[20:21], v[10:11]
	v_mov_b32_e32 v19, v16
	v_pk_add_f32 v[10:11], v[18:19], v[10:11]
	v_mov_b32_e32 v16, v15
	v_mov_b32_e32 v17, v13
	v_pk_add_f32 v[10:11], v[16:17], v[10:11]
	v_mov_b32_e32 v15, v12
	v_pk_add_f32 v[10:11], v[14:15], v[10:11]
	s_nop 1
	v_add_f32_dpp v23, v23, v23 quad_perm:[1,0,3,2] row_mask:0xf bank_mask:0xf
	v_add_f32_dpp v22, v22, v22 quad_perm:[1,0,3,2] row_mask:0xf bank_mask:0xf
	v_add_f32_dpp v11, v11, v11 quad_perm:[1,0,3,2] row_mask:0xf bank_mask:0xf
	v_add_f32_dpp v10, v10, v10 quad_perm:[1,0,3,2] row_mask:0xf bank_mask:0xf
	v_add_f32_dpp v23, v23, v23 quad_perm:[2,3,0,1] row_mask:0xf bank_mask:0xf
	v_add_f32_dpp v22, v22, v22 quad_perm:[2,3,0,1] row_mask:0xf bank_mask:0xf
	v_add_f32_dpp v11, v11, v11 quad_perm:[2,3,0,1] row_mask:0xf bank_mask:0xf
	v_add_f32_dpp v10, v10, v10 quad_perm:[2,3,0,1] row_mask:0xf bank_mask:0xf
	v_add_f32_dpp v23, v23, v23 row_half_mirror row_mask:0xf bank_mask:0xf
	v_add_f32_dpp v22, v22, v22 row_half_mirror row_mask:0xf bank_mask:0xf
	v_add_f32_dpp v11, v11, v11 row_half_mirror row_mask:0xf bank_mask:0xf
	v_add_f32_dpp v10, v10, v10 row_half_mirror row_mask:0xf bank_mask:0xf
	v_add_f32_dpp v23, v23, v23 row_mirror row_mask:0xf bank_mask:0xf
	v_add_f32_dpp v22, v22, v22 row_mirror row_mask:0xf bank_mask:0xf
	v_add_f32_dpp v11, v11, v11 row_mirror row_mask:0xf bank_mask:0xf
	v_add_f32_dpp v10, v10, v10 row_mirror row_mask:0xf bank_mask:0xf
	v_mov_b32_e32 v152, 0x3c000000
	v_mov_b32_e32 v153, 0x358637bd
	s_mov_b32 s2, 0x800000
	v_fma_f32 v154, v23, v152, v153
	v_fma_f32 v155, v22, v152, v153
	v_fma_f32 v156, v11, v152, v153
	v_fma_f32 v157, v10, v152, v153
	v_mul_f32_e32 v158, 0x4b800000, v154
	v_cmp_gt_f32_e32 vcc, s2, v154
	s_nop 1
	v_cndmask_b32_e32 v154, v154, v158, vcc
	v_rsq_f32_e32 v154, v154
	s_nop 0
	v_mul_f32_e32 v158, 0x45800000, v154
	v_cndmask_b32_e32 v154, v154, v158, vcc
	v_mul_f32_e32 v159, 0x4b800000, v155
	v_cmp_gt_f32_e32 vcc, s2, v155
	s_nop 1
	v_cndmask_b32_e32 v155, v155, v159, vcc
	v_rsq_f32_e32 v155, v155
	s_nop 0
	v_mul_f32_e32 v159, 0x45800000, v155
	v_cndmask_b32_e32 v155, v155, v159, vcc
	v_mul_f32_e32 v160, 0x4b800000, v156
	v_cmp_gt_f32_e32 vcc, s2, v156
	s_nop 1
	v_cndmask_b32_e32 v156, v156, v160, vcc
	v_rsq_f32_e32 v156, v156
	s_nop 0
	v_mul_f32_e32 v160, 0x45800000, v156
	v_cndmask_b32_e32 v156, v156, v160, vcc
	v_mul_f32_e32 v161, 0x4b800000, v157
	v_cmp_gt_f32_e32 vcc, s2, v157
	s_nop 1
	v_cndmask_b32_e32 v157, v157, v161, vcc
	v_rsq_f32_e32 v157, v157
	s_nop 0
	v_mul_f32_e32 v161, 0x45800000, v157
	v_cndmask_b32_e32 v157, v157, v161, vcc
	s_mov_b32 s0, 0xbfb8aa3b
	s_mov_b32 s1, 0xbfb8aa3b
	s_mov_b32 s4, 1.0
	s_mov_b32 s5, 1.0
	s_waitcnt lgkmcnt(0)
	v_lshlrev_b32_e32 v96, 16, v96
	v_lshlrev_b32_e32 v98, 16, v98
	v_lshlrev_b32_e32 v100, 16, v100
	v_lshlrev_b32_e32 v102, 16, v102
	v_lshlrev_b32_e32 v97, 16, v97
	v_lshlrev_b32_e32 v99, 16, v99
	v_lshlrev_b32_e32 v101, 16, v101
	v_lshlrev_b32_e32 v103, 16, v103
	v_pk_mul_f32 v[128:129], v[96:97], s[0:1]
	v_pk_mul_f32 v[134:135], v[98:99], s[0:1]
	v_pk_mul_f32 v[140:141], v[100:101], s[0:1]
	v_pk_mul_f32 v[146:147], v[102:103], s[0:1]
	v_exp_f32_e32 v128, v128
	v_exp_f32_e32 v134, v134
	v_exp_f32_e32 v140, v140
	v_exp_f32_e32 v146, v146
	v_exp_f32_e32 v129, v129
	v_exp_f32_e32 v135, v135
	v_exp_f32_e32 v141, v141
	v_exp_f32_e32 v147, v147
	v_pk_add_f32 v[128:129], v[128:129], s[4:5]
	v_pk_add_f32 v[134:135], v[134:135], s[4:5]
	v_pk_add_f32 v[140:141], v[140:141], s[4:5]
	v_pk_add_f32 v[146:147], v[146:147], s[4:5]
	v_rcp_f32_e32 v130, v128
	v_rcp_f32_e32 v136, v134
	v_rcp_f32_e32 v142, v140
	v_rcp_f32_e32 v148, v146
	v_rcp_f32_e32 v131, v129
	v_rcp_f32_e32 v137, v135
	v_rcp_f32_e32 v143, v141
	v_rcp_f32_e32 v149, v147
	v_pk_fma_f32 v[132:133], v[128:129], v[130:131], s[4:5] neg_lo:[1,0,0] neg_hi:[1,0,0]
	v_pk_fma_f32 v[138:139], v[134:135], v[136:137], s[4:5] neg_lo:[1,0,0] neg_hi:[1,0,0]
	v_pk_fma_f32 v[144:145], v[140:141], v[142:143], s[4:5] neg_lo:[1,0,0] neg_hi:[1,0,0]
	v_pk_fma_f32 v[150:151], v[146:147], v[148:149], s[4:5] neg_lo:[1,0,0] neg_hi:[1,0,0]
	v_pk_fma_f32 v[130:131], v[132:133], v[130:131], v[130:131]
	v_pk_fma_f32 v[136:137], v[138:139], v[136:137], v[136:137]
	v_pk_fma_f32 v[142:143], v[144:145], v[142:143], v[142:143]
	v_pk_fma_f32 v[148:149], v[150:151], v[148:149], v[148:149]
	v_pk_mul_f32 v[130:131], v[130:131], v[96:97]
	v_pk_mul_f32 v[136:137], v[136:137], v[98:99]
	v_pk_mul_f32 v[142:143], v[142:143], v[100:101]
	v_pk_mul_f32 v[148:149], v[148:149], v[102:103]
	v_pk_mul_f32 v[130:131], v[64:65], v[130:131]
	v_pk_mul_f32 v[136:137], v[60:61], v[136:137]
	v_pk_mul_f32 v[142:143], v[88:89], v[142:143]
	v_pk_mul_f32 v[148:149], v[86:87], v[148:149]
	v_pk_mul_f32 v[130:131], v[130:131], v[154:155]
	v_pk_mul_f32 v[136:137], v[136:137], v[154:155]
	v_pk_mul_f32 v[142:143], v[142:143], v[154:155] op_sel_hi:[1,0]
	v_pk_mul_f32 v[148:149], v[148:149], v[154:155] op_sel_hi:[1,0]
	v_cvt_pk_bf16_f32 v128, v130, v131
	v_cvt_pk_bf16_f32 v134, v136, v137
	v_cvt_pk_bf16_f32 v140, v142, v143
	v_cvt_pk_bf16_f32 v146, v148, v149
	ds_write_b16 v26, v128
	ds_write_b16_d16_hi v26, v128 offset:272
	ds_write_b16 v26, v134 offset:32
	ds_write_b16_d16_hi v26, v134 offset:304
	ds_write_b16 v26, v140 offset:96
	ds_write_b16_d16_hi v26, v140 offset:64
	ds_write_b16 v26, v146 offset:160
	ds_write_b16_d16_hi v26, v146 offset:128
	v_lshlrev_b32_e32 v104, 16, v104
	v_lshlrev_b32_e32 v106, 16, v106
; DEV bf16_t f2bf(float f) { return (bf16_t)(cvt_pk_bf16(f, 0.f) & 0xffffu); }
; DEV float bf2f(unsigned h) { return __uint_as_float(h << 16); }
; DEV float sigmoidf_(float x) { return 1.0f / (1.0f + __expf(-x)); }
; DEV void ret_out_item(const Params& p, int l, int item, unsigned char* smem) {
;     ...
;     bf16_t* gp = Gs + (w * 16 + fq * 4 + j) * 136 + fr;
; #pragma unroll
;     for (int et = 0; et < 8; ++et) {
;       const float g = bf2f(gp[et * 16]);
;       gp[et * 16] = f2bf(g * sigmoidf_(g) * a1[et][j] * rstd);
;     }
	v_lshlrev_b32_e32 v108, 16, v108
	v_lshlrev_b32_e32 v110, 16, v110
	v_lshlrev_b32_e32 v105, 16, v105
	v_lshlrev_b32_e32 v107, 16, v107
	v_lshlrev_b32_e32 v109, 16, v109
	v_lshlrev_b32_e32 v111, 16, v111
	v_pk_mul_f32 v[128:129], v[104:105], s[0:1]
	v_pk_mul_f32 v[134:135], v[106:107], s[0:1]
	v_pk_mul_f32 v[140:141], v[108:109], s[0:1]
	v_pk_mul_f32 v[146:147], v[110:111], s[0:1]
	v_exp_f32_e32 v128, v128
	v_exp_f32_e32 v134, v134
	v_exp_f32_e32 v140, v140
	v_exp_f32_e32 v146, v146
	v_exp_f32_e32 v129, v129
	v_exp_f32_e32 v135, v135
	v_exp_f32_e32 v141, v141
	v_exp_f32_e32 v147, v147
	v_pk_add_f32 v[128:129], v[128:129], s[4:5]
	v_pk_add_f32 v[134:135], v[134:135], s[4:5]
	v_pk_add_f32 v[140:141], v[140:141], s[4:5]
	v_pk_add_f32 v[146:147], v[146:147], s[4:5]
	v_rcp_f32_e32 v130, v128
	v_rcp_f32_e32 v136, v134
	v_rcp_f32_e32 v142, v140
	v_rcp_f32_e32 v148, v146
	v_rcp_f32_e32 v131, v129
	v_rcp_f32_e32 v137, v135
	v_rcp_f32_e32 v143, v141
	v_rcp_f32_e32 v149, v147
	v_pk_fma_f32 v[132:133], v[128:129], v[130:131], s[4:5] neg_lo:[1,0,0] neg_hi:[1,0,0]
	v_pk_fma_f32 v[138:139], v[134:135], v[136:137], s[4:5] neg_lo:[1,0,0] neg_hi:[1,0,0]
	v_pk_fma_f32 v[144:145], v[140:141], v[142:143], s[4:5] neg_lo:[1,0,0] neg_hi:[1,0,0]
	v_pk_fma_f32 v[150:151], v[146:147], v[148:149], s[4:5] neg_lo:[1,0,0] neg_hi:[1,0,0]
	v_pk_fma_f32 v[130:131], v[132:133], v[130:131], v[130:131]
	v_pk_fma_f32 v[136:137], v[138:139], v[136:137], v[136:137]
	v_pk_fma_f32 v[142:143], v[144:145], v[142:143], v[142:143]
	v_pk_fma_f32 v[148:149], v[150:151], v[148:149], v[148:149]
	v_pk_mul_f32 v[130:131], v[130:131], v[104:105]
	v_pk_mul_f32 v[136:137], v[136:137], v[106:107]
	v_pk_mul_f32 v[142:143], v[142:143], v[108:109]
	v_pk_mul_f32 v[148:149], v[148:149], v[110:111]
	v_pk_mul_f32 v[130:131], v[84:85], v[130:131]
	v_pk_mul_f32 v[136:137], v[56:57], v[136:137]
	v_pk_mul_f32 v[142:143], v[48:49], v[142:143]
	v_pk_mul_f32 v[148:149], v[40:41], v[148:149]
	v_pk_mul_f32 v[130:131], v[130:131], v[154:155] op_sel_hi:[1,0]
	v_pk_mul_f32 v[136:137], v[136:137], v[154:155] op_sel:[0,1] op_sel_hi:[1,1]
	v_pk_mul_f32 v[142:143], v[142:143], v[154:155] op_sel:[0,1] op_sel_hi:[1,1]
	v_pk_mul_f32 v[148:149], v[148:149], v[154:155] op_sel:[0,1] op_sel_hi:[1,1]
	v_cvt_pk_bf16_f32 v128, v130, v131
	v_cvt_pk_bf16_f32 v134, v136, v137
	v_cvt_pk_bf16_f32 v140, v142, v143
	v_cvt_pk_bf16_f32 v146, v148, v149
	ds_write_b16 v26, v128 offset:224
	ds_write_b16_d16_hi v26, v128 offset:192
	ds_write_b16 v26, v134 offset:368
	ds_write_b16_d16_hi v26, v134 offset:336
	ds_write_b16 v26, v140 offset:432
	ds_write_b16_d16_hi v26, v140 offset:400
	ds_write_b16 v26, v146 offset:496
	ds_write_b16_d16_hi v26, v146 offset:464
	v_lshlrev_b32_e32 v112, 16, v112
	v_lshlrev_b32_e32 v114, 16, v114
	v_lshlrev_b32_e32 v116, 16, v116
	v_lshlrev_b32_e32 v118, 16, v118
	v_lshlrev_b32_e32 v113, 16, v113
	v_lshlrev_b32_e32 v115, 16, v115
	v_lshlrev_b32_e32 v117, 16, v117
	v_lshlrev_b32_e32 v119, 16, v119
	v_pk_mul_f32 v[128:129], v[112:113], s[0:1]
	v_pk_mul_f32 v[134:135], v[114:115], s[0:1]
	v_pk_mul_f32 v[140:141], v[116:117], s[0:1]
	v_pk_mul_f32 v[146:147], v[118:119], s[0:1]
	v_exp_f32_e32 v128, v128
	v_exp_f32_e32 v134, v134
	v_exp_f32_e32 v140, v140
	v_exp_f32_e32 v146, v146
	v_exp_f32_e32 v129, v129
	v_exp_f32_e32 v135, v135
	v_exp_f32_e32 v141, v141
	v_exp_f32_e32 v147, v147
	v_pk_add_f32 v[128:129], v[128:129], s[4:5]
	v_pk_add_f32 v[134:135], v[134:135], s[4:5]
	v_pk_add_f32 v[140:141], v[140:141], s[4:5]
	v_pk_add_f32 v[146:147], v[146:147], s[4:5]
	v_rcp_f32_e32 v130, v128
	v_rcp_f32_e32 v136, v134
	v_rcp_f32_e32 v142, v140
	v_rcp_f32_e32 v148, v146
	v_rcp_f32_e32 v131, v129
	v_rcp_f32_e32 v137, v135
	v_rcp_f32_e32 v143, v141
	v_rcp_f32_e32 v149, v147
	v_pk_fma_f32 v[132:133], v[128:129], v[130:131], s[4:5] neg_lo:[1,0,0] neg_hi:[1,0,0]
	v_pk_fma_f32 v[138:139], v[134:135], v[136:137], s[4:5] neg_lo:[1,0,0] neg_hi:[1,0,0]
	v_pk_fma_f32 v[144:145], v[140:141], v[142:143], s[4:5] neg_lo:[1,0,0] neg_hi:[1,0,0]
	v_pk_fma_f32 v[150:151], v[146:147], v[148:149], s[4:5] neg_lo:[1,0,0] neg_hi:[1,0,0]
	v_pk_fma_f32 v[130:131], v[132:133], v[130:131], v[130:131]
	v_pk_fma_f32 v[136:137], v[138:139], v[136:137], v[136:137]
	v_pk_fma_f32 v[142:143], v[144:145], v[142:143], v[142:143]
	v_pk_fma_f32 v[148:149], v[150:151], v[148:149], v[148:149]
	v_pk_mul_f32 v[130:131], v[130:131], v[112:113]
	v_pk_mul_f32 v[136:137], v[136:137], v[114:115]
	v_pk_mul_f32 v[142:143], v[142:143], v[116:117]
	v_pk_mul_f32 v[148:149], v[148:149], v[118:119]
	v_pk_mul_f32 v[130:131], v[8:9], v[130:131]
	v_pk_mul_f32 v[136:137], v[6:7], v[136:137]
	v_pk_mul_f32 v[142:143], v[36:37], v[142:143]
	v_pk_mul_f32 v[148:149], v[32:33], v[148:149]
	v_pk_mul_f32 v[130:131], v[130:131], v[156:157]
	v_pk_mul_f32 v[136:137], v[136:137], v[156:157]
	v_pk_mul_f32 v[142:143], v[142:143], v[156:157] op_sel_hi:[1,0]
	v_pk_mul_f32 v[148:149], v[148:149], v[156:157] op_sel_hi:[1,0]
	v_cvt_pk_bf16_f32 v128, v130, v131
	v_cvt_pk_bf16_f32 v134, v136, v137
; DEV bf16_t f2bf(float f) { return (bf16_t)(cvt_pk_bf16(f, 0.f) & 0xffffu); }
; DEV float bf2f(unsigned h) { return __uint_as_float(h << 16); }
; DEV float sigmoidf_(float x) { return 1.0f / (1.0f + __expf(-x)); }
; DEV void ret_out_item(const Params& p, int l, int item, unsigned char* smem) {
;     ...
;     bf16_t* gp = Gs + (w * 16 + fq * 4 + j) * 136 + fr;
; #pragma unroll
;     for (int et = 0; et < 8; ++et) {
;       const float g = bf2f(gp[et * 16]);
;       gp[et * 16] = f2bf(g * sigmoidf_(g) * a1[et][j] * rstd);
;     }
;   }
;   asm volatile("s_waitcnt lgkmcnt(0)" ::: "memory");
; #pragma unroll
;   for (int i = 0; i < 4; ++i) {
;     const int c = lane + i * 64, r = c >> 4, kc = c & 15;
;     const u32x4 v = *(const u32x4*)(Gs + (w * 16 + r) * 136 + kc * 8);
;     *(u32x4*)(Z + (rowbase + w * 16 + r) * NIN + RG + h * 128 + kc * 8) = v;
;   }
;   __syncthreads();
	v_cvt_pk_bf16_f32 v140, v142, v143
	v_cvt_pk_bf16_f32 v146, v148, v149
	ds_write_b16 v26, v128 offset:544
	ds_write_b16_d16_hi v26, v128 offset:816
	ds_write_b16 v26, v134 offset:576
	ds_write_b16_d16_hi v26, v134 offset:848
	ds_write_b16 v26, v140 offset:640
	ds_write_b16_d16_hi v26, v140 offset:608
	ds_write_b16 v26, v146 offset:704
	ds_write_b16_d16_hi v26, v146 offset:672
	v_lshlrev_b32_e32 v120, 16, v120
	v_lshlrev_b32_e32 v122, 16, v122
	v_lshlrev_b32_e32 v124, 16, v124
	v_lshlrev_b32_e32 v126, 16, v126
	v_lshlrev_b32_e32 v121, 16, v121
	v_lshlrev_b32_e32 v123, 16, v123
	v_lshlrev_b32_e32 v125, 16, v125
	v_lshlrev_b32_e32 v127, 16, v127
	v_pk_mul_f32 v[128:129], v[120:121], s[0:1]
	v_pk_mul_f32 v[134:135], v[122:123], s[0:1]
	v_pk_mul_f32 v[140:141], v[124:125], s[0:1]
	v_pk_mul_f32 v[146:147], v[126:127], s[0:1]
	v_exp_f32_e32 v128, v128
	v_exp_f32_e32 v134, v134
	v_exp_f32_e32 v140, v140
	v_exp_f32_e32 v146, v146
	v_exp_f32_e32 v129, v129
	v_exp_f32_e32 v135, v135
	v_exp_f32_e32 v141, v141
	v_exp_f32_e32 v147, v147
	v_pk_add_f32 v[128:129], v[128:129], s[4:5]
	v_pk_add_f32 v[134:135], v[134:135], s[4:5]
	v_pk_add_f32 v[140:141], v[140:141], s[4:5]
	v_pk_add_f32 v[146:147], v[146:147], s[4:5]
	v_rcp_f32_e32 v130, v128
	v_rcp_f32_e32 v136, v134
	v_rcp_f32_e32 v142, v140
	v_rcp_f32_e32 v148, v146
	v_rcp_f32_e32 v131, v129
	v_rcp_f32_e32 v137, v135
	v_rcp_f32_e32 v143, v141
	v_rcp_f32_e32 v149, v147
	v_pk_fma_f32 v[132:133], v[128:129], v[130:131], s[4:5] neg_lo:[1,0,0] neg_hi:[1,0,0]
	v_pk_fma_f32 v[138:139], v[134:135], v[136:137], s[4:5] neg_lo:[1,0,0] neg_hi:[1,0,0]
	v_pk_fma_f32 v[144:145], v[140:141], v[142:143], s[4:5] neg_lo:[1,0,0] neg_hi:[1,0,0]
	v_pk_fma_f32 v[150:151], v[146:147], v[148:149], s[4:5] neg_lo:[1,0,0] neg_hi:[1,0,0]
	v_pk_fma_f32 v[130:131], v[132:133], v[130:131], v[130:131]
	v_pk_fma_f32 v[136:137], v[138:139], v[136:137], v[136:137]
	v_pk_fma_f32 v[142:143], v[144:145], v[142:143], v[142:143]
	v_pk_fma_f32 v[148:149], v[150:151], v[148:149], v[148:149]
	v_pk_mul_f32 v[130:131], v[130:131], v[120:121]
	v_pk_mul_f32 v[136:137], v[136:137], v[122:123]
	v_pk_mul_f32 v[142:143], v[142:143], v[124:125]
	v_pk_mul_f32 v[148:149], v[148:149], v[126:127]
	v_pk_mul_f32 v[130:131], v[28:29], v[130:131]
	v_pk_mul_f32 v[136:137], v[4:5], v[136:137]
	v_pk_mul_f32 v[142:143], v[2:3], v[142:143]
	v_pk_mul_f32 v[148:149], v[0:1], v[148:149]
	v_pk_mul_f32 v[130:131], v[130:131], v[156:157] op_sel_hi:[1,0]
	v_pk_mul_f32 v[136:137], v[136:137], v[156:157] op_sel:[0,1] op_sel_hi:[1,1]
	v_pk_mul_f32 v[142:143], v[142:143], v[156:157] op_sel:[0,1] op_sel_hi:[1,1]
	v_pk_mul_f32 v[148:149], v[148:149], v[156:157] op_sel:[0,1] op_sel_hi:[1,1]
	v_cvt_pk_bf16_f32 v128, v130, v131
	v_cvt_pk_bf16_f32 v134, v136, v137
	v_cvt_pk_bf16_f32 v140, v142, v143
	v_cvt_pk_bf16_f32 v146, v148, v149
	ds_write_b16 v26, v128 offset:768
	ds_write_b16_d16_hi v26, v128 offset:736
	ds_write_b16 v26, v134 offset:912
	ds_write_b16_d16_hi v26, v134 offset:880
	ds_write_b16 v26, v140 offset:976
	ds_write_b16_d16_hi v26, v140 offset:944
	ds_write_b16 v26, v146 offset:1040
	ds_write_b16_d16_hi v26, v146 offset:1008
	v_or_b32_e32 v0, v79, v80
	s_waitcnt lgkmcnt(0)
	v_lshl_add_u64 v[4:5], s[38:39], 0, v[80:81]
	v_mad_u64_u32 v[0:1], s[0:1], v0, s13, v[78:79]
	ds_read_b128 v[0:3], v0
	v_or_b32_e32 v8, v4, v79
	v_mov_b64_e32 v[6:7], s[30:31]
	v_mul_lo_u32 v10, v5, s95
	v_mad_u64_u32 v[8:9], s[0:1], v8, s95, v[6:7]
	v_add_u32_e32 v9, v10, v9
	v_lshl_add_u64 v[8:9], v[8:9], 0, s[6:7]
	v_lshl_add_u64 v[8:9], v[8:9], 0, v[76:77]
	v_or_b32_e32 v5, 4, v79
	s_waitcnt lgkmcnt(0)
	global_store_dwordx4 v[8:9], v[0:3], off offset:2048
	s_nop 1
	v_or_b32_e32 v0, v5, v80
	v_mad_u64_u32 v[0:1], s[0:1], v0, s13, v[78:79]
	ds_read_b128 v[0:3], v0
	v_or_b32_e32 v5, v4, v5
	v_mad_u64_u32 v[8:9], s[0:1], v5, s95, v[6:7]
	v_add_u32_e32 v9, v10, v9
	v_lshl_add_u64 v[8:9], v[8:9], 0, s[6:7]
	v_lshl_add_u64 v[8:9], v[8:9], 0, v[76:77]
	v_or_b32_e32 v5, 8, v79
	s_waitcnt lgkmcnt(0)
	global_store_dwordx4 v[8:9], v[0:3], off offset:2048
	s_nop 1
	v_or_b32_e32 v0, v5, v80
	v_mad_u64_u32 v[0:1], s[0:1], v0, s13, v[78:79]
	ds_read_b128 v[0:3], v0
	v_or_b32_e32 v5, v4, v5
	v_mad_u64_u32 v[8:9], s[0:1], v5, s95, v[6:7]
	v_add_u32_e32 v9, v10, v9
	v_lshl_add_u64 v[8:9], v[8:9], 0, s[6:7]
	v_lshl_add_u64 v[8:9], v[8:9], 0, v[76:77]
	v_or_b32_e32 v5, 12, v79
	s_waitcnt lgkmcnt(0)
	global_store_dwordx4 v[8:9], v[0:3], off offset:2048
	v_or_b32_e32 v4, v4, v5
	s_nop 0
	v_or_b32_e32 v0, v5, v80
	v_mad_u64_u32 v[0:1], s[0:1], v0, s13, v[78:79]
	ds_read_b128 v[0:3], v0
	v_mad_u64_u32 v[4:5], s[0:1], v4, s95, v[6:7]
	v_readlane_b32 s0, v248, 37
	v_add_u32_e32 v5, v10, v5
	v_readlane_b32 s2, v248, 39
	v_lshl_add_u64 v[4:5], v[4:5], 0, s[6:7]
	s_add_i32 s18, s18, s2
	v_lshl_add_u64 v[4:5], v[4:5], 0, v[76:77]
	s_cmpk_gt_i32 s18, 0x1ff
	s_waitcnt lgkmcnt(0)
	global_store_dwordx4 v[4:5], v[0:3], off offset:2048
	s_barrier
	v_readlane_b32 s1, v248, 38
	v_readlane_b32 s3, v248, 40
	s_cbranch_scc1 .LBB0_93

; DEV float sigmoidf_(float x) { return 1.0f / (1.0f + __expf(-x)); }
; DEV void sg_ple(const Params& p, unsigned char* smem) {
;     ...
;     sg_core<8>(H + (size_t)TP * D, D, Wpg, D, D, row0, col0, acc, smem);
;     SG_EPI({
;       float* xp = X + row * D + col;
;       f32x4 x = *(const f32x4*)xp;
;       x[0] += sigmoidf_(acc[ni][0]) * pr[ni][0]; x[1] += sigmoidf_(acc[ni][1]) * pr[ni][1]; x[2] += sigmoidf_(acc[ni][2]) * pr[ni][2]; x[3] += sigmoidf_(acc[ni][3]) * pr[ni][3];
;       *(f32x4*)xp = x;
;     })
.LBB0_97:
	v_mfma_f32_16x16x32_bf16 v[8:11], v[8:11], v[0:3], 0
	s_ashr_i32 s12, s17, 31
	s_add_u32 s13, s17, 0x4000
	s_addc_u32 s12, s12, 0
	v_mfma_f32_16x16x32_bf16 v[0:3], v[12:15], v[0:3], 0
	v_mov_b32_e32 v12, v171
	v_mov_b32_e32 v13, v171
	v_mfma_f32_16x16x32_bf16 v[8:11], v[16:19], v[4:7], v[8:11]
	v_mul_f32_e32 v14, 0xbfb8aa3b, v164
	v_mul_f32_e32 v15, 0xbfb8aa3b, v165
	v_mfma_f32_16x16x32_bf16 v[0:3], v[20:23], v[4:7], v[0:3]
	v_exp_f32_e32 v14, v14
	v_exp_f32_e32 v15, v15
	v_mul_f32_e32 v16, 0xbfb8aa3b, v166
	v_mfma_f32_16x16x32_bf16 v[4:7], v[32:35], v[24:27], v[8:11]
	v_mul_f32_e32 v17, 0xbfb8aa3b, v167
	v_pk_add_f32 v[14:15], v[14:15], 1.0 op_sel_hi:[1,0]
	v_exp_f32_e32 v16, v16
	v_ashrrev_i32_e32 v8, 3, v13
	v_and_b32_e32 v8, -16, v8
	v_ashrrev_i32_e32 v9, 31, v8
	v_and_or_b32 v10, v12, 15, s13
	v_mov_b32_e32 v11, s12
	v_lshl_add_u64 v[8:9], v[10:11], 0, v[8:9]
	v_lshrrev_b32_e32 v10, 1, v13
	v_lshrrev_b32_e32 v11, 2, v12
	v_and_b32_e32 v10, 32, v10
	v_and_b32_e32 v11, 12, v11
	v_or3_b32 v10, v11, v10, s16
	v_lshlrev_b64 v[8:9], 12, v[8:9]
	v_lshl_add_u64 v[8:9], s[22:23], 0, v[8:9]
	v_lshlrev_b32_e32 v168, 2, v10
	v_lshl_add_u64 v[8:9], v[8:9], 0, v[168:169]
	v_mov_b64_e32 v[10:11], v[232:233]
	v_mov_b64_e32 v[12:13], v[234:235]
	v_rcp_f32_e32 v19, v15
	v_exp_f32_e32 v17, v17
	v_mfma_f32_16x16x32_bf16 v[4:7], v[40:43], v[28:31], v[4:7]
	v_fma_f32 v20, -v15, v19, 1.0
	v_fmac_f32_e32 v19, v20, v19
	v_mov_b32_e32 v15, v19
	v_rcp_f32_e32 v19, v14
	v_pk_add_f32 v[16:17], v[16:17], 1.0 op_sel_hi:[1,0]
	v_mfma_f32_16x16x32_bf16 v[4:7], v[56:59], v[48:51], v[4:7]
	v_fma_f32 v20, -v14, v19, 1.0
	v_fmac_f32_e32 v19, v20, v19
	v_mov_b32_e32 v14, v19
	v_rcp_f32_e32 v19, v17
	v_mfma_f32_16x16x32_bf16 v[4:7], v[64:67], v[52:55], v[4:7]
	v_fma_f32 v20, -v17, v19, 1.0
	v_fmac_f32_e32 v19, v20, v19
	v_mov_b32_e32 v17, v19
	v_rcp_f32_e32 v19, v16
	v_mfma_f32_16x16x32_bf16 v[4:7], v[72:75], v[76:79], v[4:7]
	v_fma_f32 v20, -v16, v19, 1.0
	v_fmac_f32_e32 v19, v20, v19
	v_mfma_f32_16x16x32_bf16 v[4:7], v[88:91], v[80:83], v[4:7]
	v_mov_b32_e32 v16, v19
	v_mfma_f32_16x16x32_bf16 v[0:3], v[36:39], v[24:27], v[0:3]
	s_waitcnt vmcnt(0)
	s_nop 1
	s_nop 2
	v_pk_fma_f32 v[6:7], v[16:17], v[6:7], v[12:13]
	s_nop 1
	v_pk_fma_f32 v[4:5], v[14:15], v[4:5], v[10:11]
	s_nop 0
	global_store_dwordx4 v[8:9], v[4:7], off
	s_nop 1
	v_mov_b64_e32 v[4:5], v[236:237]
	v_mov_b64_e32 v[6:7], v[238:239]
	v_mul_f32_e32 v10, 0xbfb8aa3b, v160
	v_mul_f32_e32 v11, 0xbfb8aa3b, v161
	v_exp_f32_e32 v10, v10
	v_exp_f32_e32 v11, v11
	v_mul_f32_e32 v12, 0xbfb8aa3b, v162
	v_mul_f32_e32 v13, 0xbfb8aa3b, v163
	v_exp_f32_e32 v12, v12
	v_pk_add_f32 v[10:11], v[10:11], 1.0 op_sel_hi:[1,0]
	v_exp_f32_e32 v13, v13
	v_rcp_f32_e32 v15, v11
	v_pk_add_f32 v[12:13], v[12:13], 1.0 op_sel_hi:[1,0]
	v_mfma_f32_16x16x32_bf16 v[0:3], v[44:47], v[28:31], v[0:3]
	v_fma_f32 v16, -v11, v15, 1.0
	v_fmac_f32_e32 v15, v16, v15
	v_mov_b32_e32 v11, v15
	v_rcp_f32_e32 v15, v10
	v_mfma_f32_16x16x32_bf16 v[0:3], v[60:63], v[48:51], v[0:3]
	v_fma_f32 v16, -v10, v15, 1.0
	v_fmac_f32_e32 v15, v16, v15
	v_mov_b32_e32 v10, v15
	v_rcp_f32_e32 v15, v13
	v_mfma_f32_16x16x32_bf16 v[0:3], v[68:71], v[52:55], v[0:3]
	v_fma_f32 v16, -v13, v15, 1.0
	v_fmac_f32_e32 v15, v16, v15
	v_mov_b32_e32 v13, v15
	v_rcp_f32_e32 v15, v12
	v_mfma_f32_16x16x32_bf16 v[0:3], v[84:87], v[76:79], v[0:3]
	v_readlane_b32 s12, v248, 37
	v_readlane_b32 s14, v248, 39
	v_fma_f32 v16, -v12, v15, 1.0
	v_fmac_f32_e32 v15, v16, v15
	v_mfma_f32_16x16x32_bf16 v[0:3], v[92:95], v[80:83], v[0:3]
	v_mov_b32_e32 v12, v15
	s_add_i32 s6, s6, s14
	s_cmpk_lt_i32 s6, 0x100
	v_readlane_b32 s13, v248, 38
	v_readlane_b32 s15, v248, 40
	s_waitcnt vmcnt(0)
	s_nop 1
	v_pk_fma_f32 v[2:3], v[12:13], v[2:3], v[6:7]
	s_nop 0
	v_pk_fma_f32 v[0:1], v[10:11], v[0:1], v[4:5]
	global_store_dwordx4 v[8:9], v[0:3], off offset:64
	s_cbranch_scc0 .LBB0_116
; DEV int tidx() { int t = threadIdx.x; asm volatile("" : "+v"(t)); return t; }
; DEV int bidx() { int t = blockIdx.x; asm volatile("" : "+s"(t)); return t; }
; template <int R>
; DEV void sg_core(const bf16_t* __restrict__ A, int lda, const bf16_t* __restrict__ Bt, int ldb, int K, int row0, int col0, f32x4 (&acc)[2], unsigned char* smem) {
;   const int tid = tidx(), lane = tid & 63, wid = tid >> 6, wr = wid >> 1, wc = wid & 1, fr = lane & 15, fq = lane >> 4;
;   const int crow = tid >> 3, ckc = tid & 7;
;   const bf16_t* pa = A + (size_t)(row0 + crow) * lda + ckc * 8;
;   const bf16_t* pb = Bt + (size_t)(col0 + crow) * ldb + ckc * 8;
;   const int nt = K >> 6;
;   const int woff = crow * 144 + ckc * 16;
;   u32x4 ra[R], rb[R];
; #pragma unroll
;   for (int j = 0; j < R; ++j) { ra[j] = *(const u32x4*)(pa + j * 64); rb[j] = *(const u32x4*)(pb + j * 64); }
;   *(u32x4*)(smem + woff) = ra[0]; *(u32x4*)(smem + 9216 + woff) = rb[0];
;   asm volatile("s_waitcnt lgkmcnt(0)\n\ts_barrier" ::: "memory");
;   const int aoff = (wr * 16 + fr) * 144 + fq * 16, boff = 9216 + (wc * 32 + fr) * 144 + fq * 16;
; DEV void sg_ple(const Params& p, unsigned char* smem) {
;     ...
;   for (int t = bidx(); t < 256; t += gridDim.x) {
;     const int row0 = (2 * (t & 7) + (t >> 7)) * 64, col0 = ((t >> 3) & 15) * 64;
;     f32x4 pr[2]; pr[0] = (f32x4){0.f, 0.f, 0.f, 0.f}; pr[1] = (f32x4){0.f, 0.f, 0.f, 0.f};
;     sg_core<4>(Pb + (size_t)TP * DPLE, DPLE, Wpp, DPLE, DPLE, row0, col0, pr, smem);
;     f32x4 acc[2]; acc[0] = (f32x4){0.f, 0.f, 0.f, 0.f}; acc[1] = (f32x4){0.f, 0.f, 0.f, 0.f};
;     sg_core<8>(H + (size_t)TP * D, D, Wpg, D, D, row0, col0, acc, smem);
.LBB0_98:
	s_lshl_b32 s12, s6, 1
	s_and_b32 s12, s12, 14
	s_ashr_i32 s13, s6, 7
	s_add_i32 s12, s12, s13
	v_mov_b32_e32 v20, v171
	s_lshl_b32 s17, s12, 6
	s_lshl_b32 s12, s6, 3
	v_ashrrev_i32_e32 v22, 3, v20
	v_add_u32_e32 v0, s17, v22
	s_waitcnt lgkmcnt(0)
	v_ashrrev_i32_e32 v1, 31, v0
	v_lshlrev_b64 v[0:1], 9, v[0:1]
	v_lshlrev_b32_e32 v2, 4, v20
	s_and_b32 s16, s12, 0x3c0
	v_lshl_add_u64 v[0:1], s[4:5], 0, v[0:1]
	v_and_b32_e32 v168, 0x70, v2
	v_lshl_add_u64 v[16:17], v[0:1], 0, v[168:169]
	v_add_u32_e32 v0, s16, v22
	v_ashrrev_i32_e32 v1, 31, v0
	v_lshlrev_b64 v[0:1], 9, v[0:1]
	v_lshl_add_u64 v[0:1], s[2:3], 0, v[0:1]
	v_lshl_add_u64 v[18:19], v[0:1], 0, v[168:169]
	global_load_dwordx4 v[0:3], v[16:17], off
	global_load_dwordx4 v[4:7], v[18:19], off
	global_load_dwordx4 v[8:11], v[16:17], off offset:128
	global_load_dwordx4 v[12:15], v[18:19], off offset:128
	global_load_dwordx4 v[24:27], v[16:17], off offset:256
	global_load_dwordx4 v[28:31], v[18:19], off offset:256
	global_load_dwordx4 v[48:51], v[16:17], off offset:384
	global_load_dwordx4 v[52:55], v[18:19], off offset:384
	v_ashrrev_i32_e32 v164, 3, v171
	v_add_u32_e32 v96, s17, v164
	v_ashrrev_i32_e32 v97, 31, v96
	v_lshlrev_b64 v[96:97], 11, v[96:97]
	v_lshlrev_b32_e32 v98, 4, v171
	v_lshl_add_u64 v[96:97], s[8:9], 0, v[96:97]
	v_and_b32_e32 v168, 0x70, v98
	v_lshl_add_u64 v[180:181], v[96:97], 0, v[168:169]
	v_add_u32_e32 v96, s16, v164
	v_ashrrev_i32_e32 v97, 31, v96
	v_lshlrev_b64 v[96:97], 11, v[96:97]
	v_lshl_add_u64 v[96:97], s[0:1], 0, v[96:97]
	v_lshl_add_u64 v[182:183], v[96:97], 0, v[168:169]
	global_load_dwordx4 v[96:99], v[180:181], off
	global_load_dwordx4 v[116:119], v[182:183], off
	global_load_dwordx4 v[100:103], v[180:181], off offset:128
	global_load_dwordx4 v[104:107], v[182:183], off offset:128
	global_load_dwordx4 v[108:111], v[180:181], off offset:256
	global_load_dwordx4 v[112:115], v[182:183], off offset:256
	global_load_dwordx4 v[120:123], v[180:181], off offset:384
	global_load_dwordx4 v[124:127], v[182:183], off offset:384
	global_load_dwordx4 v[128:131], v[180:181], off offset:512
	global_load_dwordx4 v[132:135], v[182:183], off offset:512
	global_load_dwordx4 v[136:139], v[180:181], off offset:640
	global_load_dwordx4 v[140:143], v[182:183], off offset:640
	global_load_dwordx4 v[144:147], v[180:181], off offset:768
	global_load_dwordx4 v[148:151], v[182:183], off offset:768
	global_load_dwordx4 v[152:155], v[180:181], off offset:896
	global_load_dwordx4 v[156:159], v[182:183], off offset:896
	s_ashr_i32 s12, s17, 31
	s_add_u32 s13, s17, 0x4000
	s_addc_u32 s12, s12, 0
	v_ashrrev_i32_e32 v240, 3, v171
	v_and_b32_e32 v240, -16, v240
	v_ashrrev_i32_e32 v241, 31, v240
	v_and_or_b32 v242, v171, 15, s13
	v_mov_b32_e32 v243, s12
	v_lshl_add_u64 v[240:241], v[242:243], 0, v[240:241]
	v_lshrrev_b32_e32 v242, 1, v171
	v_lshrrev_b32_e32 v243, 2, v171
	v_and_b32_e32 v242, 32, v242
	v_and_b32_e32 v243, 12, v243
	v_or3_b32 v242, v243, v242, s16
	v_lshlrev_b64 v[240:241], 12, v[240:241]
	v_lshl_add_u64 v[240:241], s[22:23], 0, v[240:241]
	v_lshlrev_b32_e32 v242, 2, v242
	v_mov_b32_e32 v243, 0
	v_lshl_add_u64 v[240:241], v[240:241], 0, v[242:243]
	global_load_dwordx4 v[232:235], v[240:241], off
	global_load_dwordx4 v[236:239], v[240:241], off offset:64
	v_mul_lo_u32 v17, v22, s33
	v_and_b32_e32 v21, 15, v20
	v_add3_u32 v56, v17, v168, 0
	s_mov_b32 s14, 0xffffff0
	v_and_b32_e32 v16, 48, v20
	v_mov_b32_e32 v162, v171
	s_mov_b32 s94, 0xffffff0
	s_waitcnt vmcnt(0)
	ds_write_b128 v56, v[0:3]
	s_waitcnt vmcnt(6)
	ds_write_b128 v56, v[4:7] offset:9216
	v_and_or_b32 v0, v22, s14, v21
	v_lshrrev_b32_e32 v1, 1, v20
	v_mul_lo_u32 v0, v0, s33
	v_and_or_b32 v1, v1, 32, v21
	s_waitcnt lgkmcnt(0)
	s_barrier
	v_mul_u32_u24_e32 v1, 0x90, v1
	s_waitcnt vmcnt(5)
	ds_write_b128 v56, v[8:11] offset:18432
	s_waitcnt vmcnt(4)
	ds_write_b128 v56, v[12:15] offset:27648
	v_add3_u32 v80, 0, v0, v16
	v_add3_u32 v92, 0, v1, v16
	ds_read_b128 v[0:3], v80
	ds_read_b128 v[8:11], v92 offset:9216
	ds_read_b128 v[12:15], v92 offset:11520
	ds_read_b128 v[4:7], v80 offset:64
	ds_read_b128 v[16:19], v92 offset:9280
	ds_read_b128 v[20:23], v92 offset:11584
	s_waitcnt lgkmcnt(0)
	s_barrier
	s_waitcnt vmcnt(3)
	ds_write_b128 v56, v[24:27]
	s_waitcnt vmcnt(2)
	ds_write_b128 v56, v[28:31] offset:9216
	ds_read_b128 v[24:27], v80 offset:18432
	ds_read_b128 v[32:35], v92 offset:27648
	ds_read_b128 v[36:39], v92 offset:29952
	ds_read_b128 v[28:31], v80 offset:18496
	ds_read_b128 v[40:43], v92 offset:27712
	ds_read_b128 v[44:47], v92 offset:30016
	s_waitcnt lgkmcnt(0)
	s_barrier
	s_waitcnt vmcnt(1)
	ds_write_b128 v56, v[48:51] offset:18432
	s_waitcnt vmcnt(0)
	ds_write_b128 v56, v[52:55] offset:27648
	ds_read_b128 v[48:51], v80
	ds_read_b128 v[56:59], v92 offset:9216
	ds_read_b128 v[60:63], v92 offset:11520
	ds_read_b128 v[52:55], v80 offset:64
	ds_read_b128 v[64:67], v92 offset:9280
	ds_read_b128 v[68:71], v92 offset:11584
	s_waitcnt lgkmcnt(0)
	s_barrier
	ds_read_b128 v[72:75], v92 offset:27648
	ds_read_b128 v[76:79], v80 offset:18432
	ds_read_b128 v[84:87], v92 offset:29952
	ds_read_b128 v[80:83], v80 offset:18496
	ds_read_b128 v[88:91], v92 offset:27712
	ds_read_b128 v[92:95], v92 offset:30016
	s_waitcnt lgkmcnt(0)
	s_barrier
	s_nop 0
	v_mad_u64_u32 v[160:161], s[12:13], v164, s33, v[168:169]
	v_and_b32_e32 v163, 15, v162
	v_add_u32_e32 v168, 0, v160
	v_and_or_b32 v160, v164, s14, v163
	v_lshrrev_b32_e32 v161, 1, v162
	v_mul_lo_u32 v160, v160, s33
	v_and_or_b32 v161, v161, 32, v163
	v_and_b32_e32 v165, 48, v162
	v_add_u32_e32 v160, 0, v160
	v_mad_u32_u24 v161, v161, s33, 0
	v_mov_b32_e32 v164, 0
	s_mov_b64 s[14:15], -1
	v_add_u32_e32 v177, v160, v165
	v_add_u32_e32 v179, v161, v165
	v_mov_b32_e32 v165, v164
	v_mov_b32_e32 v166, v164
	v_mov_b32_e32 v167, v164
	v_mov_b32_e32 v160, v164
	v_mov_b32_e32 v161, v164
	v_mov_b32_e32 v162, v164
	v_mov_b32_e32 v163, v164
	s_waitcnt vmcnt(15)
	ds_write_b128 v168, v[96:99]
	s_waitcnt vmcnt(14)
	ds_write_b128 v168, v[116:119] offset:9216
	s_waitcnt lgkmcnt(0)
	s_barrier
	s_branch .LBB0_100

; DEV unsigned cvt_pk_bf16(float lo, float hi) { const f32x2_ v = {lo, hi}; return __builtin_bit_cast(unsigned, __builtin_convertvector(v, bf16x2n_)); }
;   DEV void operator()(const f32x4 (&acc)[2][2][4][2], const Unit& u, int wr, int wc, int fr, int fq) const {
;     ...
;           if (ACT == 1) {
; #pragma unroll
;             for (int c = 0; c < 4; ++c) { const float a = fmaxf(v0[c], 0.f), b = fmaxf(v1[c], 0.f); v0[c] = a * a; v1[c] = b * b; }
;           }
;           u32x4 w; w.x = cvt_pk_bf16(v0[0], v0[1]); w.y = cvt_pk_bf16(v0[2], v0[3]); w.z = cvt_pk_bf16(v1[0], v1[1]); w.w = cvt_pk_bf16(v1[2], v1[3]);
;           *(u32x4*)(rowp + bj * HALF) = w;
.LBB0_208:
	v_lshl_add_u32 v144, s47, 8, v140
	v_lshl_or_b32 v138, s46, 8, v142
	v_ashrrev_i32_e32 v145, 31, v144
	v_ashrrev_i32_e32 v139, 31, v138
	v_lshlrev_b64 v[146:147], 13, v[144:145]
	v_lshl_add_u64 v[146:147], s[30:31], 0, v[146:147]
	v_lshlrev_b64 v[148:149], 1, v[138:139]
	v_max_f32_e32 v120, 0, v120
	v_max_f32_e32 v121, 0, v121
	v_lshl_add_u64 v[138:139], v[146:147], 0, v[148:149]
	v_pk_mul_f32 v[146:147], v[120:121], v[120:121]
	v_max_f32_e32 v121, v122, v122
	v_max_f32_e32 v120, v126, v126
	v_max_f32_e32 v122, 0, v121
	v_max_f32_e32 v121, v127, v127
	v_max_f32_e32 v124, 0, v124
	v_max_f32_e32 v125, 0, v125
	v_max_f32_e32 v120, 0, v120
	v_max_f32_e32 v121, 0, v121
	v_max_f32_e32 v123, 0, v123
	v_pk_mul_f32 v[124:125], v[124:125], v[124:125]
	v_pk_mul_f32 v[126:127], v[120:121], v[120:121]
	v_pk_mul_f32 v[150:151], v[122:123], v[122:123]
	v_cvt_pk_bf16_f32 v120, v124, v125
	v_cvt_pk_bf16_f32 v121, v126, v127
	v_cvt_pk_bf16_f32 v122, v146, v147
	v_cvt_pk_bf16_f32 v123, v150, v151
	v_max_f32_e32 v112, 0, v112
	v_max_f32_e32 v113, 0, v113
	global_store_dwordx4 v[138:139], v[120:123], off
	s_nop 1
	v_pk_mul_f32 v[120:121], v[112:113], v[112:113]
	v_max_f32_e32 v113, v114, v114
	v_max_f32_e32 v112, v118, v118
	v_max_f32_e32 v114, 0, v113
	v_max_f32_e32 v113, v119, v119
	v_max_f32_e32 v116, 0, v116
	v_max_f32_e32 v117, 0, v117
	v_max_f32_e32 v112, 0, v112
	v_max_f32_e32 v113, 0, v113
	v_max_f32_e32 v115, 0, v115
	v_pk_mul_f32 v[116:117], v[116:117], v[116:117]
	v_pk_mul_f32 v[118:119], v[112:113], v[112:113]
	v_pk_mul_f32 v[122:123], v[114:115], v[114:115]
	v_cvt_pk_bf16_f32 v112, v116, v117
	v_cvt_pk_bf16_f32 v113, v118, v119
	v_cvt_pk_bf16_f32 v114, v120, v121
	v_cvt_pk_bf16_f32 v115, v122, v123
	v_max_f32_e32 v104, 0, v104
	v_max_f32_e32 v105, 0, v105
	global_store_dwordx4 v[138:139], v[112:115], off offset:256
	s_nop 1
	v_or_b32_e32 v112, 16, v144
	s_nop 0
	v_pk_mul_f32 v[114:115], v[104:105], v[104:105]
	v_max_f32_e32 v105, v106, v106
	v_ashrrev_i32_e32 v113, 31, v112
	v_max_f32_e32 v104, v110, v110
	v_max_f32_e32 v106, 0, v105
	v_max_f32_e32 v105, v111, v111
	v_lshlrev_b64 v[112:113], 13, v[112:113]
	v_max_f32_e32 v108, 0, v108
	v_max_f32_e32 v109, 0, v109
	v_max_f32_e32 v104, 0, v104
	v_max_f32_e32 v105, 0, v105
	v_max_f32_e32 v107, 0, v107
	v_lshl_add_u64 v[112:113], s[30:31], 0, v[112:113]
	v_pk_mul_f32 v[108:109], v[108:109], v[108:109]
	v_pk_mul_f32 v[110:111], v[104:105], v[104:105]
	v_pk_mul_f32 v[116:117], v[106:107], v[106:107]
	v_lshl_add_u64 v[112:113], v[112:113], 0, v[148:149]
	v_cvt_pk_bf16_f32 v104, v108, v109
	v_cvt_pk_bf16_f32 v105, v110, v111
	v_cvt_pk_bf16_f32 v106, v114, v115
	v_cvt_pk_bf16_f32 v107, v116, v117
	v_max_f32_e32 v96, 0, v96
	v_max_f32_e32 v97, 0, v97
	global_store_dwordx4 v[112:113], v[104:107], off
	s_nop 1
	v_pk_mul_f32 v[104:105], v[96:97], v[96:97]
	v_max_f32_e32 v97, v98, v98
	v_max_f32_e32 v96, v102, v102
	v_max_f32_e32 v98, 0, v97
	v_max_f32_e32 v97, v103, v103
	v_max_f32_e32 v100, 0, v100
	v_max_f32_e32 v101, 0, v101
	v_max_f32_e32 v96, 0, v96
	v_max_f32_e32 v97, 0, v97
	v_max_f32_e32 v99, 0, v99
	v_pk_mul_f32 v[100:101], v[100:101], v[100:101]
	v_pk_mul_f32 v[102:103], v[96:97], v[96:97]
	v_pk_mul_f32 v[106:107], v[98:99], v[98:99]
	v_cvt_pk_bf16_f32 v96, v100, v101
	v_cvt_pk_bf16_f32 v97, v102, v103
	v_cvt_pk_bf16_f32 v98, v104, v105
	v_cvt_pk_bf16_f32 v99, v106, v107
	v_max_f32_e32 v88, 0, v88
	v_max_f32_e32 v89, 0, v89
	global_store_dwordx4 v[112:113], v[96:99], off offset:256
	s_nop 1
	v_or_b32_e32 v96, 32, v144
	s_nop 0
	v_pk_mul_f32 v[98:99], v[88:89], v[88:89]
	v_max_f32_e32 v89, v90, v90
	v_ashrrev_i32_e32 v97, 31, v96
	v_max_f32_e32 v88, v94, v94
	v_max_f32_e32 v90, 0, v89
	v_max_f32_e32 v89, v95, v95
	v_lshlrev_b64 v[96:97], 13, v[96:97]
	v_max_f32_e32 v92, 0, v92
	v_max_f32_e32 v93, 0, v93
	v_max_f32_e32 v88, 0, v88
	v_max_f32_e32 v89, 0, v89
	v_max_f32_e32 v91, 0, v91
	v_lshl_add_u64 v[96:97], s[30:31], 0, v[96:97]
	v_pk_mul_f32 v[92:93], v[92:93], v[92:93]
	v_pk_mul_f32 v[94:95], v[88:89], v[88:89]
	v_pk_mul_f32 v[100:101], v[90:91], v[90:91]
	v_lshl_add_u64 v[96:97], v[96:97], 0, v[148:149]
	v_cvt_pk_bf16_f32 v88, v92, v93
	v_cvt_pk_bf16_f32 v89, v94, v95
	v_cvt_pk_bf16_f32 v90, v98, v99
	v_cvt_pk_bf16_f32 v91, v100, v101
	v_max_f32_e32 v80, 0, v80
	v_max_f32_e32 v81, 0, v81
	global_store_dwordx4 v[96:97], v[88:91], off
	s_nop 1
	v_pk_mul_f32 v[88:89], v[80:81], v[80:81]
	v_max_f32_e32 v81, v82, v82
	v_max_f32_e32 v80, v86, v86
	v_max_f32_e32 v82, 0, v81
	v_max_f32_e32 v81, v87, v87
	v_max_f32_e32 v84, 0, v84
	v_max_f32_e32 v85, 0, v85
	v_max_f32_e32 v80, 0, v80
	v_max_f32_e32 v81, 0, v81
	v_max_f32_e32 v83, 0, v83
	v_pk_mul_f32 v[84:85], v[84:85], v[84:85]
	v_pk_mul_f32 v[86:87], v[80:81], v[80:81]
	v_pk_mul_f32 v[90:91], v[82:83], v[82:83]
	v_cvt_pk_bf16_f32 v80, v84, v85
	v_cvt_pk_bf16_f32 v81, v86, v87
	v_cvt_pk_bf16_f32 v82, v88, v89
	v_cvt_pk_bf16_f32 v83, v90, v91
	v_max_f32_e32 v72, 0, v72
	v_max_f32_e32 v73, 0, v73
	global_store_dwordx4 v[96:97], v[80:83], off offset:256
	s_nop 1
	v_or_b32_e32 v80, 48, v144
	s_nop 0
	v_pk_mul_f32 v[82:83], v[72:73], v[72:73]
	v_max_f32_e32 v73, v74, v74
	v_ashrrev_i32_e32 v81, 31, v80
	v_max_f32_e32 v72, v78, v78
	v_max_f32_e32 v74, 0, v73
	v_max_f32_e32 v73, v79, v79
	v_lshlrev_b64 v[80:81], 13, v[80:81]
	v_max_f32_e32 v76, 0, v76
	v_max_f32_e32 v77, 0, v77
	v_max_f32_e32 v72, 0, v72
	v_max_f32_e32 v73, 0, v73
	v_max_f32_e32 v75, 0, v75
	v_lshl_add_u64 v[80:81], s[30:31], 0, v[80:81]
	v_pk_mul_f32 v[76:77], v[76:77], v[76:77]
	v_pk_mul_f32 v[78:79], v[72:73], v[72:73]
	v_pk_mul_f32 v[84:85], v[74:75], v[74:75]
; DEV unsigned cvt_pk_bf16(float lo, float hi) { const f32x2_ v = {lo, hi}; return __builtin_bit_cast(unsigned, __builtin_convertvector(v, bf16x2n_)); }
;   DEV void operator()(const f32x4 (&acc)[2][2][4][2], const Unit& u, int wr, int wc, int fr, int fq) const {
;     ...
;           if (ACT == 1) {
; #pragma unroll
;             for (int c = 0; c < 4; ++c) { const float a = fmaxf(v0[c], 0.f), b = fmaxf(v1[c], 0.f); v0[c] = a * a; v1[c] = b * b; }
;           }
;           u32x4 w; w.x = cvt_pk_bf16(v0[0], v0[1]); w.y = cvt_pk_bf16(v0[2], v0[3]); w.z = cvt_pk_bf16(v1[0], v1[1]); w.w = cvt_pk_bf16(v1[2], v1[3]);
;           *(u32x4*)(rowp + bj * HALF) = w;
	v_lshl_add_u64 v[80:81], v[80:81], 0, v[148:149]
	v_cvt_pk_bf16_f32 v72, v76, v77
	v_cvt_pk_bf16_f32 v73, v78, v79
	v_cvt_pk_bf16_f32 v74, v82, v83
	v_cvt_pk_bf16_f32 v75, v84, v85
	v_max_f32_e32 v64, 0, v64
	v_max_f32_e32 v65, 0, v65
	global_store_dwordx4 v[80:81], v[72:75], off
	s_nop 1
	v_pk_mul_f32 v[72:73], v[64:65], v[64:65]
	v_max_f32_e32 v65, v66, v66
	v_max_f32_e32 v64, v70, v70
	v_max_f32_e32 v66, 0, v65
	v_max_f32_e32 v65, v71, v71
	v_max_f32_e32 v68, 0, v68
	v_max_f32_e32 v69, 0, v69
	v_max_f32_e32 v64, 0, v64
	v_max_f32_e32 v65, 0, v65
	v_max_f32_e32 v67, 0, v67
	v_pk_mul_f32 v[68:69], v[68:69], v[68:69]
	v_pk_mul_f32 v[70:71], v[64:65], v[64:65]
	v_pk_mul_f32 v[74:75], v[66:67], v[66:67]
	v_cvt_pk_bf16_f32 v64, v68, v69
	v_cvt_pk_bf16_f32 v65, v70, v71
	v_cvt_pk_bf16_f32 v66, v72, v73
	v_cvt_pk_bf16_f32 v67, v74, v75
	v_max_f32_e32 v56, 0, v56
	v_max_f32_e32 v57, 0, v57
	global_store_dwordx4 v[80:81], v[64:67], off offset:256
	s_nop 1
	v_pk_mul_f32 v[66:67], v[56:57], v[56:57]
	v_max_f32_e32 v57, v58, v58
	v_max_f32_e32 v60, 0, v60
	v_max_f32_e32 v61, 0, v61
	v_max_f32_e32 v56, v62, v62
	v_max_f32_e32 v58, 0, v57
	v_max_f32_e32 v57, v63, v63
	v_pk_mul_f32 v[60:61], v[60:61], v[60:61]
	v_max_f32_e32 v56, 0, v56
	v_max_f32_e32 v57, 0, v57
	v_max_f32_e32 v59, 0, v59
	s_mov_b32 s5, 0x100000
	v_pk_mul_f32 v[62:63], v[56:57], v[56:57]
	v_pk_mul_f32 v[68:69], v[58:59], v[58:59]
	v_cvt_pk_bf16_f32 v56, v60, v61
	v_add_co_u32_e32 v60, vcc, s5, v138
	v_cvt_pk_bf16_f32 v57, v62, v63
	v_cvt_pk_bf16_f32 v58, v66, v67
	v_cvt_pk_bf16_f32 v59, v68, v69
	v_addc_co_u32_e32 v61, vcc, 0, v139, vcc
	v_max_f32_e32 v48, 0, v48
	v_max_f32_e32 v49, 0, v49
	global_store_dwordx4 v[60:61], v[56:59], off
	s_nop 1
	v_pk_mul_f32 v[56:57], v[48:49], v[48:49]
	v_max_f32_e32 v49, v50, v50
	v_max_f32_e32 v48, v54, v54
	v_max_f32_e32 v50, 0, v49
	v_max_f32_e32 v49, v55, v55
	v_max_f32_e32 v52, 0, v52
	v_max_f32_e32 v53, 0, v53
	v_max_f32_e32 v48, 0, v48
	v_max_f32_e32 v49, 0, v49
	v_max_f32_e32 v51, 0, v51
	s_mov_b64 s[18:19], 0x100000
	v_pk_mul_f32 v[52:53], v[52:53], v[52:53]
	v_pk_mul_f32 v[54:55], v[48:49], v[48:49]
	v_pk_mul_f32 v[58:59], v[50:51], v[50:51]
	v_lshl_add_u64 v[64:65], v[138:139], 0, s[18:19]
	v_cvt_pk_bf16_f32 v48, v52, v53
	v_cvt_pk_bf16_f32 v49, v54, v55
	v_cvt_pk_bf16_f32 v50, v56, v57
	v_cvt_pk_bf16_f32 v51, v58, v59
	v_max_f32_e32 v40, 0, v40
	v_max_f32_e32 v41, 0, v41
	global_store_dwordx4 v[64:65], v[48:51], off offset:256
	s_nop 1
	v_pk_mul_f32 v[50:51], v[40:41], v[40:41]
	v_max_f32_e32 v41, v42, v42
	v_max_f32_e32 v44, 0, v44
	v_max_f32_e32 v45, 0, v45
	v_max_f32_e32 v40, v46, v46
	v_max_f32_e32 v42, 0, v41
	v_max_f32_e32 v41, v47, v47
	v_pk_mul_f32 v[44:45], v[44:45], v[44:45]
	v_max_f32_e32 v40, 0, v40
	v_max_f32_e32 v41, 0, v41
	v_max_f32_e32 v43, 0, v43
	s_mov_b32 s5, 0x120000
	v_pk_mul_f32 v[46:47], v[40:41], v[40:41]
	v_pk_mul_f32 v[52:53], v[42:43], v[42:43]
	v_cvt_pk_bf16_f32 v40, v44, v45
	v_add_co_u32_e32 v44, vcc, s5, v138
	v_cvt_pk_bf16_f32 v41, v46, v47
	v_cvt_pk_bf16_f32 v42, v50, v51
	v_cvt_pk_bf16_f32 v43, v52, v53
	v_addc_co_u32_e32 v45, vcc, 0, v139, vcc
	v_max_f32_e32 v32, 0, v32
	v_max_f32_e32 v33, 0, v33
	global_store_dwordx4 v[44:45], v[40:43], off
	s_nop 1
	v_pk_mul_f32 v[40:41], v[32:33], v[32:33]
	v_max_f32_e32 v33, v34, v34
	v_max_f32_e32 v32, v38, v38
	v_max_f32_e32 v34, 0, v33
	v_max_f32_e32 v33, v39, v39
	v_max_f32_e32 v36, 0, v36
	v_max_f32_e32 v37, 0, v37
	v_max_f32_e32 v32, 0, v32
	v_max_f32_e32 v33, 0, v33
	v_max_f32_e32 v35, 0, v35
	s_mov_b64 s[18:19], 0x120000
	v_pk_mul_f32 v[36:37], v[36:37], v[36:37]
	v_pk_mul_f32 v[38:39], v[32:33], v[32:33]
	v_pk_mul_f32 v[42:43], v[34:35], v[34:35]
	v_lshl_add_u64 v[48:49], v[138:139], 0, s[18:19]
	v_cvt_pk_bf16_f32 v32, v36, v37
	v_cvt_pk_bf16_f32 v33, v38, v39
	v_cvt_pk_bf16_f32 v34, v40, v41
	v_cvt_pk_bf16_f32 v35, v42, v43
	v_max_f32_e32 v24, 0, v24
	v_max_f32_e32 v25, 0, v25
	global_store_dwordx4 v[48:49], v[32:35], off offset:256
	s_nop 1
	v_pk_mul_f32 v[34:35], v[24:25], v[24:25]
	v_max_f32_e32 v25, v26, v26
	v_max_f32_e32 v28, 0, v28
	v_max_f32_e32 v29, 0, v29
	v_max_f32_e32 v24, v30, v30
	v_max_f32_e32 v26, 0, v25
	v_max_f32_e32 v25, v31, v31
	v_pk_mul_f32 v[28:29], v[28:29], v[28:29]
	v_max_f32_e32 v24, 0, v24
	v_max_f32_e32 v25, 0, v25
	v_max_f32_e32 v27, 0, v27
	s_mov_b32 s5, 0x140000
	v_pk_mul_f32 v[30:31], v[24:25], v[24:25]
	v_pk_mul_f32 v[36:37], v[26:27], v[26:27]
	v_cvt_pk_bf16_f32 v24, v28, v29
	v_add_co_u32_e32 v28, vcc, s5, v138
	v_cvt_pk_bf16_f32 v25, v30, v31
	v_cvt_pk_bf16_f32 v26, v34, v35
	v_cvt_pk_bf16_f32 v27, v36, v37
	v_addc_co_u32_e32 v29, vcc, 0, v139, vcc
	v_max_f32_e32 v16, 0, v16
	v_max_f32_e32 v17, 0, v17
	global_store_dwordx4 v[28:29], v[24:27], off
	s_nop 1
	v_pk_mul_f32 v[24:25], v[16:17], v[16:17]
	v_max_f32_e32 v17, v18, v18
	v_max_f32_e32 v16, v22, v22
	v_max_f32_e32 v18, 0, v17
	v_max_f32_e32 v17, v23, v23
	v_max_f32_e32 v20, 0, v20
	v_max_f32_e32 v21, 0, v21
	v_max_f32_e32 v16, 0, v16
	v_max_f32_e32 v17, 0, v17
	v_max_f32_e32 v19, 0, v19
	s_mov_b64 s[18:19], 0x140000
	v_pk_mul_f32 v[20:21], v[20:21], v[20:21]
	v_pk_mul_f32 v[22:23], v[16:17], v[16:17]
	v_pk_mul_f32 v[26:27], v[18:19], v[18:19]
	v_lshl_add_u64 v[32:33], v[138:139], 0, s[18:19]
	v_cvt_pk_bf16_f32 v16, v20, v21
	v_cvt_pk_bf16_f32 v17, v22, v23
	v_cvt_pk_bf16_f32 v18, v24, v25
	v_cvt_pk_bf16_f32 v19, v26, v27
	v_max_f32_e32 v8, 0, v8
	v_max_f32_e32 v9, 0, v9
	global_store_dwordx4 v[32:33], v[16:19], off offset:256
	s_nop 1
	v_pk_mul_f32 v[18:19], v[8:9], v[8:9]
	v_max_f32_e32 v9, v10, v10
	v_max_f32_e32 v12, 0, v12
	v_max_f32_e32 v13, 0, v13
	v_max_f32_e32 v8, v14, v14
	v_max_f32_e32 v10, 0, v9
	v_max_f32_e32 v9, v15, v15
	v_pk_mul_f32 v[12:13], v[12:13], v[12:13]
	v_max_f32_e32 v8, 0, v8
	v_max_f32_e32 v9, 0, v9
	v_max_f32_e32 v11, 0, v11
	s_mov_b32 s5, 0x160000
	v_pk_mul_f32 v[14:15], v[8:9], v[8:9]
	v_pk_mul_f32 v[20:21], v[10:11], v[10:11]
	v_cvt_pk_bf16_f32 v8, v12, v13
	v_add_co_u32_e32 v12, vcc, s5, v138
	v_cvt_pk_bf16_f32 v9, v14, v15
	v_cvt_pk_bf16_f32 v10, v18, v19
	v_cvt_pk_bf16_f32 v11, v20, v21
	v_addc_co_u32_e32 v13, vcc, 0, v139, vcc
	v_max_f32_e32 v0, 0, v0
	v_max_f32_e32 v1, 0, v1
	global_store_dwordx4 v[12:13], v[8:11], off
	s_nop 1
	v_pk_mul_f32 v[8:9], v[0:1], v[0:1]
	v_max_f32_e32 v1, v2, v2
	v_max_f32_e32 v0, v6, v6
	v_max_f32_e32 v2, 0, v1
	v_max_f32_e32 v1, v7, v7
	v_max_f32_e32 v4, 0, v4
	v_max_f32_e32 v5, 0, v5
	v_max_f32_e32 v0, 0, v0
	v_max_f32_e32 v1, 0, v1
	v_max_f32_e32 v3, 0, v3
	s_mov_b64 s[18:19], 0x160000
	v_pk_mul_f32 v[4:5], v[4:5], v[4:5]
	v_pk_mul_f32 v[6:7], v[0:1], v[0:1]
	v_pk_mul_f32 v[10:11], v[2:3], v[2:3]
	v_lshl_add_u64 v[16:17], v[138:139], 0, s[18:19]
	v_cvt_pk_bf16_f32 v0, v4, v5
	v_cvt_pk_bf16_f32 v1, v6, v7
	v_cvt_pk_bf16_f32 v2, v8, v9
	v_cvt_pk_bf16_f32 v3, v10, v11
	s_andn2_b64 vcc, exec, s[12:13]
	s_mov_b64 s[12:13], -1
	global_store_dwordx4 v[16:17], v[0:3], off offset:256
	s_cbranch_vccnz .LBB0_201
; #define PG8_BAR __builtin_amdgcn_s_barrier()
; template <class Epi, bool SEQ>
; DEV void gemm_phase(PG8_LAS unsigned char* lds, const Gemm g, const Epi& E) {
;     ...
;     cur = nxt; cA = nA; cB = nB; ++ui;
;     if (wr == 1) PG8_BAR;
;   }
	s_andn2_b64 vcc, exec, s[0:1]
	s_cbranch_vccnz .LBB0_200
	s_barrier
	s_branch .LBB0_200

; DEV int tidx() { int t = threadIdx.x; asm volatile("" : "+v"(t)); return t; }
; template <int R>
; DEV void sg_core(const bf16_t* __restrict__ A, int lda, const bf16_t* __restrict__ Bt, int ldb, int K, int row0, int col0, f32x4 (&acc)[2], unsigned char* smem) {
;   const int tid = tidx(), lane = tid & 63, wid = tid >> 6, wr = wid >> 1, wc = wid & 1, fr = lane & 15, fq = lane >> 4;
;   const int crow = tid >> 3, ckc = tid & 7;
;   const bf16_t* pa = A + (size_t)(row0 + crow) * lda + ckc * 8;
;   const bf16_t* pb = Bt + (size_t)(col0 + crow) * ldb + ckc * 8;
;   const int nt = K >> 6;
;   const int woff = crow * 144 + ckc * 16;
;   u32x4 ra[R], rb[R];
; #pragma unroll
;   for (int j = 0; j < R; ++j) { ra[j] = *(const u32x4*)(pa + j * 64); rb[j] = *(const u32x4*)(pb + j * 64); }
;   *(u32x4*)(smem + woff) = ra[0]; *(u32x4*)(smem + 9216 + woff) = rb[0];
;   asm volatile("s_waitcnt lgkmcnt(0)\n\ts_barrier" ::: "memory");
;   const int aoff = (wr * 16 + fr) * 144 + fq * 16, boff = 9216 + (wc * 32 + fr) * 144 + fq * 16;
; DEV void sg_branch(const Params& p, unsigned char* smem) {
;     ...
;     for (int s = 0; s < 3; ++s) {
;       const int aoff = (s == 0) ? RG : (s == 1 ? AQ : CB);
;       sg_core<8>(Z + (size_t)TP * NIN + aoff, NIN, W + (size_t)s * D * 512, 512, 512, row0, col0, acc, smem);
;       const int sb = s == 2 ? 2 : s + 1; const float one = s == 2 ? 0.f : 1.f;
;       SG_EPI({
;         const u32x2 ga = *(const u32x2*)(Z + row * NIN + GT + s * D + col), gb = *(const u32x2*)(Z + row * NIN + GT + sb * D + col);
.LBB0_299:
	s_cmp_eq_u32 s4, 0x100000
	s_cselect_b32 s6, 0x600, s75
	s_cmp_lg_u32 s4, 0
	s_cselect_b32 s6, s6, 0x400
	s_lshl_b32 s6, s6, 1
	s_add_u32 s12, s15, s6
	v_mov_b32_e32 v74, v171
	s_addc_u32 s13, s16, 0
	v_mov_b64_e32 v[8:9], s[12:13]
	v_ashrrev_i32_e32 v72, 3, v74
	v_add_u32_e32 v10, s35, v72
	v_mad_i64_i32 v[8:9], s[12:13], v10, s95, v[8:9]
	v_lshlrev_b32_e32 v10, 4, v74
	v_and_b32_e32 v168, 0x70, v10
	v_ashrrev_i32_e32 v73, 31, v72
	v_lshl_add_u64 v[64:65], v[8:9], 0, v[168:169]
	v_lshlrev_b64 v[8:9], 10, v[72:73]
	s_add_u32 s12, s21, s4
	v_or_b32_e32 v8, v8, v168
	s_addc_u32 s13, s34, s5
	v_lshl_add_u64 v[12:13], s[12:13], 0, v[8:9]
	global_load_dwordx4 v[8:11], v[64:65], off
	s_mov_b32 s6, 0xd80000
	v_add_co_u32_e32 v68, vcc, s6, v12
	v_mul_lo_u32 v76, v72, s33
	s_nop 0
	v_addc_co_u32_e32 v69, vcc, 0, v13, vcc
	global_load_dwordx4 v[12:15], v[68:69], off
	global_load_dwordx4 v[16:19], v[64:65], off offset:128
	global_load_dwordx4 v[20:23], v[68:69], off offset:128
	global_load_dwordx4 v[24:27], v[64:65], off offset:256
	global_load_dwordx4 v[28:31], v[68:69], off offset:256
	global_load_dwordx4 v[32:35], v[64:65], off offset:384
	global_load_dwordx4 v[36:39], v[68:69], off offset:384
	global_load_dwordx4 v[40:43], v[64:65], off offset:512
	global_load_dwordx4 v[44:47], v[68:69], off offset:512
	global_load_dwordx4 v[48:51], v[64:65], off offset:640
	global_load_dwordx4 v[52:55], v[68:69], off offset:640
	global_load_dwordx4 v[56:59], v[64:65], off offset:768
	global_load_dwordx4 v[60:63], v[68:69], off offset:768
	s_nop 0
	global_load_dwordx4 v[64:67], v[64:65], off offset:896
	s_nop 0
	global_load_dwordx4 v[68:71], v[68:69], off offset:896
	v_and_b32_e32 v75, 15, v74
	v_add3_u32 v76, v76, v168, 0
	v_and_b32_e32 v73, 48, v74
	s_cmp_eq_u32 s4, 0x200000
	s_cselect_b64 s[12:13], -1, 0
	v_mov_b32_e32 v119, 0
	v_mov_b32_e32 v109, v171
	v_mov_b32_e32 v114, v171
	v_mov_b32_e32 v113, s27
	v_ashrrev_i32_e32 v110, 3, v114
	v_and_b32_e32 v110, -16, v110
	v_and_b32_e32 v118, 15, v109
	v_ashrrev_i32_e32 v111, 31, v110
	v_or_b32_e32 v112, s26, v118
	v_lshrrev_b32_e32 v114, 1, v114
	v_lshl_add_u64 v[112:113], v[112:113], 0, v[110:111]
	v_and_b32_e32 v116, 32, v114
	v_lshrrev_b32_e32 v109, 2, v109
	v_mov_b64_e32 v[114:115], s[28:29]
	v_and_b32_e32 v109, 12, v109
	v_mad_u64_u32 v[114:115], s[38:39], v112, s95, v[114:115]
	s_and_b64 s[12:13], s[12:13], exec
	v_lshl_add_u64 v[110:111], s[2:3], 0, v[110:111]
	v_add_u32_e32 v112, s20, v116
	v_or3_b32 v117, v109, v116, s19
	v_mad_i32_i24 v115, v113, s95, v115
	s_cselect_b32 s6, 0x800, s36
	v_lshl_add_u64 v[110:111], v[110:111], 0, v[118:119]
	v_add_lshl_u32 v118, v112, v109, 1
	v_lshl_add_u64 v[114:115], s[6:7], 1, v[114:115]
	v_mad_u64_u32 v[112:113], s[38:39], v110, s95, v[118:119]
	v_lshlrev_b32_e32 v118, 1, v117
	v_lshl_add_u64 v[114:115], v[114:115], 0, v[118:119]
	s_mov_b64 s[38:39], 0x4701e00
	s_mov_b32 s6, 0x4701000
	v_lshl_add_u64 v[116:117], v[114:115], 0, s[38:39]
	v_add_co_u32_e32 v114, vcc, s6, v114
	v_mad_i32_i24 v113, v111, s95, v113
	s_nop 0
	v_addc_co_u32_e32 v115, vcc, 0, v115, vcc
	global_load_dwordx2 v[120:121], v[114:115], off offset:3584
	v_lshl_add_u64 v[110:111], s[8:9], 0, v[112:113]
	global_load_dwordx2 v[122:123], v[110:111], off
	global_load_dwordx2 v[124:125], v[110:111], off offset:32
	global_load_dwordx2 v[126:127], v[116:117], off offset:32
	s_waitcnt vmcnt(0)
	ds_write_b128 v76, v[8:11]
	ds_write_b128 v76, v[12:15] offset:9216
	v_and_or_b32 v8, v72, s40, v75
	v_lshrrev_b32_e32 v9, 1, v74
	v_mul_lo_u32 v8, v8, s33
	v_and_or_b32 v9, v9, 32, v75
	s_waitcnt lgkmcnt(0)
	s_barrier
	v_mul_u32_u24_e32 v9, 0x90, v9
	v_add3_u32 v72, 0, v8, v73
	ds_write_b128 v76, v[16:19] offset:18432
	ds_write_b128 v76, v[20:23] offset:27648
	v_add3_u32 v73, 0, v9, v73
	ds_read_b128 v[8:11], v72
	ds_read_b128 v[12:15], v73 offset:9216
	ds_read_b128 v[80:83], v73 offset:11520
	ds_read_b128 v[84:87], v72 offset:64
	ds_read_b128 v[88:91], v73 offset:9280
	ds_read_b128 v[92:95], v73 offset:11584
	s_waitcnt lgkmcnt(4)
	v_mfma_f32_16x16x32_bf16 v[4:7], v[12:15], v[8:11], v[4:7]
	s_waitcnt lgkmcnt(3)
	v_mfma_f32_16x16x32_bf16 v[0:3], v[80:83], v[8:11], v[0:3]
	s_waitcnt lgkmcnt(1)
	v_mfma_f32_16x16x32_bf16 v[4:7], v[88:91], v[84:87], v[4:7]
	s_waitcnt lgkmcnt(0)
	v_mfma_f32_16x16x32_bf16 v[0:3], v[92:95], v[84:87], v[0:3]
	s_waitcnt lgkmcnt(0)
	s_barrier
	ds_write_b128 v76, v[24:27]
	ds_write_b128 v76, v[28:31] offset:9216
	ds_read_b128 v[8:11], v72 offset:18432
	ds_read_b128 v[12:15], v73 offset:27648
	ds_read_b128 v[80:83], v73 offset:29952
	ds_read_b128 v[84:87], v72 offset:18496
	ds_read_b128 v[88:91], v73 offset:27712
	ds_read_b128 v[92:95], v73 offset:30016
	s_waitcnt lgkmcnt(4)
	v_mfma_f32_16x16x32_bf16 v[4:7], v[12:15], v[8:11], v[4:7]
	s_waitcnt lgkmcnt(3)
	v_mfma_f32_16x16x32_bf16 v[0:3], v[80:83], v[8:11], v[0:3]
	s_waitcnt lgkmcnt(1)
	v_mfma_f32_16x16x32_bf16 v[4:7], v[88:91], v[84:87], v[4:7]
	s_waitcnt lgkmcnt(0)
	v_mfma_f32_16x16x32_bf16 v[0:3], v[92:95], v[84:87], v[0:3]
	s_waitcnt lgkmcnt(0)
	s_barrier
	ds_write_b128 v76, v[32:35] offset:18432
	ds_write_b128 v76, v[36:39] offset:27648
	ds_read_b128 v[8:11], v72
	ds_read_b128 v[12:15], v73 offset:9216
	ds_read_b128 v[80:83], v73 offset:11520
	ds_read_b128 v[84:87], v72 offset:64
	ds_read_b128 v[88:91], v73 offset:9280
	ds_read_b128 v[92:95], v73 offset:11584
	s_waitcnt lgkmcnt(4)
	v_mfma_f32_16x16x32_bf16 v[4:7], v[12:15], v[8:11], v[4:7]
	s_waitcnt lgkmcnt(3)
	v_mfma_f32_16x16x32_bf16 v[0:3], v[80:83], v[8:11], v[0:3]
	s_waitcnt lgkmcnt(1)
	v_mfma_f32_16x16x32_bf16 v[4:7], v[88:91], v[84:87], v[4:7]
	s_waitcnt lgkmcnt(0)
	v_mfma_f32_16x16x32_bf16 v[0:3], v[92:95], v[84:87], v[0:3]
	s_waitcnt lgkmcnt(0)
	s_barrier
; DEV f32x4 mfma32(bf16x8 a, bf16x8 b, f32x4 c) { return __builtin_amdgcn_mfma_f32_16x16x32_bf16(a, b, c, 0, 0, 0); }
; template <int R>
; DEV void sg_core(const bf16_t* __restrict__ A, int lda, const bf16_t* __restrict__ Bt, int ldb, int K, int row0, int col0, f32x4 (&acc)[2], unsigned char* smem) {
;     ...
;   for (int kt0 = 0; kt0 < nt; kt0 += R) {
; #pragma unroll
;     for (int u = 0; u < R; ++u) {
;       const int kt = kt0 + u;
;       unsigned char* cur = smem + (u & 1) * 18432;
;       unsigned char* nxt = smem + ((u + 1) & 1) * 18432;
;       if (kt + 1 < nt) { *(u32x4*)(nxt + woff) = ra[(u + 1) % R]; *(u32x4*)(nxt + 9216 + woff) = rb[(u + 1) % R]; }
;       if (kt + R < nt) { ra[u] = *(const u32x4*)(pa + (size_t)(kt + R) * 64); rb[u] = *(const u32x4*)(pb + (size_t)(kt + R) * 64); }
; #pragma unroll
;       for (int ks = 0; ks < 2; ++ks) {
;         const bf16x8 af = *(const bf16x8*)(cur + aoff + ks * 64);
; #pragma unroll
;         for (int ni = 0; ni < 2; ++ni) {
;           const bf16x8 bfr = *(const bf16x8*)(cur + boff + ni * 16 * 144 + ks * 64);
;           acc[ni] = mfma32(bfr, af, acc[ni]);
;         }
;       }
;       asm volatile("s_waitcnt lgkmcnt(0)\n\ts_barrier" ::: "memory");
;     }
	ds_write_b128 v76, v[40:43]
	ds_write_b128 v76, v[44:47] offset:9216
	ds_read_b128 v[8:11], v72 offset:18432
	ds_read_b128 v[12:15], v73 offset:27648
	ds_read_b128 v[80:83], v73 offset:29952
	ds_read_b128 v[84:87], v72 offset:18496
	ds_read_b128 v[88:91], v73 offset:27712
	ds_read_b128 v[92:95], v73 offset:30016
	s_waitcnt lgkmcnt(4)
	v_mfma_f32_16x16x32_bf16 v[4:7], v[12:15], v[8:11], v[4:7]
	s_waitcnt lgkmcnt(3)
	v_mfma_f32_16x16x32_bf16 v[0:3], v[80:83], v[8:11], v[0:3]
	s_waitcnt lgkmcnt(1)
	v_mfma_f32_16x16x32_bf16 v[4:7], v[88:91], v[84:87], v[4:7]
	s_waitcnt lgkmcnt(0)
	v_mfma_f32_16x16x32_bf16 v[0:3], v[92:95], v[84:87], v[0:3]
	s_waitcnt lgkmcnt(0)
	s_barrier
	ds_write_b128 v76, v[48:51] offset:18432
	ds_write_b128 v76, v[52:55] offset:27648
	ds_read_b128 v[8:11], v72
	ds_read_b128 v[12:15], v73 offset:9216
	ds_read_b128 v[80:83], v73 offset:11520
	ds_read_b128 v[84:87], v72 offset:64
	ds_read_b128 v[88:91], v73 offset:9280
	ds_read_b128 v[92:95], v73 offset:11584
	s_waitcnt lgkmcnt(4)
	v_mfma_f32_16x16x32_bf16 v[4:7], v[12:15], v[8:11], v[4:7]
	s_waitcnt lgkmcnt(3)
	v_mfma_f32_16x16x32_bf16 v[0:3], v[80:83], v[8:11], v[0:3]
	s_waitcnt lgkmcnt(1)
	v_mfma_f32_16x16x32_bf16 v[4:7], v[88:91], v[84:87], v[4:7]
	s_waitcnt lgkmcnt(0)
	v_mfma_f32_16x16x32_bf16 v[0:3], v[92:95], v[84:87], v[0:3]
	s_waitcnt lgkmcnt(0)
	s_barrier
	ds_write_b128 v76, v[56:59]
	ds_write_b128 v76, v[60:63] offset:9216
	ds_read_b128 v[8:11], v72 offset:18432
	ds_read_b128 v[12:15], v73 offset:27648
	ds_read_b128 v[80:83], v73 offset:29952
	ds_read_b128 v[84:87], v72 offset:18496
	ds_read_b128 v[88:91], v73 offset:27712
	ds_read_b128 v[92:95], v73 offset:30016
	s_waitcnt lgkmcnt(4)
	v_mfma_f32_16x16x32_bf16 v[4:7], v[12:15], v[8:11], v[4:7]
	s_waitcnt lgkmcnt(3)
	v_mfma_f32_16x16x32_bf16 v[0:3], v[80:83], v[8:11], v[0:3]
	s_waitcnt lgkmcnt(1)
	v_mfma_f32_16x16x32_bf16 v[4:7], v[88:91], v[84:87], v[4:7]
	s_waitcnt lgkmcnt(0)
	v_mfma_f32_16x16x32_bf16 v[0:3], v[92:95], v[84:87], v[0:3]
	s_waitcnt lgkmcnt(0)
	s_barrier
	ds_write_b128 v76, v[64:67] offset:18432
	ds_write_b128 v76, v[68:71] offset:27648
	ds_read_b128 v[8:11], v72
	ds_read_b128 v[12:15], v73 offset:9216
	ds_read_b128 v[80:83], v73 offset:11520
	ds_read_b128 v[84:87], v72 offset:64
	ds_read_b128 v[88:91], v73 offset:9280
	ds_read_b128 v[92:95], v73 offset:11584
	s_waitcnt lgkmcnt(4)
	v_mfma_f32_16x16x32_bf16 v[4:7], v[12:15], v[8:11], v[4:7]
	s_waitcnt lgkmcnt(3)
	v_mfma_f32_16x16x32_bf16 v[0:3], v[80:83], v[8:11], v[0:3]
	s_waitcnt lgkmcnt(1)
	v_mfma_f32_16x16x32_bf16 v[4:7], v[88:91], v[84:87], v[4:7]
	s_waitcnt lgkmcnt(0)
	v_mfma_f32_16x16x32_bf16 v[0:3], v[92:95], v[84:87], v[0:3]
	s_waitcnt lgkmcnt(0)
	s_barrier
	ds_read_b128 v[8:11], v72 offset:18432
	ds_read_b128 v[12:15], v73 offset:27648
	ds_read_b128 v[80:83], v73 offset:29952
	ds_read_b128 v[84:87], v72 offset:18496
	ds_read_b128 v[88:91], v73 offset:27712
	ds_read_b128 v[92:95], v73 offset:30016
	s_waitcnt lgkmcnt(4)
	v_mfma_f32_16x16x32_bf16 v[4:7], v[12:15], v[8:11], v[4:7]
	s_waitcnt lgkmcnt(3)
	v_mfma_f32_16x16x32_bf16 v[0:3], v[80:83], v[8:11], v[0:3]
	s_waitcnt lgkmcnt(1)
	v_mfma_f32_16x16x32_bf16 v[4:7], v[88:91], v[84:87], v[4:7]
	s_waitcnt lgkmcnt(0)
	v_mfma_f32_16x16x32_bf16 v[0:3], v[92:95], v[84:87], v[0:3]
	s_waitcnt lgkmcnt(0)
	s_barrier
; DEV unsigned cvt_pk_bf16(float lo, float hi) { const f32x2_ v = {lo, hi}; return __builtin_bit_cast(unsigned, __builtin_convertvector(v, bf16x2n_)); }
; DEV float bflo(unsigned w) { return __uint_as_float(w << 16); }
; DEV float bfhi(unsigned w) { return __uint_as_float(w & 0xffff0000u); }
; DEV void sg_branch(const Params& p, unsigned char* smem) {
;     ...
;       const int sb = s == 2 ? 2 : s + 1; const float one = s == 2 ? 0.f : 1.f;
;       SG_EPI({
;         const u32x2 ga = *(const u32x2*)(Z + row * NIN + GT + s * D + col), gb = *(const u32x2*)(Z + row * NIN + GT + sb * D + col);
;         acc[ni][0] *= (1.0f + one * __expf(-bflo(gb.x))) * __builtin_amdgcn_rcpf(1.0f + __expf(-bflo(ga.x)));
;         acc[ni][1] *= (1.0f + one * __expf(-bfhi(gb.x))) * __builtin_amdgcn_rcpf(1.0f + __expf(-bfhi(ga.x)));
;         acc[ni][2] *= (1.0f + one * __expf(-bflo(gb.y))) * __builtin_amdgcn_rcpf(1.0f + __expf(-bflo(ga.y)));
;         acc[ni][3] *= (1.0f + one * __expf(-bfhi(gb.y))) * __builtin_amdgcn_rcpf(1.0f + __expf(-bfhi(ga.y)));
;       })
;     }
;     SG_EPI({ u32x2 w; w.x = cvt_pk_bf16(acc[ni][0], acc[ni][1]); w.y = cvt_pk_bf16(acc[ni][2], acc[ni][3]); *(u32x2*)(H + row * D + col) = w; })
	v_mov_b32_e32 v9, v171
	v_mov_b32_e32 v14, v171
	v_mov_b32_e32 v13, s27
	v_ashrrev_i32_e32 v10, 3, v14
	v_and_b32_e32 v10, -16, v10
	v_and_b32_e32 v168, 15, v9
	v_ashrrev_i32_e32 v11, 31, v10
	v_or_b32_e32 v12, s26, v168
	v_lshrrev_b32_e32 v14, 1, v14
	v_lshl_add_u64 v[12:13], v[12:13], 0, v[10:11]
	v_and_b32_e32 v16, 32, v14
	v_lshrrev_b32_e32 v9, 2, v9
	v_mov_b64_e32 v[14:15], s[28:29]
	v_cndmask_b32_e64 v8, 1.0, 0, s[12:13]
	v_and_b32_e32 v9, 12, v9
	v_mad_u64_u32 v[14:15], s[38:39], v12, s95, v[14:15]
	s_and_b64 s[12:13], s[12:13], exec
	v_lshl_add_u64 v[10:11], s[2:3], 0, v[10:11]
	v_add_u32_e32 v12, s20, v16
	v_or3_b32 v17, v9, v16, s19
	v_mad_i32_i24 v15, v13, s95, v15
	s_cselect_b32 s6, 0x800, s36
	v_lshl_add_u64 v[10:11], v[10:11], 0, v[168:169]
	v_add_lshl_u32 v168, v12, v9, 1
	v_lshl_add_u64 v[14:15], s[6:7], 1, v[14:15]
	v_mad_u64_u32 v[12:13], s[12:13], v10, s95, v[168:169]
	v_lshlrev_b32_e32 v168, 1, v17
	v_lshl_add_u64 v[14:15], v[14:15], 0, v[168:169]
	s_mov_b64 s[12:13], 0x4701e00
	s_mov_b32 s6, 0x4701000
	v_lshl_add_u64 v[16:17], v[14:15], 0, s[12:13]
	v_add_co_u32_e32 v14, vcc, s6, v14
	v_mad_i32_i24 v13, v11, s95, v13
	s_nop 0
	v_addc_co_u32_e32 v15, vcc, 0, v15, vcc
	v_mov_b64_e32 v[14:15], v[120:121]
	v_lshl_add_u64 v[10:11], s[8:9], 0, v[12:13]
	v_mov_b64_e32 v[12:13], v[122:123]
	s_add_u32 s4, s4, 0x100000
	s_addc_u32 s5, s5, 0
	s_add_u32 s8, s8, 0x800
	s_addc_u32 s9, s9, 0
	s_addk_i32 s36, 0x400
	s_cmp_eq_u32 s4, 0x300000
	s_waitcnt vmcnt(1)
	v_lshlrev_b32_e32 v9, 16, v14
	v_mul_f32_e32 v9, 0xbfb8aa3b, v9
	v_exp_f32_e32 v18, v9
	s_waitcnt vmcnt(0)
	v_lshlrev_b32_e32 v9, 16, v12
	v_mul_f32_e32 v9, 0xbfb8aa3b, v9
	v_exp_f32_e32 v9, v9
	s_nop 0
	v_add_f32_e32 v9, 1.0, v9
	v_rcp_f32_e32 v20, v9
	v_and_b32_e32 v9, 0xffff0000, v14
	v_mul_f32_e32 v9, 0xbfb8aa3b, v9
	v_exp_f32_e32 v19, v9
	v_and_b32_e32 v9, 0xffff0000, v12
	v_mul_f32_e32 v9, 0xbfb8aa3b, v9
	v_exp_f32_e32 v9, v9
	s_nop 0
	v_add_f32_e32 v9, 1.0, v9
	v_rcp_f32_e32 v21, v9
	v_pk_fma_f32 v[18:19], v[8:9], v[18:19], 1.0 op_sel_hi:[0,1,0]
	v_lshlrev_b32_e32 v9, 16, v15
	v_mul_f32_e32 v9, 0xbfb8aa3b, v9
	v_exp_f32_e32 v14, v9
	v_lshlrev_b32_e32 v9, 16, v13
	v_mul_f32_e32 v9, 0xbfb8aa3b, v9
	v_exp_f32_e32 v9, v9
	v_pk_mul_f32 v[18:19], v[20:21], v[18:19]
	v_add_f32_e32 v9, 1.0, v9
	v_rcp_f32_e32 v12, v9
	v_and_b32_e32 v9, 0xffff0000, v15
	v_mul_f32_e32 v9, 0xbfb8aa3b, v9
	v_exp_f32_e32 v15, v9
	v_and_b32_e32 v9, 0xffff0000, v13
	v_mul_f32_e32 v9, 0xbfb8aa3b, v9
	v_exp_f32_e32 v9, v9
	v_pk_mul_f32 v[4:5], v[4:5], v[18:19]
	v_add_f32_e32 v9, 1.0, v9
	v_rcp_f32_e32 v13, v9
	v_pk_fma_f32 v[14:15], v[8:9], v[14:15], 1.0 op_sel_hi:[0,1,0]
	v_pk_mul_f32 v[12:13], v[12:13], v[14:15]
	s_nop 0
	v_pk_mul_f32 v[6:7], v[6:7], v[12:13]
	v_mov_b64_e32 v[10:11], v[124:125]
	s_nop 0
	v_mov_b64_e32 v[12:13], v[126:127]
	s_waitcnt vmcnt(0)
	v_lshlrev_b32_e32 v9, 16, v12
	v_mul_f32_e32 v9, 0xbfb8aa3b, v9
	v_exp_f32_e32 v14, v9
	v_lshlrev_b32_e32 v9, 16, v10
	v_mul_f32_e32 v9, 0xbfb8aa3b, v9
	v_exp_f32_e32 v9, v9
	s_nop 0
	v_add_f32_e32 v9, 1.0, v9
	v_rcp_f32_e32 v16, v9
	v_and_b32_e32 v9, 0xffff0000, v12
	v_mul_f32_e32 v9, 0xbfb8aa3b, v9
	v_exp_f32_e32 v15, v9
	v_and_b32_e32 v9, 0xffff0000, v10
	v_mul_f32_e32 v9, 0xbfb8aa3b, v9
	v_exp_f32_e32 v9, v9
	s_nop 0
	v_add_f32_e32 v9, 1.0, v9
	v_rcp_f32_e32 v17, v9
	v_pk_fma_f32 v[14:15], v[8:9], v[14:15], 1.0 op_sel_hi:[0,1,0]
	v_lshlrev_b32_e32 v9, 16, v13
	v_mul_f32_e32 v9, 0xbfb8aa3b, v9
	v_exp_f32_e32 v12, v9
	v_lshlrev_b32_e32 v9, 16, v11
	v_mul_f32_e32 v9, 0xbfb8aa3b, v9
	v_exp_f32_e32 v9, v9
	v_pk_mul_f32 v[14:15], v[16:17], v[14:15]
	v_add_f32_e32 v9, 1.0, v9
	v_rcp_f32_e32 v10, v9
	v_and_b32_e32 v9, 0xffff0000, v13
	v_mul_f32_e32 v9, 0xbfb8aa3b, v9
	v_exp_f32_e32 v13, v9
	v_and_b32_e32 v9, 0xffff0000, v11
	v_mul_f32_e32 v9, 0xbfb8aa3b, v9
	v_exp_f32_e32 v9, v9
	v_pk_mul_f32 v[0:1], v[0:1], v[14:15]
	v_add_f32_e32 v9, 1.0, v9
	v_rcp_f32_e32 v11, v9
	v_pk_fma_f32 v[8:9], v[8:9], v[12:13], 1.0 op_sel_hi:[0,1,0]
	v_pk_mul_f32 v[8:9], v[10:11], v[8:9]
	s_nop 0
	v_pk_mul_f32 v[2:3], v[2:3], v[8:9]
	s_cbranch_scc0 .LBB0_299
	v_mov_b32_e32 v12, v171
	v_mov_b32_e32 v13, v171
	v_mov_b32_e32 v11, s27
	v_ashrrev_i32_e32 v8, 3, v13
	v_and_b32_e32 v8, -16, v8
	v_ashrrev_i32_e32 v9, 31, v8
	v_and_or_b32 v10, v12, 15, s26
	v_lshl_add_u64 v[8:9], v[10:11], 0, v[8:9]
	v_lshrrev_b32_e32 v10, 1, v13
	v_lshrrev_b32_e32 v11, 2, v12
	v_and_b32_e32 v10, 32, v10
	v_and_b32_e32 v11, 12, v11
	v_readlane_b32 s36, v248, 37
	v_readlane_b32 s2, v249, 52
	v_or3_b32 v10, v11, v10, s19
	v_lshlrev_b64 v[8:9], 11, v[8:9]
	v_readlane_b32 s38, v248, 39
	s_add_i32 s17, s17, s2
	v_readlane_b32 s2, v249, 33
	v_lshl_add_u64 v[8:9], s[24:25], 0, v[8:9]
	v_lshlrev_b32_e32 v168, 1, v10
	s_add_i32 s14, s14, s38
	s_add_i32 s18, s18, s2
	v_cvt_pk_bf16_f32 v4, v4, v5
	v_cvt_pk_bf16_f32 v5, v6, v7
	v_lshl_add_u64 v[6:7], v[8:9], 0, v[168:169]
	v_cvt_pk_bf16_f32 v0, v0, v1
	v_cvt_pk_bf16_f32 v1, v2, v3
	s_cmpk_gt_i32 s14, 0xff
	global_store_dwordx2 v[6:7], v[4:5], off
	v_readlane_b32 s37, v248, 38
	v_readlane_b32 s39, v248, 40
	global_store_dwordx2 v[6:7], v[0:1], off offset:32
	s_cbranch_scc0 .LBB0_298

; DEV void ret_sample_item(const Params& p, int l, int item, unsigned char* smem) {
;     ...
;     const float* S0 = p.in[I_SRET] + (size_t)((l * 128 + b) * 4 + h) * 8192;
;     float* Sn = p.out + O_RETS + (size_t)((l * 128 + b) * 4 + h) * 8192;
;     const float cdec = __expf(lg * 8.0f);
;     float po[8];
; #pragma unroll
;     for (int i = 0; i < 8; ++i) po[i] = 0.f;
;     float kv[8];
; #pragma unroll
;     for (int j = 0; j < 8; ++j) kv[j] = __expf(lg * (float)(7 - j)) * vs[j * 128 + e];
;     float s0v[16];
; #pragma unroll
;     for (int dd = 0; dd < 16; ++dd) s0v[dd] = S0[(dg * 16 + dd) * 128 + e];
; DEV void run_phase(const Params& pin, int ph, unsigned char* smem) {
;     ...
;       ret_scan(p, l);
.LBB0_329:
	s_andn2_b64 vcc, exec, s[0:1]
	s_cbranch_vccnz .LBB0_422
	v_readlane_b32 s45, v248, 43
	s_and_b32 s44, s74, -4
	s_nop 0
	s_lshl_b32 s45, s45, 9
	s_add_i32 s44, s44, s45
	s_and_b32 s45, s74, 3
	s_or_b32 s44, s44, s45
	v_readlane_b32 s52, v248, 28
	v_readlane_b32 s53, v248, 29
	s_ashr_i32 s45, s44, 31
	s_lshl_b64 s[44:45], s[44:45], 15
	v_ashrrev_i32_e32 v236, 7, v171
	v_and_b32_e32 v237, 0x7f, v171
	v_lshl_or_b32 v236, v236, 11, v237
	v_ashrrev_i32_e32 v237, 31, v236
	v_lshlrev_b64 v[236:237], 2, v[236:237]
	s_add_u32 s44, s52, s44
	s_addc_u32 s45, s53, s45
	v_lshl_add_u64 v[234:235], s[44:45], 0, v[236:237]
	s_add_u32 s44, s44, 0x1000
	s_addc_u32 s45, s45, 0
	v_lshl_add_u64 v[238:239], s[44:45], 0, v[236:237]
	global_load_dword v218, v[234:235], off
	global_load_dword v219, v[234:235], off offset:512
	global_load_dword v220, v[234:235], off offset:1024
	global_load_dword v221, v[234:235], off offset:1536
	global_load_dword v222, v[234:235], off offset:2048
	global_load_dword v223, v[234:235], off offset:2560
	global_load_dword v224, v[234:235], off offset:3072
	global_load_dword v225, v[234:235], off offset:3584
	global_load_dword v226, v[238:239], off
	global_load_dword v227, v[238:239], off offset:512
	global_load_dword v228, v[238:239], off offset:1024
	global_load_dword v229, v[238:239], off offset:1536
	global_load_dword v230, v[238:239], off offset:2048
	global_load_dword v231, v[238:239], off offset:2560
	global_load_dword v232, v[238:239], off offset:3072
	global_load_dword v233, v[238:239], off offset:3584
	s_mov_b32 s4, s74
	v_mov_b32_e32 v0, v171
	s_mov_b32 s13, 0x20000
	v_lshl_add_u32 v4, s4, 9, v0
	v_cmp_gt_i32_e32 vcc, s13, v4
	s_and_saveexec_b64 s[0:1], vcc
	v_readlane_b32 s9, v249, 34
	v_readlane_b32 s12, v249, 59
	s_mov_b32 s14, 0x10000
	s_mov_b32 s15, 0xc2fc0000
	s_mov_b32 s16, 0x3f2aaaab
	s_mov_b32 s17, 0x3f317218
	s_mov_b32 s18, 0x33800000
	s_mov_b32 s19, 0x40000
	s_mov_b32 s20, 0x48000
	s_mov_b32 s21, 0x50000
	s_mov_b32 s26, 0x58000
	s_mov_b32 s35, 0x88000
	s_mov_b32 s40, 0x1ffff
	s_cbranch_execz .LBB0_333
	s_add_u32 s2, s28, 0x3500000
	v_readlane_b32 s36, v248, 43
	v_lshlrev_b32_e32 v0, 7, v0
	s_addc_u32 s3, s29, 0
	s_lshl_b32 s6, s36, 4
	v_lshl_add_u32 v5, s4, 16, v0
	s_mov_b64 s[4:5], 0
	v_readlane_b32 s37, v248, 44

; DEV int tidx() { int t = threadIdx.x; asm volatile("" : "+v"(t)); return t; }
; DEV float bf2f(unsigned h) { return __uint_as_float(h << 16); }
; DEV float log_gamma(int h) { return log1pf(-exp2f(-5.0f - (float)h)); }
; DEV void ret_sample_item(const Params& p, int l, int item, unsigned char* smem) {
;   const int b = item >> 2, h = item & 3;
;   bf16_t* Z = (bf16_t*)(p.ws + WS_Z);
;   float* qs = (float*)smem;
;   float* ks = qs + 512;
;   float* vs = ks + 512;
;   float* inn = vs + 1024;
;   float* part = inn + 64;
;   const int tid = tidx(), lane = tid & 63, w = tid >> 6;
;   const size_t rowbase = (size_t)TP + b * 8;
;   const float lg = log_gamma(h);
;   {
;     const int i = tid >> 6, d = tid & 63;
;     qs[tid] = bf2f(Z[(rowbase + i) * NIN + RQ + h * 64 + d]);
;     ks[tid] = bf2f(Z[(rowbase + i) * NIN + RK + h * 64 + d]) * 0.125f;
; #pragma unroll
;     for (int it = 0; it < 2; ++it) { const int idx = tid + it * 512, ii = idx >> 7, e = idx & 127; vs[idx] = bf2f(Z[(rowbase + ii) * NIN + RV + h * 128 + e]); }
;   }
;   __syncthreads();
;     ...
;     const float* S0 = p.in[I_SRET] + (size_t)((l * 128 + b) * 4 + h) * 8192;
;     float* Sn = p.out + O_RETS + (size_t)((l * 128 + b) * 4 + h) * 8192;
;     const float cdec = __expf(lg * 8.0f);
;     float po[8];
; #pragma unroll
;     for (int i = 0; i < 8; ++i) po[i] = 0.f;
;     float kv[8];
; #pragma unroll
;     for (int j = 0; j < 8; ++j) kv[j] = __expf(lg * (float)(7 - j)) * vs[j * 128 + e];
;     float s0v[16];
; #pragma unroll
;     for (int dd = 0; dd < 16; ++dd) s0v[dd] = S0[(dg * 16 + dd) * 128 + e];
.LBB0_353:
	s_and_b64 vcc, exec, s[0:1]
	s_cbranch_vccz .LBB0_336
	s_cmp_eq_u32 s12, s74
	s_cbranch_scc1 .Lrs_skip_s0
	s_and_b32 s44, s12, -4
	s_add_i32 s44, s44, s19
	s_and_b32 s45, s12, 3
	s_or_b32 s44, s44, s45
	v_readlane_b32 s52, v248, 28
	v_readlane_b32 s53, v248, 29
	s_ashr_i32 s45, s44, 31
	s_lshl_b64 s[44:45], s[44:45], 15
	v_ashrrev_i32_e32 v236, 7, v171
	v_and_b32_e32 v237, 0x7f, v171
	v_lshl_or_b32 v236, v236, 11, v237
	v_ashrrev_i32_e32 v237, 31, v236
	v_lshlrev_b64 v[236:237], 2, v[236:237]
	s_add_u32 s44, s52, s44
	s_addc_u32 s45, s53, s45
	v_lshl_add_u64 v[234:235], s[44:45], 0, v[236:237]
	s_add_u32 s44, s44, 0x1000
	s_addc_u32 s45, s45, 0
	v_lshl_add_u64 v[238:239], s[44:45], 0, v[236:237]
	global_load_dword v218, v[234:235], off
	global_load_dword v219, v[234:235], off offset:512
	global_load_dword v220, v[234:235], off offset:1024
	global_load_dword v221, v[234:235], off offset:1536
	global_load_dword v222, v[234:235], off offset:2048
	global_load_dword v223, v[234:235], off offset:2560
	global_load_dword v224, v[234:235], off offset:3072
	global_load_dword v225, v[234:235], off offset:3584
	global_load_dword v226, v[238:239], off
	global_load_dword v227, v[238:239], off offset:512
	global_load_dword v228, v[238:239], off offset:1024
	global_load_dword v229, v[238:239], off offset:1536
	global_load_dword v230, v[238:239], off offset:2048
	global_load_dword v231, v[238:239], off offset:2560
	global_load_dword v232, v[238:239], off offset:3072
	global_load_dword v233, v[238:239], off offset:3584
.Lrs_skip_s0:
	s_and_b32 s2, s12, 3
	v_cvt_f32_ubyte0_e32 v0, s2
	v_sub_f32_e32 v0, 0xc0a00000, v0
	s_mov_b32 s3, 0xc2fc0000
	s_lshl_b32 s0, s12, 1
	v_cmp_gt_f32_e32 vcc, s3, v0
	s_and_b32 s0, s0, -8
	s_ashr_i32 s1, s0, 31
	v_cndmask_b32_e32 v2, 0, v203, vcc
	v_add_f32_e32 v0, v0, v2
	s_add_u32 s0, s0, 0x4000
	v_exp_f32_e32 v0, v0
	s_addc_u32 s1, s1, 0
	s_and_b64 s[4:5], vcc, exec
	s_cselect_b32 s3, 0xffffffc0, 0
	v_ldexp_f32 v10, v0, s3
	v_sub_f32_e32 v0, 1.0, v10
	v_add_f32_e32 v2, -1.0, v0
	v_sub_f32_e32 v3, v2, v0
	v_add_f32_e32 v3, 1.0, v3
	v_sub_f32_e64 v2, -v10, v2
	v_add_f32_e32 v4, v2, v3
	v_frexp_mant_f32_e32 v5, v0
	v_cvt_f64_f32_e32 v[2:3], v0
	s_mov_b32 s3, 0x3f2aaaab
	v_frexp_exp_i32_f64_e32 v2, v[2:3]
	v_cmp_gt_f32_e32 vcc, s3, v5
	s_waitcnt lgkmcnt(0)
	v_mov_b32_e32 v1, v171
	s_lshl_b32 s6, s2, 7
	v_subbrev_co_u32_e32 v11, vcc, 0, v2, vcc
	v_sub_u32_e32 v2, 0, v11
	v_ldexp_f32 v0, v0, v2
	v_add_f32_e32 v3, -1.0, v0
	v_add_f32_e32 v5, 1.0, v0
	v_ldexp_f32 v2, v4, v2
	v_add_f32_e32 v4, 1.0, v3
	v_add_f32_e32 v6, -1.0, v5
	v_sub_f32_e32 v4, v0, v4
	v_sub_f32_e32 v0, v0, v6
	v_add_f32_e32 v4, v2, v4
	v_add_f32_e32 v0, v2, v0
	v_ashrrev_i32_e32 v66, 6, v1
	v_add_f32_e32 v12, v3, v4
	v_add_f32_e32 v13, v5, v0
	v_sub_f32_e32 v3, v12, v3
	v_sub_f32_e32 v2, v13, v5
	v_ashrrev_i32_e32 v67, 31, v66
	v_sub_f32_e32 v15, v4, v3
	v_sub_f32_e32 v16, v0, v2
	v_lshl_add_u64 v[2:3], s[0:1], 0, v[66:67]
	v_mov_b64_e32 v[4:5], s[30:31]
	v_mad_u64_u32 v[64:65], s[4:5], v2, s95, v[4:5]
	v_and_b32_e32 v72, 63, v1
	v_mad_i32_i24 v65, v3, s95, v65
	v_add_u32_e32 v8, 0x200, v1
	v_lshl_add_u64 v[2:3], v[64:65], 0, s[6:7]
	v_lshlrev_b32_e32 v168, 1, v72
	v_ashrrev_i32_e32 v68, 7, v1
	v_ashrrev_i32_e32 v8, 7, v8
	v_lshl_add_u64 v[2:3], v[2:3], 0, v[168:169]
	v_ashrrev_i32_e32 v69, 31, v68
	v_ashrrev_i32_e32 v9, 31, v8
	global_load_ushort v18, v[2:3], off
	global_load_ushort v19, v[2:3], off offset:512
	v_lshl_add_u64 v[2:3], s[0:1], 0, v[68:69]
	v_lshl_add_u64 v[8:9], s[0:1], 0, v[8:9]
	v_mad_u64_u32 v[6:7], s[4:5], v2, s95, v[4:5]
	v_mad_u64_u32 v[4:5], s[0:1], v8, s95, v[4:5]
	v_and_b32_e32 v0, 0x7f, v1
	v_mad_i32_i24 v7, v3, s95, v7
	s_lshl_b32 s4, s2, 8
	s_mov_b32 s5, s7
	v_mad_i32_i24 v5, v9, s95, v5
	v_lshl_add_u64 v[2:3], v[6:7], 0, s[4:5]
	v_lshlrev_b32_e32 v6, 1, v0
	v_mov_b32_e32 v7, v169
	v_lshl_add_u64 v[4:5], v[4:5], 0, s[4:5]
	v_lshl_add_u64 v[2:3], v[2:3], 0, v[6:7]
	v_lshl_add_u64 v[4:5], v[4:5], 0, v[6:7]
	global_load_ushort v3, v[2:3], off offset:1024
	s_nop 0
	global_load_ushort v4, v[4:5], off offset:1024
	v_rcp_f32_e32 v14, v13
	s_mov_b32 s0, 0x3f317218
	v_cmp_nlt_f32_e32 vcc, 1.0, v10
	v_mul_f32_e32 v17, v12, v14
	v_mul_f32_e32 v2, v13, v17
	v_fma_f32 v5, v17, v13, -v2
	v_fmac_f32_e32 v5, v17, v16
	v_add_f32_e32 v6, v2, v5
	v_sub_f32_e32 v7, v12, v6
	v_sub_f32_e32 v8, v12, v7
	v_sub_f32_e32 v2, v6, v2
	v_sub_f32_e32 v6, v8, v6
	v_add_f32_e32 v6, v15, v6
	v_sub_f32_e32 v2, v2, v5
	v_add_f32_e32 v2, v2, v6
	v_add_f32_e32 v5, v7, v2
	v_mul_f32_e32 v6, v14, v5
	v_mul_f32_e32 v8, v13, v6
	v_fma_f32 v9, v6, v13, -v8
	v_fmac_f32_e32 v9, v6, v16
	v_sub_f32_e32 v7, v7, v5
	v_add_f32_e32 v2, v2, v7
	v_add_f32_e32 v7, v8, v9
	v_sub_f32_e32 v12, v5, v7
	v_sub_f32_e32 v5, v5, v12
	v_sub_f32_e32 v8, v7, v8
	v_sub_f32_e32 v5, v5, v7
	v_add_f32_e32 v2, v2, v5
	v_sub_f32_e32 v5, v8, v9
	v_add_f32_e32 v2, v5, v2
	v_add_f32_e32 v5, v17, v6
	v_sub_f32_e32 v7, v5, v17
	v_sub_f32_e32 v6, v6, v7
	v_cvt_f32_i32_e32 v7, v11
	v_add_f32_e32 v2, v12, v2
	v_mul_f32_e32 v2, v14, v2
	v_add_f32_e32 v2, v6, v2
	v_mul_f32_e32 v11, 0x3f317218, v7
	v_add_f32_e32 v6, v5, v2
	v_fma_f32 v12, v7, s0, -v11
	v_mul_f32_e32 v8, v6, v6
	v_fmac_f32_e32 v12, 0xb102e308, v7
	v_sub_f32_e32 v5, v6, v5
	v_fmamk_f32 v9, v8, 0x3e9b6dac, v201
	v_sub_f32_e32 v2, v2, v5
	v_add_f32_e32 v5, v11, v12
	v_fmaak_f32 v9, v8, v9, 0x3f2aaada
	v_sub_f32_e32 v7, v5, v11
	v_ldexp_f32 v11, v6, 1
	v_mul_f32_e32 v6, v6, v8
	v_mul_f32_e32 v6, v6, v9
	v_add_f32_e32 v8, v11, v6
	v_sub_f32_e32 v9, v8, v11
	v_ldexp_f32 v2, v2, 1
	v_sub_f32_e32 v6, v6, v9
	v_add_f32_e32 v2, v2, v6
	v_add_f32_e32 v6, v8, v2
	v_sub_f32_e32 v8, v6, v8
	v_sub_f32_e32 v2, v2, v8
	v_add_f32_e32 v8, v5, v6
	v_sub_f32_e32 v9, v8, v5
	v_sub_f32_e32 v11, v8, v9
	v_sub_f32_e32 v7, v12, v7
	v_sub_f32_e32 v5, v5, v11
	v_sub_f32_e32 v6, v6, v9
	v_add_f32_e32 v5, v6, v5
	v_add_f32_e32 v6, v7, v2
	v_sub_f32_e32 v9, v6, v7
	v_sub_f32_e32 v11, v6, v9
	v_add_f32_e32 v5, v6, v5
	v_sub_f32_e32 v7, v7, v11
	v_sub_f32_e32 v2, v2, v9
	v_add_f32_e32 v6, v8, v5
	v_add_f32_e32 v2, v2, v7
	v_sub_f32_e32 v7, v6, v8
	v_sub_f32_e32 v5, v5, v7
	v_add_f32_e32 v5, v2, v5
	v_lshl_add_u32 v2, v1, 2, 0
	s_waitcnt vmcnt(0)
	v_lshlrev_b32_e32 v3, 16, v3
	v_lshlrev_b32_e32 v4, 16, v4
	ds_write2st64_b32 v2, v3, v4 offset0:16 offset1:24
	v_add_f32_e32 v3, v6, v5
	v_cndmask_b32_e32 v3, v204, v3, vcc
	v_cmp_neq_f32_e32 vcc, 1.0, v10
	s_mov_b32 s0, 0x33800000
	v_lshlrev_b32_e32 v8, 16, v19
	v_cndmask_b32_e32 v3, v205, v3, vcc
	v_cmp_gt_f32_e32 vcc, s0, v10
	v_lshlrev_b32_e32 v7, 16, v18
	v_mul_f32_e32 v8, 0x3e000000, v8
	v_cndmask_b32_e64 v67, v3, -v10, vcc
	v_cmp_gt_i32_e32 vcc, 64, v1
	ds_write2st64_b32 v2, v7, v8 offset1:8
	s_waitcnt lgkmcnt(0)
	s_barrier
; DEV void ret_sample_item(const Params& p, int l, int item, unsigned char* smem) {
;     ...
;   if (tid < 64) {
;     const int i = tid >> 3, j = tid & 7;
;     float dsum = 0.f;
;     for (int d = 0; d < 64; ++d) dsum += qs[i * 64 + d] * ks[j * 64 + d];
;     inn[tid] = (i >= j) ? dsum * __expf(lg * (float)(i - j)) : 0.f;
;   }
;   {
;     const int e = tid & 127, dg = tid >> 7;
;     const float* S0 = p.in[I_SRET] + (size_t)((l * 128 + b) * 4 + h) * 8192;
;     float* Sn = p.out + O_RETS + (size_t)((l * 128 + b) * 4 + h) * 8192;
;     const float cdec = __expf(lg * 8.0f);
;     float po[8];
; #pragma unroll
;     for (int i = 0; i < 8; ++i) po[i] = 0.f;
;     float kv[8];
; #pragma unroll
;     for (int j = 0; j < 8; ++j) kv[j] = __expf(lg * (float)(7 - j)) * vs[j * 128 + e];
;     float s0v[16];
; #pragma unroll
;     for (int dd = 0; dd < 16; ++dd) s0v[dd] = S0[(dg * 16 + dd) * 128 + e];
	s_and_saveexec_b64 s[0:1], vcc
	s_cbranch_execz .LBB0_356
	v_ashrrev_i32_e32 v3, 3, v1
	v_and_b32_e32 v1, 7, v1
	v_lshl_add_u32 v36, v3, 8, 0
	v_lshl_add_u32 v37, v1, 8, 0
	ds_read_b128 v[4:7], v36
	ds_read_b128 v[8:11], v36 offset:16
	ds_read_b128 v[12:15], v37 offset:2048
	ds_read_b128 v[16:19], v36 offset:32
	ds_read_b128 v[20:23], v36 offset:48
	ds_read_b128 v[24:27], v37 offset:2064
	ds_read_b128 v[28:31], v37 offset:2080
	ds_read_b128 v[32:35], v37 offset:2096
	s_waitcnt lgkmcnt(5)
	v_fma_f32 v38, v4, v12, 0
	v_fmac_f32_e32 v38, v5, v13
	v_fmac_f32_e32 v38, v6, v14
	v_fmac_f32_e32 v38, v7, v15
	s_waitcnt lgkmcnt(2)
	v_fmac_f32_e32 v38, v8, v24
	v_fmac_f32_e32 v38, v9, v25
	v_fmac_f32_e32 v38, v10, v26
	v_fmac_f32_e32 v38, v11, v27
	s_waitcnt lgkmcnt(1)
	v_fmac_f32_e32 v38, v16, v28
	v_fmac_f32_e32 v38, v17, v29
	v_fmac_f32_e32 v38, v18, v30
	v_fmac_f32_e32 v38, v19, v31
	ds_read_b128 v[4:7], v36 offset:64
	ds_read_b128 v[8:11], v37 offset:2112
	s_waitcnt lgkmcnt(2)
	v_fmac_f32_e32 v38, v20, v32
	v_fmac_f32_e32 v38, v21, v33
	v_fmac_f32_e32 v38, v22, v34
	v_fmac_f32_e32 v38, v23, v35
	ds_read_b128 v[12:15], v36 offset:80
	ds_read_b128 v[16:19], v37 offset:2128
	s_waitcnt lgkmcnt(2)
	v_fmac_f32_e32 v38, v4, v8
	v_fmac_f32_e32 v38, v5, v9
	v_fmac_f32_e32 v38, v6, v10
	v_fmac_f32_e32 v38, v7, v11
	ds_read_b128 v[4:7], v36 offset:96
	ds_read_b128 v[8:11], v37 offset:2144
	s_waitcnt lgkmcnt(2)
	v_fmac_f32_e32 v38, v12, v16
	v_fmac_f32_e32 v38, v13, v17
	v_fmac_f32_e32 v38, v14, v18
	v_fmac_f32_e32 v38, v15, v19
	ds_read_b128 v[12:15], v36 offset:112
	ds_read_b128 v[16:19], v37 offset:2160
	s_waitcnt lgkmcnt(2)
	v_fmac_f32_e32 v38, v4, v8
	v_fmac_f32_e32 v38, v5, v9
	v_fmac_f32_e32 v38, v6, v10
	v_fmac_f32_e32 v38, v7, v11
	ds_read_b128 v[4:7], v36 offset:128
	ds_read_b128 v[8:11], v37 offset:2176
	s_waitcnt lgkmcnt(2)
	v_fmac_f32_e32 v38, v12, v16
	v_fmac_f32_e32 v38, v13, v17
	v_fmac_f32_e32 v38, v14, v18
	v_fmac_f32_e32 v38, v15, v19
	ds_read_b128 v[12:15], v36 offset:144
	ds_read_b128 v[16:19], v37 offset:2192
	s_waitcnt lgkmcnt(2)
	v_fmac_f32_e32 v38, v4, v8
	v_fmac_f32_e32 v38, v5, v9
	v_fmac_f32_e32 v38, v6, v10
	v_fmac_f32_e32 v38, v7, v11
	ds_read_b128 v[4:7], v36 offset:160
	ds_read_b128 v[8:11], v37 offset:2208
	s_waitcnt lgkmcnt(2)
	v_fmac_f32_e32 v38, v12, v16
	v_fmac_f32_e32 v38, v13, v17
	v_fmac_f32_e32 v38, v14, v18
	v_fmac_f32_e32 v38, v15, v19
	ds_read_b128 v[12:15], v36 offset:176
	ds_read_b128 v[16:19], v37 offset:2224
	s_waitcnt lgkmcnt(2)
	v_fmac_f32_e32 v38, v4, v8
	v_fmac_f32_e32 v38, v5, v9
	v_fmac_f32_e32 v38, v6, v10
	v_fmac_f32_e32 v38, v7, v11
	ds_read_b128 v[4:7], v36 offset:192
	ds_read_b128 v[8:11], v37 offset:2240
	s_waitcnt lgkmcnt(2)
	v_fmac_f32_e32 v38, v12, v16
	v_fmac_f32_e32 v38, v13, v17
	v_fmac_f32_e32 v38, v14, v18
	v_fmac_f32_e32 v38, v15, v19
	ds_read_b128 v[12:15], v36 offset:208
	ds_read_b128 v[16:19], v37 offset:2256
	s_waitcnt lgkmcnt(2)
	v_fmac_f32_e32 v38, v4, v8
	v_fmac_f32_e32 v38, v5, v9
	v_fmac_f32_e32 v38, v6, v10
	v_fmac_f32_e32 v38, v7, v11
	ds_read_b128 v[4:7], v36 offset:224
	ds_read_b128 v[8:11], v37 offset:2272
	s_waitcnt lgkmcnt(2)
	v_fmac_f32_e32 v38, v12, v16
	v_fmac_f32_e32 v38, v13, v17
	v_pk_mul_f32 v[12:13], v[14:15], v[18:19]
	v_cmp_ge_i32_e32 vcc, v3, v1
	v_add_f32_e32 v12, v38, v12
	v_add_f32_e32 v20, v12, v13
	s_waitcnt lgkmcnt(0)
	v_pk_mul_f32 v[4:5], v[4:5], v[8:9]
	ds_read_b128 v[12:15], v36 offset:240
	ds_read_b128 v[16:19], v37 offset:2288
	v_add_f32_e32 v4, v20, v4
	v_add_f32_e32 v8, v4, v5
	v_pk_mul_f32 v[4:5], v[6:7], v[10:11]
	s_nop 0
	v_add_f32_e32 v4, v8, v4
	v_add_f32_e32 v6, v4, v5
	v_sub_u32_e32 v4, v3, v1
	v_cvt_f32_i32_e32 v7, v4
	s_waitcnt lgkmcnt(0)
	v_pk_mul_f32 v[4:5], v[12:13], v[16:17]
	s_nop 0
	v_add_f32_e32 v4, v6, v4
	v_add_f32_e32 v6, v4, v5
	v_mul_f32_e32 v4, v67, v7
	v_mul_f32_e32 v4, 0x3fb8aa3b, v4
	v_exp_f32_e32 v7, v4
	v_pk_mul_f32 v[4:5], v[14:15], v[18:19]
	s_nop 0
	v_add_f32_e32 v4, v6, v4
	v_add_f32_e32 v4, v4, v5
	v_mul_f32_e32 v4, v7, v4
	v_cndmask_b32_e32 v1, 0, v4, vcc
	ds_write_b32 v2, v1 offset:8192
.LBB0_356:
	s_or_b64 exec, exec, s[0:1]
	v_mul_f32_e32 v1, 0x41000000, v67
	v_mul_f32_e32 v4, 0x3fb8aa3b, v1
	v_lshl_add_u32 v69, v0, 2, 0
	v_mul_f32_e32 v1, 0x40e00000, v67
	v_mul_f32_e32 v1, 0x3fb8aa3b, v1
	ds_read2st64_b32 v[2:3], v69 offset0:16 offset1:18
	v_exp_f32_e32 v1, v1
	s_and_b32 s0, s12, -4
	s_add_i32 s0, s0, s19
	s_or_b32 s0, s0, s2
	s_waitcnt lgkmcnt(0)
	v_mul_f32_e32 v73, v1, v2
	v_mul_f32_e32 v1, 0x40c00000, v67
	v_mul_f32_e32 v1, 0x3fb8aa3b, v1
	v_exp_f32_e32 v1, v1
	s_ashr_i32 s1, s0, 31
	s_lshl_b64 s[2:3], s[0:1], 15
	s_add_u32 s0, s20, s2
	v_mul_f32_e32 v74, v1, v3
	v_mul_f32_e32 v1, 0x40a00000, v67
	v_mul_f32_e32 v1, 0x3fb8aa3b, v1
	ds_read2st64_b32 v[2:3], v69 offset0:20 offset1:22
	v_exp_f32_e32 v1, v1
	v_readlane_b32 s44, v248, 20
	s_addc_u32 s1, s21, s3
	v_readlane_b32 s52, v248, 28
	s_waitcnt lgkmcnt(0)
	v_mul_f32_e32 v75, v1, v2
	v_mul_f32_e32 v1, 4.0, v67
	v_mul_f32_e32 v1, 0x3fb8aa3b, v1
	v_exp_f32_e32 v1, v1
	v_lshl_or_b32 v70, v68, 11, v0
	v_readlane_b32 s53, v248, 29
	s_add_u32 s2, s52, s2
	v_mul_f32_e32 v76, v1, v3
	v_mul_f32_e32 v1, 0x40400000, v67
	v_mul_f32_e32 v1, 0x3fb8aa3b, v1
	ds_read2st64_b32 v[2:3], v69 offset0:24 offset1:26
	v_exp_f32_e32 v1, v1
	v_ashrrev_i32_e32 v71, 31, v70
	s_addc_u32 s3, s53, s3
	v_lshlrev_b64 v[32:33], 2, v[70:71]
	s_waitcnt lgkmcnt(0)
	v_mul_f32_e32 v77, v1, v2
	v_add_f32_e32 v1, v67, v67
	v_mul_f32_e32 v1, 0x3fb8aa3b, v1
	v_exp_f32_e32 v1, v1
	v_lshl_add_u32 v93, v68, 6, 0
	v_exp_f32_e32 v81, v4
	v_readlane_b32 s45, v248, 21
	v_mul_f32_e32 v78, v1, v3
	v_mul_f32_e32 v1, 0x3fb8aa3b, v67
	ds_read2st64_b32 v[2:3], v69 offset0:28 offset1:30
	v_exp_f32_e32 v1, v1
	v_readlane_b32 s46, v248, 22
	v_readlane_b32 s47, v248, 23
	v_readlane_b32 s48, v248, 24
	s_waitcnt lgkmcnt(0)
; DEV void ret_sample_item(const Params& p, int l, int item, unsigned char* smem) {
;     ...
; #pragma unroll
;     for (int dd = 0; dd < 16; ++dd) {
;       const int d = dg * 16 + dd;
;       const float s0 = s0v[dd];
;       float a = cdec * s0;
; #pragma unroll
;       for (int j = 0; j < 8; ++j) a += ks[j * 64 + d] * kv[j];
;       Sn[d * 128 + e] = a;
; #pragma unroll
;       for (int i = 0; i < 8; ++i) po[i] += qs[i * 64 + d] * s0;
;     }
	v_mul_f32_e32 v79, v1, v2
	v_mul_f32_e32 v1, 0, v67
	v_mul_f32_e32 v1, 0x3fb8aa3b, v1
	v_exp_f32_e32 v1, v1
	v_readlane_b32 s49, v248, 25
	v_readlane_b32 s50, v248, 26
	v_readlane_b32 s51, v248, 27
	v_mul_f32_e32 v80, v1, v3
	v_lshl_add_u64 v[0:1], s[2:3], 0, v[32:33]
	s_movk_i32 s2, 0x1000
	v_add_co_u32_e32 v0, vcc, s2, v0
	v_lshl_add_u64 v[32:33], s[0:1], 0, v[32:33]
	s_nop 0
	v_addc_co_u32_e32 v1, vcc, 0, v1, vcc
	ds_read_b128 v[0:3], v93 offset:2048
	ds_read_b128 v[4:7], v93 offset:2304
	ds_read_b128 v[8:11], v93 offset:2560
	ds_read_b128 v[12:15], v93 offset:2816
	ds_read_b128 v[16:19], v93 offset:3072
	ds_read_b128 v[20:23], v93 offset:3328
	s_waitcnt lgkmcnt(5)
	v_mul_f32_e32 v0, v73, v0
	ds_read_b128 v[24:27], v93 offset:3584
	ds_read_b128 v[28:31], v93 offset:3840
	v_mul_f32_e32 v2, v73, v2
	ds_read_b128 v[40:43], v93 offset:512
	ds_read_b128 v[44:47], v93 offset:768
	ds_read_b128 v[48:51], v93 offset:1024
	ds_read_b128 v[52:55], v93 offset:1280
	ds_read_b128 v[56:59], v93 offset:1536
	ds_read_b128 v[60:63], v93 offset:1792
	v_cmp_lt_i32_e32 vcc, -1, v66
	v_readlane_b32 s54, v248, 30
	v_readlane_b32 s55, v248, 31
	v_readlane_b32 s56, v248, 32
	v_readlane_b32 s57, v248, 33
	v_readlane_b32 s58, v248, 34
	v_readlane_b32 s59, v248, 35
	ds_read_b128 v[36:39], v93 offset:256
	s_waitcnt vmcnt(15)
	v_fmac_f32_e32 v0, v81, v218
	s_waitcnt lgkmcnt(13)
	v_fmac_f32_e32 v0, v74, v4
	s_waitcnt lgkmcnt(12)
	v_fmac_f32_e32 v0, v75, v8
	v_mul_f32_e32 v4, v73, v1
	s_waitcnt lgkmcnt(11)
	v_fmac_f32_e32 v0, v76, v12
	s_waitcnt vmcnt(14)
	v_fmac_f32_e32 v4, v81, v219
	s_waitcnt lgkmcnt(10)
	v_fmac_f32_e32 v0, v77, v16
	v_fmac_f32_e32 v4, v74, v5
	s_waitcnt lgkmcnt(9)
	v_fmac_f32_e32 v0, v78, v20
	v_fmac_f32_e32 v4, v75, v9
	s_waitcnt lgkmcnt(8)
	v_fmac_f32_e32 v0, v79, v24
	v_fmac_f32_e32 v4, v76, v13
	s_waitcnt vmcnt(13)
	v_fmac_f32_e32 v2, v81, v220
	s_waitcnt lgkmcnt(7)
	v_fmac_f32_e32 v0, v80, v28
	v_fmac_f32_e32 v4, v77, v17
	v_fmac_f32_e32 v2, v74, v6
	global_store_dword v[32:33], v0, off
	v_fmac_f32_e32 v4, v78, v21
	v_or_b32_e32 v0, 0x80, v70
	v_fmac_f32_e32 v2, v75, v10
	v_fmac_f32_e32 v4, v79, v25
	v_ashrrev_i32_e32 v1, 31, v0
	v_fmac_f32_e32 v2, v76, v14
	v_fmac_f32_e32 v4, v80, v29
	v_lshl_add_u64 v[0:1], v[0:1], 2, s[0:1]
	v_fmac_f32_e32 v2, v77, v18
	global_store_dword v[0:1], v4, off
	v_fmac_f32_e32 v2, v78, v22
	v_or_b32_e32 v0, 0x100, v70
	v_fmac_f32_e32 v2, v79, v26
	v_ashrrev_i32_e32 v1, 31, v0
	v_fmac_f32_e32 v2, v80, v30
	v_lshl_add_u64 v[0:1], v[0:1], 2, s[0:1]
	global_store_dword v[0:1], v2, off
	v_mul_f32_e32 v2, v73, v3
	s_waitcnt vmcnt(15)
	v_fmac_f32_e32 v2, v81, v221
	v_fmac_f32_e32 v2, v74, v7
	v_fmac_f32_e32 v2, v75, v11
	v_fmac_f32_e32 v2, v76, v15
	v_fmac_f32_e32 v2, v77, v19
	v_fmac_f32_e32 v2, v78, v23
	v_or_b32_e32 v0, 0x180, v70
	v_fmac_f32_e32 v2, v79, v27
	v_ashrrev_i32_e32 v1, 31, v0
	v_fmac_f32_e32 v2, v80, v31
	v_lshl_add_u64 v[0:1], v[0:1], 2, s[0:1]
	global_store_dword v[0:1], v2, off
	ds_read_b128 v[0:3], v93 offset:2064
	ds_read_b128 v[4:7], v93 offset:2320
	ds_read_b128 v[8:11], v93 offset:2576
	ds_read_b128 v[12:15], v93 offset:2832
	ds_read_b128 v[16:19], v93 offset:3088
	ds_read_b128 v[20:23], v93 offset:3344
	s_waitcnt lgkmcnt(5)
	v_mul_f32_e32 v0, v73, v0
	ds_read_b128 v[32:35], v93
	s_waitcnt vmcnt(15)
	v_fmac_f32_e32 v0, v81, v222
	s_waitcnt lgkmcnt(5)
	v_fmac_f32_e32 v0, v74, v4
	ds_read_b128 v[24:27], v93 offset:3600
	ds_read_b128 v[28:31], v93 offset:3856
	s_waitcnt lgkmcnt(6)
	v_fmac_f32_e32 v0, v75, v8
	v_mul_f32_e32 v4, v73, v1
	s_waitcnt lgkmcnt(5)
	v_fmac_f32_e32 v0, v76, v12
	s_waitcnt vmcnt(14)
	v_fmac_f32_e32 v4, v81, v223
	s_waitcnt lgkmcnt(4)
	v_fmac_f32_e32 v0, v77, v16
	v_fmac_f32_e32 v4, v74, v5
	s_waitcnt lgkmcnt(2)
	v_fma_f32 v85, v218, v32, 0
	v_fmac_f32_e32 v0, v78, v20
	v_or_b32_e32 v32, 0x200, v70
	v_fmac_f32_e32 v4, v75, v9
	v_mul_f32_e32 v2, v73, v2
	v_fmac_f32_e32 v85, v219, v33
	s_waitcnt lgkmcnt(1)
	v_fmac_f32_e32 v0, v79, v24
	v_ashrrev_i32_e32 v33, 31, v32
	v_fmac_f32_e32 v4, v76, v13
	s_waitcnt vmcnt(13)
	v_fmac_f32_e32 v2, v81, v224
	s_waitcnt lgkmcnt(0)
	v_fmac_f32_e32 v0, v80, v28
	v_lshl_add_u64 v[32:33], v[32:33], 2, s[0:1]
	v_fmac_f32_e32 v4, v77, v17
	v_fmac_f32_e32 v2, v74, v6
	global_store_dword v[32:33], v0, off
	v_fmac_f32_e32 v4, v78, v21
	v_or_b32_e32 v0, 0x280, v70
	v_fmac_f32_e32 v2, v75, v10
	v_fmac_f32_e32 v4, v79, v25
	v_ashrrev_i32_e32 v1, 31, v0
	v_fmac_f32_e32 v2, v76, v14
	v_fmac_f32_e32 v4, v80, v29
	v_lshl_add_u64 v[0:1], v[0:1], 2, s[0:1]
	v_fmac_f32_e32 v2, v77, v18
	global_store_dword v[0:1], v4, off
	v_fmac_f32_e32 v2, v78, v22
	v_or_b32_e32 v0, 0x300, v70
	v_fmac_f32_e32 v2, v79, v26
	v_ashrrev_i32_e32 v1, 31, v0
	v_fmac_f32_e32 v2, v80, v30
	v_lshl_add_u64 v[0:1], v[0:1], 2, s[0:1]
	global_store_dword v[0:1], v2, off
	v_mul_f32_e32 v2, v73, v3
	s_waitcnt vmcnt(15)
	v_fmac_f32_e32 v2, v81, v225
	v_fmac_f32_e32 v2, v74, v7
	v_fmac_f32_e32 v2, v75, v11
	v_fmac_f32_e32 v2, v76, v15
	v_fmac_f32_e32 v2, v77, v19
	v_fmac_f32_e32 v2, v78, v23
	v_or_b32_e32 v0, 0x380, v70
	v_fmac_f32_e32 v2, v79, v27
	v_ashrrev_i32_e32 v1, 31, v0
	v_fmac_f32_e32 v2, v80, v31
	v_lshl_add_u64 v[0:1], v[0:1], 2, s[0:1]
	global_store_dword v[0:1], v2, off
	ds_read_b128 v[0:3], v93 offset:2080
	ds_read_b128 v[4:7], v93 offset:2336
	ds_read_b128 v[8:11], v93 offset:2592
	ds_read_b128 v[12:15], v93 offset:2848
	v_fmac_f32_e32 v85, v220, v34
	s_waitcnt lgkmcnt(3)
	v_mul_f32_e32 v0, v73, v0
	ds_read_b128 v[16:19], v93 offset:3104
	ds_read_b128 v[20:23], v93 offset:3360
	v_fmac_f32_e32 v85, v221, v35
	ds_read_b128 v[32:35], v93 offset:16
	s_waitcnt vmcnt(15)
; DEV void ret_sample_item(const Params& p, int l, int item, unsigned char* smem) {
;     ...
;     for (int dd = 0; dd < 16; ++dd) {
;       const int d = dg * 16 + dd;
;       const float s0 = s0v[dd];
;       float a = cdec * s0;
; #pragma unroll
;       for (int j = 0; j < 8; ++j) a += ks[j * 64 + d] * kv[j];
;       Sn[d * 128 + e] = a;
; #pragma unroll
;       for (int i = 0; i < 8; ++i) po[i] += qs[i * 64 + d] * s0;
;     }
	v_fmac_f32_e32 v0, v81, v226
	s_waitcnt lgkmcnt(5)
	v_fmac_f32_e32 v0, v74, v4
	ds_read_b128 v[24:27], v93 offset:3616
	ds_read_b128 v[28:31], v93 offset:3872
	v_fma_f32 v86, v218, v36, 0
	s_waitcnt lgkmcnt(6)
	v_fmac_f32_e32 v0, v75, v8
	v_mul_f32_e32 v4, v73, v1
	v_fmac_f32_e32 v86, v219, v37
	s_waitcnt lgkmcnt(5)
	v_fmac_f32_e32 v0, v76, v12
	s_waitcnt vmcnt(14)
	v_fmac_f32_e32 v4, v81, v227
	v_fmac_f32_e32 v86, v220, v38
	s_waitcnt lgkmcnt(4)
	v_fmac_f32_e32 v0, v77, v16
	v_fmac_f32_e32 v4, v74, v5
	v_fmac_f32_e32 v86, v221, v39
	ds_read_b128 v[36:39], v93 offset:272
	s_waitcnt lgkmcnt(3)
	v_fmac_f32_e32 v85, v222, v32
	v_fmac_f32_e32 v0, v78, v20
	v_or_b32_e32 v32, 0x400, v70
	v_fmac_f32_e32 v4, v75, v9
	v_mul_f32_e32 v2, v73, v2
	v_fmac_f32_e32 v85, v223, v33
	s_waitcnt lgkmcnt(2)
	v_fmac_f32_e32 v0, v79, v24
	v_ashrrev_i32_e32 v33, 31, v32
	v_fmac_f32_e32 v4, v76, v13
	s_waitcnt vmcnt(13)
	v_fmac_f32_e32 v2, v81, v228
	s_waitcnt lgkmcnt(1)
	v_fmac_f32_e32 v0, v80, v28
	v_lshl_add_u64 v[32:33], v[32:33], 2, s[0:1]
	v_fmac_f32_e32 v4, v77, v17
	v_fmac_f32_e32 v2, v74, v6
	global_store_dword v[32:33], v0, off
	v_fmac_f32_e32 v4, v78, v21
	v_or_b32_e32 v0, 0x480, v70
	v_fmac_f32_e32 v2, v75, v10
	v_fmac_f32_e32 v4, v79, v25
	v_ashrrev_i32_e32 v1, 31, v0
	v_fmac_f32_e32 v2, v76, v14
	v_fmac_f32_e32 v4, v80, v29
	v_lshl_add_u64 v[0:1], v[0:1], 2, s[0:1]
	v_fmac_f32_e32 v2, v77, v18
	global_store_dword v[0:1], v4, off
	v_fmac_f32_e32 v2, v78, v22
	v_or_b32_e32 v0, 0x500, v70
	v_fmac_f32_e32 v2, v79, v26
	v_ashrrev_i32_e32 v1, 31, v0
	v_fmac_f32_e32 v2, v80, v30
	v_lshl_add_u64 v[0:1], v[0:1], 2, s[0:1]
	global_store_dword v[0:1], v2, off
	v_mul_f32_e32 v2, v73, v3
	s_waitcnt vmcnt(15)
	v_fmac_f32_e32 v2, v81, v229
	v_fmac_f32_e32 v2, v74, v7
	v_fmac_f32_e32 v2, v75, v11
	v_fmac_f32_e32 v2, v76, v15
	v_fmac_f32_e32 v2, v77, v19
	v_fmac_f32_e32 v2, v78, v23
	v_or_b32_e32 v0, 0x580, v70
	v_fmac_f32_e32 v2, v79, v27
	v_ashrrev_i32_e32 v1, 31, v0
	v_fmac_f32_e32 v2, v80, v31
	v_lshl_add_u64 v[0:1], v[0:1], 2, s[0:1]
	global_store_dword v[0:1], v2, off
	ds_read_b128 v[0:3], v93 offset:2096
	ds_read_b128 v[4:7], v93 offset:2352
	v_fma_f32 v87, v218, v40, 0
	v_fma_f32 v88, v218, v44, 0
	v_fma_f32 v89, v218, v48, 0
	v_fma_f32 v90, v218, v52, 0
	v_fma_f32 v91, v218, v56, 0
	v_fma_f32 v92, v218, v60, 0
	ds_read_b128 v[8:11], v93 offset:2608
	ds_read_b128 v[12:15], v93 offset:2864
	v_fmac_f32_e32 v87, v219, v41
	v_fmac_f32_e32 v88, v219, v45
	v_fmac_f32_e32 v89, v219, v49
	v_fmac_f32_e32 v90, v219, v53
	v_fmac_f32_e32 v91, v219, v57
	v_fmac_f32_e32 v92, v219, v61
	v_fmac_f32_e32 v87, v220, v42
	v_fmac_f32_e32 v88, v220, v46
	v_fmac_f32_e32 v89, v220, v50
	v_fmac_f32_e32 v90, v220, v54
	v_fmac_f32_e32 v91, v220, v58
	v_fmac_f32_e32 v92, v220, v62
	v_fmac_f32_e32 v85, v224, v34
	s_waitcnt lgkmcnt(3)
	v_mul_f32_e32 v0, v73, v0
	ds_read_b128 v[16:19], v93 offset:3120
	ds_read_b128 v[20:23], v93 offset:3376
	v_fmac_f32_e32 v87, v221, v43
	v_fmac_f32_e32 v88, v221, v47
	v_fmac_f32_e32 v89, v221, v51
	v_fmac_f32_e32 v90, v221, v55
	v_fmac_f32_e32 v91, v221, v59
	v_fmac_f32_e32 v92, v221, v63
	ds_read_b128 v[40:43], v93 offset:528
	ds_read_b128 v[44:47], v93 offset:784
	ds_read_b128 v[48:51], v93 offset:1040
	ds_read_b128 v[52:55], v93 offset:1296
	ds_read_b128 v[56:59], v93 offset:1552
	ds_read_b128 v[60:63], v93 offset:1808
	v_fmac_f32_e32 v85, v225, v35
	ds_read_b128 v[32:35], v93 offset:32
	s_waitcnt vmcnt(15)
	v_fmac_f32_e32 v0, v81, v230
	s_waitcnt lgkmcnt(11)
	v_fmac_f32_e32 v0, v74, v4
	ds_read_b128 v[24:27], v93 offset:3632
	ds_read_b128 v[28:31], v93 offset:3888
	v_fmac_f32_e32 v86, v222, v36
	s_waitcnt lgkmcnt(12)
	v_fmac_f32_e32 v0, v75, v8
	v_mul_f32_e32 v4, v73, v1
	v_fmac_f32_e32 v86, v223, v37
	s_waitcnt lgkmcnt(11)
	v_fmac_f32_e32 v0, v76, v12
	s_waitcnt vmcnt(14)
	v_fmac_f32_e32 v4, v81, v231
	v_fmac_f32_e32 v86, v224, v38
	s_waitcnt lgkmcnt(10)
	v_fmac_f32_e32 v0, v77, v16
	v_fmac_f32_e32 v4, v74, v5
	s_waitcnt lgkmcnt(8)
	v_fmac_f32_e32 v87, v222, v40
	s_waitcnt lgkmcnt(7)
	v_fmac_f32_e32 v88, v222, v44
	s_waitcnt lgkmcnt(6)
	v_fmac_f32_e32 v89, v222, v48
	s_waitcnt lgkmcnt(5)
	v_fmac_f32_e32 v90, v222, v52
	s_waitcnt lgkmcnt(4)
	v_fmac_f32_e32 v91, v222, v56
	s_waitcnt lgkmcnt(3)
	v_fmac_f32_e32 v92, v222, v60
	v_fmac_f32_e32 v86, v225, v39
	ds_read_b128 v[36:39], v93 offset:288
	s_waitcnt lgkmcnt(3)
	v_fmac_f32_e32 v85, v226, v32
	v_fmac_f32_e32 v0, v78, v20
	v_or_b32_e32 v32, 0x600, v70
	v_fmac_f32_e32 v4, v75, v9
	v_mul_f32_e32 v2, v73, v2
	v_fmac_f32_e32 v87, v223, v41
	v_fmac_f32_e32 v88, v223, v45
	v_fmac_f32_e32 v89, v223, v49
	v_fmac_f32_e32 v90, v223, v53
	v_fmac_f32_e32 v91, v223, v57
	v_fmac_f32_e32 v92, v223, v61
	v_fmac_f32_e32 v85, v227, v33
	s_waitcnt lgkmcnt(2)
	v_fmac_f32_e32 v0, v79, v24
	v_ashrrev_i32_e32 v33, 31, v32
	v_fmac_f32_e32 v4, v76, v13
	s_waitcnt vmcnt(13)
	v_fmac_f32_e32 v2, v81, v232
	v_fmac_f32_e32 v87, v224, v42
	v_fmac_f32_e32 v88, v224, v46
	v_fmac_f32_e32 v89, v224, v50
	v_fmac_f32_e32 v90, v224, v54
	v_fmac_f32_e32 v91, v224, v58
	v_fmac_f32_e32 v92, v224, v62
	s_waitcnt lgkmcnt(1)
; DEV void ret_sample_item(const Params& p, int l, int item, unsigned char* smem) {
;     ...
;     for (int dd = 0; dd < 16; ++dd) {
;       const int d = dg * 16 + dd;
;       const float s0 = s0v[dd];
;       float a = cdec * s0;
; #pragma unroll
;       for (int j = 0; j < 8; ++j) a += ks[j * 64 + d] * kv[j];
;       Sn[d * 128 + e] = a;
; #pragma unroll
;       for (int i = 0; i < 8; ++i) po[i] += qs[i * 64 + d] * s0;
;     }
; #pragma unroll
;     for (int i = 0; i < 8; ++i) part[(dg * 8 + i) * 128 + e] = po[i];
;   }
;   __syncthreads();
;   {
;     const int i = w;
;     const float qd = __expf(lg * (float)(i + 1));
;     float o[2]; float ss = 0.f;
; #pragma unroll
;     for (int c = 0; c < 2; ++c) {
;       const int e = lane + c * 64;
;       float a = qd * (part[(0 * 8 + i) * 128 + e] + part[(1 * 8 + i) * 128 + e] + part[(2 * 8 + i) * 128 + e] + part[(3 * 8 + i) * 128 + e]);
;       for (int j = 0; j <= i; ++j) a += inn[i * 8 + j] * vs[j * 128 + e];
	v_fmac_f32_e32 v0, v80, v28
	v_lshl_add_u64 v[32:33], v[32:33], 2, s[0:1]
	v_fmac_f32_e32 v4, v77, v17
	v_fmac_f32_e32 v2, v74, v6
	v_fmac_f32_e32 v87, v225, v43
	v_fmac_f32_e32 v88, v225, v47
	v_fmac_f32_e32 v89, v225, v51
	v_fmac_f32_e32 v90, v225, v55
	v_fmac_f32_e32 v91, v225, v59
	v_fmac_f32_e32 v92, v225, v63
	ds_read_b128 v[40:43], v93 offset:544
	ds_read_b128 v[44:47], v93 offset:800
	ds_read_b128 v[48:51], v93 offset:1056
	ds_read_b128 v[52:55], v93 offset:1312
	ds_read_b128 v[56:59], v93 offset:1568
	ds_read_b128 v[60:63], v93 offset:1824
	global_store_dword v[32:33], v0, off
	v_fmac_f32_e32 v4, v78, v21
	v_or_b32_e32 v0, 0x680, v70
	v_fmac_f32_e32 v2, v75, v10
	v_fmac_f32_e32 v4, v79, v25
	v_ashrrev_i32_e32 v1, 31, v0
	v_fmac_f32_e32 v2, v76, v14
	v_fmac_f32_e32 v4, v80, v29
	v_lshl_add_u64 v[0:1], v[0:1], 2, s[0:1]
	v_fmac_f32_e32 v2, v77, v18
	global_store_dword v[0:1], v4, off
	v_fmac_f32_e32 v2, v78, v22
	v_or_b32_e32 v0, 0x700, v70
	s_waitcnt lgkmcnt(6)
	v_fmac_f32_e32 v86, v226, v36
	v_fmac_f32_e32 v2, v79, v26
	v_ashrrev_i32_e32 v1, 31, v0
	s_waitcnt lgkmcnt(5)
	v_fmac_f32_e32 v87, v226, v40
	s_waitcnt lgkmcnt(4)
	v_fmac_f32_e32 v88, v226, v44
	s_waitcnt lgkmcnt(3)
	v_fmac_f32_e32 v89, v226, v48
	s_waitcnt lgkmcnt(2)
	v_fmac_f32_e32 v90, v226, v52
	s_waitcnt lgkmcnt(1)
	v_fmac_f32_e32 v91, v226, v56
	s_waitcnt lgkmcnt(0)
	v_fmac_f32_e32 v92, v226, v60
	v_fmac_f32_e32 v86, v227, v37
	v_fmac_f32_e32 v2, v80, v30
	v_lshl_add_u64 v[0:1], v[0:1], 2, s[0:1]
	v_fmac_f32_e32 v87, v227, v41
	v_fmac_f32_e32 v88, v227, v45
	v_fmac_f32_e32 v89, v227, v49
	v_fmac_f32_e32 v90, v227, v53
	v_fmac_f32_e32 v91, v227, v57
	v_fmac_f32_e32 v92, v227, v61
	v_fmac_f32_e32 v85, v228, v34
	v_fmac_f32_e32 v86, v228, v38
	global_store_dword v[0:1], v2, off
	v_mul_f32_e32 v2, v73, v3
	v_fmac_f32_e32 v87, v228, v42
	v_fmac_f32_e32 v88, v228, v46
	v_fmac_f32_e32 v89, v228, v50
	v_fmac_f32_e32 v90, v228, v54
	v_fmac_f32_e32 v91, v228, v58
	v_fmac_f32_e32 v92, v228, v62
	v_fmac_f32_e32 v85, v229, v35
	v_fmac_f32_e32 v86, v229, v39
	ds_read_b128 v[32:35], v93 offset:48
	ds_read_b128 v[36:39], v93 offset:304
	s_waitcnt vmcnt(15)
	v_fmac_f32_e32 v2, v81, v233
	v_fmac_f32_e32 v87, v229, v43
	v_fmac_f32_e32 v88, v229, v47
	v_fmac_f32_e32 v89, v229, v51
	v_fmac_f32_e32 v90, v229, v55
	v_fmac_f32_e32 v91, v229, v59
	v_fmac_f32_e32 v92, v229, v63
	ds_read_b128 v[40:43], v93 offset:560
	ds_read_b128 v[44:47], v93 offset:816
	ds_read_b128 v[48:51], v93 offset:1072
	ds_read_b128 v[52:55], v93 offset:1328
	ds_read_b128 v[56:59], v93 offset:1584
	ds_read_b128 v[60:63], v93 offset:1840
	v_fmac_f32_e32 v2, v74, v7
	v_fmac_f32_e32 v2, v75, v11
	v_fmac_f32_e32 v2, v76, v15
	v_fmac_f32_e32 v2, v77, v19
	s_waitcnt lgkmcnt(7)
	v_fmac_f32_e32 v85, v230, v32
	s_waitcnt lgkmcnt(6)
	v_fmac_f32_e32 v86, v230, v36
	v_fmac_f32_e32 v2, v78, v23
	v_or_b32_e32 v0, 0x780, v70
	s_waitcnt lgkmcnt(5)
	v_fmac_f32_e32 v87, v230, v40
	s_waitcnt lgkmcnt(4)
	v_fmac_f32_e32 v88, v230, v44
	s_waitcnt lgkmcnt(3)
	v_fmac_f32_e32 v89, v230, v48
	s_waitcnt lgkmcnt(2)
	v_fmac_f32_e32 v90, v230, v52
	s_waitcnt lgkmcnt(1)
	v_fmac_f32_e32 v91, v230, v56
	s_waitcnt lgkmcnt(0)
	v_fmac_f32_e32 v92, v230, v60
	v_fmac_f32_e32 v85, v231, v33
	v_fmac_f32_e32 v86, v231, v37
	v_fmac_f32_e32 v2, v79, v27
	v_ashrrev_i32_e32 v1, 31, v0
	v_fmac_f32_e32 v87, v231, v41
	v_fmac_f32_e32 v88, v231, v45
	v_fmac_f32_e32 v89, v231, v49
	v_fmac_f32_e32 v90, v231, v53
	v_fmac_f32_e32 v91, v231, v57
	v_fmac_f32_e32 v92, v231, v61
	v_fmac_f32_e32 v85, v232, v34
	v_fmac_f32_e32 v86, v232, v38
	v_fmac_f32_e32 v2, v80, v31
	v_lshl_add_u64 v[0:1], v[0:1], 2, s[0:1]
	v_fmac_f32_e32 v87, v232, v42
	v_fmac_f32_e32 v88, v232, v46
	v_fmac_f32_e32 v89, v232, v50
	v_fmac_f32_e32 v90, v232, v54
	v_fmac_f32_e32 v91, v232, v58
	v_fmac_f32_e32 v92, v232, v62
	global_store_dword v[0:1], v2, off
	v_fmac_f32_e32 v85, v233, v35
	v_fmac_f32_e32 v86, v233, v39
	v_lshl_add_u32 v0, v68, 12, v69
	v_add_u32_e32 v2, 1, v66
	v_fmac_f32_e32 v87, v233, v43
	v_fmac_f32_e32 v88, v233, v47
	v_fmac_f32_e32 v89, v233, v51
	v_fmac_f32_e32 v90, v233, v55
	v_fmac_f32_e32 v91, v233, v59
	v_fmac_f32_e32 v92, v233, v63
	ds_write2st64_b32 v0, v85, v86 offset0:33 offset1:35
	ds_write2st64_b32 v0, v87, v88 offset0:37 offset1:39
	ds_write2st64_b32 v0, v89, v90 offset0:41 offset1:43
	ds_write2st64_b32 v0, v91, v92 offset0:45 offset1:47
	v_cvt_f32_i32_e32 v0, v2
	v_lshlrev_b32_e32 v4, 2, v72
	s_waitcnt lgkmcnt(0)
	s_barrier
	v_mul_f32_e32 v0, v67, v0
	v_mul_f32_e32 v0, 0x3fb8aa3b, v0
	v_exp_f32_e32 v1, v0
	v_lshlrev_b32_e32 v0, 9, v66
	v_add3_u32 v4, 0, v0, v4
	ds_read2st64_b32 v[6:7], v4 offset0:33 offset1:49
	v_lshlrev_b32_e32 v3, 5, v66
	s_waitcnt lgkmcnt(0)
	v_add_f32_e32 v0, v6, v7
	ds_read2st64_b32 v[6:7], v4 offset0:65 offset1:81
	s_waitcnt lgkmcnt(0)
	v_add_f32_e32 v0, v0, v6
	v_add_f32_e32 v0, v0, v7
	v_mul_f32_e32 v0, v1, v0
	s_and_saveexec_b64 s[2:3], vcc
	s_cbranch_execz .LBB0_360
	s_add_i32 s0, 0, 0x2000
	v_add_u32_e32 v5, s0, v3
	s_add_i32 s0, 0, 0x1000
	v_lshl_add_u32 v6, v72, 2, s0
	s_mov_b64 s[4:5], 0
	v_mov_b32_e32 v7, v2

; DEV void attn_prompt_group(const Params& p, int l, int item, unsigned char* smem) {
;     ...
;     for (int t = 0; t < 9; ++t)
; #pragma unroll
;       for (int j = 0; j < 4; ++j) {
;         const int si = (w + t) * 16 + fq * 4 + j;
;         const bool ok = (si > qi) && (si <= 128 + qi) && (nb > 0 || si >= 128);
;         const float sc = ok ? s[t][j] * 0.125f - slope * (float)(128 + qi - si) : -INFINITY;
;         s[t][j] = sc; mx = fmaxf(mx, sc);
;       }
;     mx = fmaxf(mx, __shfl_xor(mx, 16)); mx = fmaxf(mx, __shfl_xor(mx, 32));
;     float sum = 0.f;
; #pragma unroll
;     for (int t = 0; t < 9; ++t)
; #pragma unroll
;       for (int j = 0; j < 4; ++j) { const float e = __expf(s[t][j] - mx); s[t][j] = e; sum += e; }
.Lattn_nos:
	v_pk_mul_f32 v[186:187], v[108:109], s[38:39]
	v_pk_mul_f32 v[188:189], v[110:111], s[38:39]
	v_pk_mul_f32 v[190:191], v[112:113], s[38:39]
	v_pk_mul_f32 v[192:193], v[114:115], s[38:39]
	v_fma_f32 v161, v164, v178, v186
	v_fma_f32 v162, v165, v178, v187
	v_fma_f32 v163, v166, v178, v188
	v_fma_f32 v164, v167, v178, v189
	v_fma_f32 v165, v180, v178, v190
	v_fma_f32 v166, v181, v178, v191
	v_fma_f32 v167, v182, v178, v192
	v_fma_f32 v168, v183, v178, v193
	v_pk_mul_f32 v[186:187], v[116:117], s[38:39]
	v_pk_mul_f32 v[188:189], v[118:119], s[38:39]
	v_pk_fma_f32 v[96:97], v[96:97], s[36:37], v[186:187]
	v_pk_fma_f32 v[98:99], v[98:99], s[36:37], v[188:189]
	v_pk_mul_f32 v[190:191], v[120:121], s[38:39]
	v_pk_mul_f32 v[192:193], v[122:123], s[38:39]
	v_pk_fma_f32 v[92:93], v[92:93], s[36:37], v[190:191]
	v_pk_fma_f32 v[94:95], v[94:95], s[36:37], v[192:193]
	v_pk_mul_f32 v[186:187], v[124:125], s[38:39]
	v_pk_mul_f32 v[188:189], v[126:127], s[38:39]
	v_pk_fma_f32 v[88:89], v[88:89], s[36:37], v[186:187]
	v_pk_fma_f32 v[90:91], v[90:91], s[36:37], v[188:189]
	v_pk_mul_f32 v[190:191], v[128:129], s[38:39]
	v_pk_mul_f32 v[192:193], v[130:131], s[38:39]
	v_pk_fma_f32 v[84:85], v[84:85], s[36:37], v[190:191]
	v_pk_fma_f32 v[86:87], v[86:87], s[36:37], v[192:193]
	v_pk_mul_f32 v[186:187], v[132:133], s[38:39]
	v_pk_mul_f32 v[188:189], v[134:135], s[38:39]
	v_pk_fma_f32 v[80:81], v[80:81], s[36:37], v[186:187]
	v_pk_fma_f32 v[82:83], v[82:83], s[36:37], v[188:189]
	v_pk_mul_f32 v[190:191], v[136:137], s[38:39]
	v_pk_mul_f32 v[192:193], v[138:139], s[38:39]
	v_pk_fma_f32 v[76:77], v[76:77], s[36:37], v[190:191]
	v_pk_fma_f32 v[78:79], v[78:79], s[36:37], v[192:193]
	v_pk_mul_f32 v[186:187], v[140:141], s[38:39]
	v_pk_mul_f32 v[188:189], v[142:143], s[38:39]
	v_pk_fma_f32 v[72:73], v[72:73], s[36:37], v[186:187]
	v_pk_fma_f32 v[74:75], v[74:75], s[36:37], v[188:189]
	v_max3_f32 v186, v160, v161, v162
	v_max3_f32 v187, v163, v164, v165
	v_max3_f32 v186, v186, v166, v167
	v_max3_f32 v187, v187, v168, v96
	v_max3_f32 v186, v186, v97, v98
	v_max3_f32 v187, v187, v99, v92
	v_max3_f32 v186, v186, v93, v94
	v_max3_f32 v187, v187, v95, v88
	v_max3_f32 v186, v186, v89, v90
	v_max3_f32 v187, v187, v91, v84
	v_max3_f32 v186, v186, v85, v86
	v_max3_f32 v187, v187, v87, v80
	v_max3_f32 v186, v186, v81, v82
	v_max3_f32 v187, v187, v83, v76
	v_max3_f32 v186, v186, v77, v78
	v_max3_f32 v187, v187, v79, v72
	v_and_b32_e32 v177, 64, v202
	v_max3_f32 v186, v186, v73, v74
	v_max3_f32 v104, v186, v187, v75
	s_nop 0
	v_mov_b32_e32 v180, v104
	v_mov_b32_e32 v181, v104
	s_nop 1
	v_permlane16_swap_b32_e32 v180, v181
	s_nop 0
	v_max_f32_e32 v104, v180, v181
	s_nop 0
	v_mov_b32_e32 v180, v104
	v_mov_b32_e32 v181, v104
	s_nop 1
	v_permlane32_swap_b32_e32 v180, v181
	s_nop 0
	v_max_f32_e32 v104, v180, v181
	v_sub_f32_e32 v161, v161, v104
	v_mul_f32_e32 v161, 0x3fb8aa3b, v161
	v_sub_f32_e32 v162, v162, v104
	v_exp_f32_e32 v161, v161
	v_mul_f32_e32 v162, 0x3fb8aa3b, v162
	v_sub_f32_e32 v163, v163, v104
	v_exp_f32_e32 v162, v162
	v_mul_f32_e32 v163, 0x3fb8aa3b, v163
	v_sub_f32_e32 v164, v164, v104
	v_exp_f32_e32 v163, v163
	v_mul_f32_e32 v164, 0x3fb8aa3b, v164
	v_sub_f32_e32 v165, v165, v104
	v_exp_f32_e32 v164, v164
	v_mul_f32_e32 v165, 0x3fb8aa3b, v165
	v_sub_f32_e32 v166, v166, v104
	v_add_f32_e32 v180, 0, v161
	v_exp_f32_e32 v165, v165
	v_mul_f32_e32 v166, 0x3fb8aa3b, v166
	v_sub_f32_e32 v167, v167, v104
	v_add_f32_e32 v180, v162, v180
	v_exp_f32_e32 v166, v166
	v_mul_f32_e32 v167, 0x3fb8aa3b, v167
	v_sub_f32_e32 v168, v168, v104
	v_add_f32_e32 v180, v163, v180
	v_exp_f32_e32 v167, v167
	v_mul_f32_e32 v168, 0x3fb8aa3b, v168
	v_sub_f32_e32 v96, v96, v104
	v_add_f32_e32 v180, v164, v180
	v_exp_f32_e32 v168, v168
	v_mul_f32_e32 v96, 0x3fb8aa3b, v96
	v_sub_f32_e32 v97, v97, v104
	v_add_f32_e32 v180, v165, v180
	v_exp_f32_e32 v96, v96
	v_mul_f32_e32 v97, 0x3fb8aa3b, v97
	v_sub_f32_e32 v98, v98, v104
	v_add_f32_e32 v180, v166, v180
	v_exp_f32_e32 v97, v97
	v_mul_f32_e32 v98, 0x3fb8aa3b, v98
	v_sub_f32_e32 v99, v99, v104
	v_add_f32_e32 v180, v167, v180
	v_exp_f32_e32 v98, v98
	v_mul_f32_e32 v99, 0x3fb8aa3b, v99
	v_sub_f32_e32 v92, v92, v104
	v_add_f32_e32 v180, v168, v180
	v_exp_f32_e32 v99, v99
	v_mul_f32_e32 v92, 0x3fb8aa3b, v92
	v_sub_f32_e32 v93, v93, v104
	v_add_f32_e32 v180, v96, v180
	v_exp_f32_e32 v92, v92
	v_mul_f32_e32 v93, 0x3fb8aa3b, v93
	v_sub_f32_e32 v94, v94, v104
	v_add_f32_e32 v180, v97, v180
	v_exp_f32_e32 v93, v93
	v_mul_f32_e32 v94, 0x3fb8aa3b, v94
	v_sub_f32_e32 v95, v95, v104
	v_add_f32_e32 v180, v98, v180
	v_exp_f32_e32 v94, v94
	v_mul_f32_e32 v95, 0x3fb8aa3b, v95
	v_sub_f32_e32 v88, v88, v104
	v_add_f32_e32 v180, v99, v180
	v_exp_f32_e32 v95, v95
	v_mul_f32_e32 v88, 0x3fb8aa3b, v88
	v_add_f32_e32 v180, v92, v180
	v_exp_f32_e32 v181, v88
	v_add_f32_e32 v180, v93, v180
	v_add_f32_e32 v180, v94, v180
	v_sub_f32_e32 v89, v89, v104
	v_add_f32_e32 v180, v95, v180
	v_mul_f32_e32 v89, 0x3fb8aa3b, v89
	v_add_f32_e32 v88, v181, v180
	v_exp_f32_e32 v180, v89
	v_sub_f32_e32 v89, v90, v104
	v_mul_f32_e32 v89, 0x3fb8aa3b, v89
	v_exp_f32_e32 v182, v89
	v_sub_f32_e32 v89, v91, v104
	v_sub_f32_e32 v85, v85, v104
	v_mul_f32_e32 v89, 0x3fb8aa3b, v89
	v_sub_f32_e32 v84, v84, v104
	v_mul_f32_e32 v85, 0x3fb8aa3b, v85
	v_exp_f32_e32 v183, v89
	v_mul_f32_e32 v84, 0x3fb8aa3b, v84
	v_exp_f32_e32 v185, v85
	v_sub_f32_e32 v85, v86, v104
	v_exp_f32_e32 v184, v84
	v_mul_f32_e32 v85, 0x3fb8aa3b, v85
	v_add_f32_e32 v88, v180, v88
	v_exp_f32_e32 v186, v85
	v_sub_f32_e32 v85, v87, v104
	v_sub_f32_e32 v81, v81, v104
	v_add_f32_e32 v88, v182, v88
	v_mul_f32_e32 v85, 0x3fb8aa3b, v85
; DEV f32x4 mfma16(bf16x4 a, bf16x4 b, f32x4 c) { return __builtin_amdgcn_mfma_f32_16x16x16bf16_1k(a, b, c, 0, 0, 0); }
; DEV void attn_prompt_group(const Params& p, int l, int item, unsigned char* smem) {
;     ...
;     for (int t = 0; t < 9; ++t)
; #pragma unroll
;       for (int j = 0; j < 4; ++j) { const float e = __expf(s[t][j] - mx); s[t][j] = e; sum += e; }
;     sum += __shfl_xor(sum, 16); sum += __shfl_xor(sum, 32);
;     const float denom = sum + __expf(sink - mx);
;     f32x4 o[4];
; #pragma unroll
;     for (int dt = 0; dt < 4; ++dt) o[dt] = (f32x4){0.f, 0.f, 0.f, 0.f};
; #pragma unroll
;     for (int t = 0; t < 9; ++t) {
;       const bf16x4 pf = pack4(s[t][0], s[t][1], s[t][2], s[t][3]);
; #pragma unroll
;       for (int dt = 0; dt < 4; ++dt) {
;         const bf16x4 vf = *(const bf16x4*)(Vt + (dt * 16 + fr) * 264 + (w + t) * 16 + fq * 4);
;         o[dt] = mfma16(pf, vf, o[dt]);
;       }
;     }
	v_sub_f32_e32 v80, v80, v104
	v_mul_f32_e32 v81, 0x3fb8aa3b, v81
	v_add_f32_e32 v88, v183, v88
	v_exp_f32_e32 v187, v85
	v_mul_f32_e32 v80, 0x3fb8aa3b, v80
	v_exp_f32_e32 v189, v81
	v_sub_f32_e32 v81, v82, v104
	v_add_f32_e32 v84, v184, v88
	v_exp_f32_e32 v188, v80
	v_mul_f32_e32 v81, 0x3fb8aa3b, v81
	v_add_f32_e32 v84, v185, v84
	v_exp_f32_e32 v190, v81
	v_sub_f32_e32 v81, v83, v104
	v_sub_f32_e32 v77, v77, v104
	v_add_f32_e32 v84, v186, v84
	v_mul_f32_e32 v81, 0x3fb8aa3b, v81
	v_sub_f32_e32 v76, v76, v104
	v_mul_f32_e32 v77, 0x3fb8aa3b, v77
	v_add_f32_e32 v84, v187, v84
	v_exp_f32_e32 v191, v81
	v_mul_f32_e32 v76, 0x3fb8aa3b, v76
	v_exp_f32_e32 v193, v77
	v_sub_f32_e32 v77, v78, v104
	v_add_f32_e32 v80, v188, v84
	v_exp_f32_e32 v192, v76
	v_mul_f32_e32 v77, 0x3fb8aa3b, v77
	v_add_f32_e32 v80, v189, v80
	v_exp_f32_e32 v194, v77
	v_sub_f32_e32 v77, v79, v104
	v_sub_f32_e32 v73, v73, v104
	v_add_f32_e32 v80, v190, v80
	v_mul_f32_e32 v77, 0x3fb8aa3b, v77
	v_sub_f32_e32 v72, v72, v104
	v_mul_f32_e32 v73, 0x3fb8aa3b, v73
	v_add_f32_e32 v80, v191, v80
	v_exp_f32_e32 v195, v77
	v_mul_f32_e32 v72, 0x3fb8aa3b, v72
	v_exp_f32_e32 v197, v73
	v_sub_f32_e32 v73, v74, v104
	v_add_f32_e32 v76, v192, v80
	v_exp_f32_e32 v196, v72
	v_mul_f32_e32 v73, 0x3fb8aa3b, v73
	v_add_f32_e32 v76, v193, v76
	v_exp_f32_e32 v198, v73
	v_sub_f32_e32 v73, v75, v104
	v_add_f32_e32 v76, v194, v76
	v_mul_f32_e32 v73, 0x3fb8aa3b, v73
	v_add_f32_e32 v76, v195, v76
	v_exp_f32_e32 v199, v73
	v_add_f32_e32 v72, v196, v76
	v_add_f32_e32 v72, v197, v72
	v_add_f32_e32 v72, v198, v72
	v_add_f32_e32 v72, v199, v72
	v_mov_b32_e32 v73, v72
	v_cvt_pk_bf16_f32 v84, v161, v162
	v_cvt_pk_bf16_f32 v85, v163, v164
	v_permlane16_swap_b32_e32 v72, v73
	v_sub_f32_e32 v74, v160, v104
	v_mul_f32_e32 v74, 0x3fb8aa3b, v74
	v_add_f32_e32 v72, v72, v73
	v_cvt_pk_bf16_f32 v88, v165, v166
	v_cvt_pk_bf16_f32 v89, v167, v168
	v_mov_b32_e32 v73, v72
	ds_read_b64 v[90:91], v148
	v_exp_f32_e32 v104, v74
	s_nop 1
	v_permlane32_swap_b32_e32 v72, v73
	s_nop 0
	v_add_f32_e32 v105, v72, v73
	ds_read_b64 v[72:73], v147
	ds_read_b64 v[76:77], v147 offset:8448
	ds_read_b64 v[80:81], v147 offset:16896
	ds_read_b64 v[86:87], v147 offset:25344
	s_waitcnt lgkmcnt(3)
	v_mfma_f32_16x16x16_bf16 v[72:75], v[84:85], v[72:73], 0
	v_mfma_f32_16x16x16_bf16 v[72:75], v[88:89], v[90:91], v[72:75]
	ds_read_b64 v[90:91], v148 offset:8448
	s_waitcnt lgkmcnt(3)
	v_mfma_f32_16x16x16_bf16 v[76:79], v[84:85], v[76:77], 0
	s_waitcnt lgkmcnt(0)
	v_mfma_f32_16x16x16_bf16 v[76:79], v[88:89], v[90:91], v[76:79]
	ds_read_b64 v[90:91], v148 offset:16896
	v_mfma_f32_16x16x16_bf16 v[80:83], v[84:85], v[80:81], 0
	s_waitcnt lgkmcnt(0)
	v_mfma_f32_16x16x16_bf16 v[80:83], v[88:89], v[90:91], v[80:83]
	ds_read_b64 v[90:91], v148 offset:25344
	v_mfma_f32_16x16x16_bf16 v[84:87], v[84:85], v[86:87], 0
	s_waitcnt lgkmcnt(0)
	v_mfma_f32_16x16x16_bf16 v[84:87], v[88:89], v[90:91], v[84:87]
	ds_read_b64 v[218:219], v149
	ds_read_b64 v[220:221], v149 offset:8448
	ds_read_b64 v[222:223], v149 offset:16896
	ds_read_b64 v[224:225], v149 offset:25344
	v_cvt_pk_bf16_f32 v88, v96, v97
	v_cvt_pk_bf16_f32 v89, v98, v99
	ds_read_b64 v[226:227], v150
	ds_read_b64 v[228:229], v150 offset:8448
	ds_read_b64 v[230:231], v150 offset:16896
	ds_read_b64 v[232:233], v150 offset:25344
	s_waitcnt lgkmcnt(4)
	v_mfma_f32_16x16x16_bf16 v[72:75], v[88:89], v[218:219], v[72:75]
	v_mfma_f32_16x16x16_bf16 v[76:79], v[88:89], v[220:221], v[76:79]
	v_mfma_f32_16x16x16_bf16 v[80:83], v[88:89], v[222:223], v[80:83]
	v_mfma_f32_16x16x16_bf16 v[84:87], v[88:89], v[224:225], v[84:87]
	v_cvt_pk_bf16_f32 v88, v92, v93
	v_cvt_pk_bf16_f32 v89, v94, v95
	ds_read_b64 v[218:219], v151
	ds_read_b64 v[220:221], v151 offset:8448
	ds_read_b64 v[222:223], v151 offset:16896
	ds_read_b64 v[224:225], v151 offset:25344
	s_waitcnt lgkmcnt(4)
	v_mfma_f32_16x16x16_bf16 v[72:75], v[88:89], v[226:227], v[72:75]
	v_mfma_f32_16x16x16_bf16 v[76:79], v[88:89], v[228:229], v[76:79]
	v_mfma_f32_16x16x16_bf16 v[80:83], v[88:89], v[230:231], v[80:83]
	v_mfma_f32_16x16x16_bf16 v[84:87], v[88:89], v[232:233], v[84:87]
	v_cvt_pk_bf16_f32 v88, v181, v180
	v_cvt_pk_bf16_f32 v89, v182, v183
	ds_read_b64 v[226:227], v152
	ds_read_b64 v[228:229], v152 offset:8448
	ds_read_b64 v[230:231], v152 offset:16896
	ds_read_b64 v[232:233], v152 offset:25344
	s_waitcnt lgkmcnt(4)
	v_mfma_f32_16x16x16_bf16 v[72:75], v[88:89], v[218:219], v[72:75]
	v_mfma_f32_16x16x16_bf16 v[76:79], v[88:89], v[220:221], v[76:79]
	v_mfma_f32_16x16x16_bf16 v[80:83], v[88:89], v[222:223], v[80:83]
	v_mfma_f32_16x16x16_bf16 v[84:87], v[88:89], v[224:225], v[84:87]
	v_cvt_pk_bf16_f32 v88, v184, v185
	v_cvt_pk_bf16_f32 v89, v186, v187
	ds_read_b64 v[218:219], v153
	ds_read_b64 v[220:221], v153 offset:8448
	ds_read_b64 v[222:223], v153 offset:16896
	ds_read_b64 v[224:225], v153 offset:25344
	s_waitcnt lgkmcnt(4)
; DEV bf16_t f2bf(float f) { return (bf16_t)(cvt_pk_bf16(f, 0.f) & 0xffffu); }
; DEV f32x4 mfma16(bf16x4 a, bf16x4 b, f32x4 c) { return __builtin_amdgcn_mfma_f32_16x16x16bf16_1k(a, b, c, 0, 0, 0); }
; DEV void attn_prompt_group(const Params& p, int l, int item, unsigned char* smem) {
;     ...
;     for (int t = 0; t < 9; ++t) {
;       const bf16x4 pf = pack4(s[t][0], s[t][1], s[t][2], s[t][3]);
; #pragma unroll
;       for (int dt = 0; dt < 4; ++dt) {
;         const bf16x4 vf = *(const bf16x4*)(Vt + (dt * 16 + fr) * 264 + (w + t) * 16 + fq * 4);
;         o[dt] = mfma16(pf, vf, o[dt]);
;       }
;     }
;     bf16_t* Os = (bf16_t*)(smem + 33792 + w * 2304);
; #pragma unroll
;     for (int j = 0; j < 4; ++j) {
;       const int r = fq * 4 + j;
;       const float inv = 1.0f / __shfl(denom, r);
; #pragma unroll
;       for (int dt = 0; dt < 4; ++dt) Os[r * 72 + dt * 16 + fr] = f2bf(o[dt][j] * inv);
;     }
;     asm volatile("s_waitcnt lgkmcnt(0)" ::: "memory");
; #pragma unroll
;     for (int i = 0; i < 2; ++i) {
;       const int c = lane + i * 64, r = c >> 3, kc = c & 7;
;       const u32x4 v = *(const u32x4*)(Os + r * 72 + kc * 8);
;       *(u32x4*)(Z + (rowbase + w * 16 + r) * NIN + AQ + h * 64 + kc * 8) = v;
;     }
;     asm volatile("s_waitcnt lgkmcnt(0)" ::: "memory");
;   }
	v_mfma_f32_16x16x16_bf16 v[72:75], v[88:89], v[226:227], v[72:75]
	v_mfma_f32_16x16x16_bf16 v[76:79], v[88:89], v[228:229], v[76:79]
	v_mfma_f32_16x16x16_bf16 v[80:83], v[88:89], v[230:231], v[80:83]
	v_mfma_f32_16x16x16_bf16 v[84:87], v[88:89], v[232:233], v[84:87]
	v_cvt_pk_bf16_f32 v88, v188, v189
	v_cvt_pk_bf16_f32 v89, v190, v191
	ds_read_b64 v[226:227], v154
	ds_read_b64 v[228:229], v154 offset:8448
	ds_read_b64 v[230:231], v154 offset:16896
	ds_read_b64 v[232:233], v154 offset:25344
	s_waitcnt lgkmcnt(4)
	v_mfma_f32_16x16x16_bf16 v[72:75], v[88:89], v[218:219], v[72:75]
	v_mfma_f32_16x16x16_bf16 v[76:79], v[88:89], v[220:221], v[76:79]
	v_mfma_f32_16x16x16_bf16 v[80:83], v[88:89], v[222:223], v[80:83]
	v_mfma_f32_16x16x16_bf16 v[84:87], v[88:89], v[224:225], v[84:87]
	v_cvt_pk_bf16_f32 v88, v192, v193
	v_cvt_pk_bf16_f32 v89, v194, v195
	ds_read_b64 v[218:219], v155
	ds_read_b64 v[220:221], v155 offset:8448
	ds_read_b64 v[222:223], v155 offset:16896
	ds_read_b64 v[224:225], v155 offset:25344
	s_waitcnt lgkmcnt(4)
	v_mfma_f32_16x16x16_bf16 v[72:75], v[88:89], v[226:227], v[72:75]
	v_mfma_f32_16x16x16_bf16 v[76:79], v[88:89], v[228:229], v[76:79]
	v_mfma_f32_16x16x16_bf16 v[80:83], v[88:89], v[230:231], v[80:83]
	v_mfma_f32_16x16x16_bf16 v[84:87], v[88:89], v[232:233], v[84:87]
	v_cvt_pk_bf16_f32 v88, v196, v197
	v_cvt_pk_bf16_f32 v89, v198, v199
	s_nop 0
	s_waitcnt lgkmcnt(0)
	v_mfma_f32_16x16x16_bf16 v[72:75], v[88:89], v[218:219], v[72:75]
	v_mfma_f32_16x16x16_bf16 v[76:79], v[88:89], v[220:221], v[76:79]
	v_mfma_f32_16x16x16_bf16 v[80:83], v[88:89], v[222:223], v[80:83]
	v_mfma_f32_16x16x16_bf16 v[84:87], v[88:89], v[224:225], v[84:87]
	v_add_f32_e32 v88, v104, v105
	v_or_b32_e32 v89, v177, v107
	v_div_scale_f32 v90, s[0:1], v88, v88, 1.0
	v_or_b32_e32 v95, v177, v144
	v_rcp_f32_e32 v91, v90
	v_lshlrev_b32_e32 v89, 2, v89
	v_fma_f32 v92, -v90, v91, 1.0
	v_fmac_f32_e32 v91, v92, v91
	v_div_scale_f32 v92, vcc, 1.0, v88, 1.0
	v_mul_f32_e32 v93, v92, v91
	v_fma_f32 v94, -v90, v93, v92
	v_fmac_f32_e32 v93, v94, v91
	v_fma_f32 v90, -v90, v93, v92
	v_div_fmas_f32 v90, v90, v91, v93
	v_div_fixup_f32 v88, v90, v88, 1.0
	v_or_b32_e32 v90, v177, v145
	v_or_b32_e32 v91, v177, v146
	v_lshlrev_b32_e32 v95, 2, v95
	v_lshlrev_b32_e32 v90, 2, v90
	v_lshlrev_b32_e32 v91, 2, v91
	ds_bpermute_b32 v89, v89, v88
	ds_bpermute_b32 v95, v95, v88
	ds_bpermute_b32 v90, v90, v88
	ds_bpermute_b32 v91, v91, v88
	s_waitcnt lgkmcnt(3)
	v_mul_f32_e32 v72, v72, v89
	v_mul_f32_e32 v76, v76, v89
	v_mul_f32_e32 v80, v80, v89
	v_mul_f32_e32 v84, v84, v89
	s_waitcnt lgkmcnt(2)
	v_mul_f32_e32 v73, v73, v95
	v_mul_f32_e32 v77, v77, v95
	v_mul_f32_e32 v81, v81, v95
	v_mul_f32_e32 v85, v85, v95
	s_waitcnt lgkmcnt(1)
	v_mul_f32_e32 v74, v74, v90
	v_mul_f32_e32 v78, v78, v90
	v_mul_f32_e32 v82, v82, v90
	v_mul_f32_e32 v86, v86, v90
	s_waitcnt lgkmcnt(0)
	v_mul_f32_e32 v75, v75, v91
	v_mul_f32_e32 v79, v79, v91
	v_mul_f32_e32 v83, v83, v91
	v_mul_f32_e32 v87, v87, v91
	v_cvt_pk_bf16_f32 v72, v72, v76
	v_cvt_pk_bf16_f32 v80, v80, v84
	ds_write_b16 v156, v72 offset:33792
	ds_write_b16_d16_hi v156, v72 offset:33824
	ds_write_b16 v156, v80 offset:33856
	ds_write_b16_d16_hi v156, v80 offset:33888
	v_cvt_pk_bf16_f32 v73, v73, v77
	v_cvt_pk_bf16_f32 v81, v81, v85
	ds_write_b16 v157, v73 offset:33792
	ds_write_b16_d16_hi v157, v73 offset:33824
	ds_write_b16 v157, v81 offset:33856
	ds_write_b16_d16_hi v157, v81 offset:33888
	v_cvt_pk_bf16_f32 v74, v74, v78
	v_cvt_pk_bf16_f32 v82, v82, v86
	ds_write_b16 v157, v74 offset:33936
	ds_write_b16_d16_hi v157, v74 offset:33968
	ds_write_b16 v157, v82 offset:34000
	ds_write_b16_d16_hi v157, v82 offset:34032
	v_cvt_pk_bf16_f32 v75, v75, v79
	v_cvt_pk_bf16_f32 v83, v83, v87
	ds_write_b16 v157, v75 offset:34080
	ds_write_b16_d16_hi v157, v75 offset:34112
	ds_write_b16 v157, v83 offset:34144
	ds_write_b16_d16_hi v157, v83 offset:34176
	s_waitcnt lgkmcnt(0)
	ds_read_b128 v[72:75], v158 offset:33792
	v_lshl_add_u64 v[76:77], v[100:101], 0, s[90:91]
	s_mov_b32 s0, 0x4700000
	v_add_co_u32_e32 v78, vcc, s0, v76
	s_mov_b32 s0, 0x471b000
	s_nop 0
	v_addc_co_u32_e32 v79, vcc, 0, v77, vcc
	s_waitcnt lgkmcnt(0)
	global_store_dwordx4 v[78:79], v[72:75], off offset:3072
	ds_read_b128 v[72:75], v159 offset:33792
	v_add_co_u32_e32 v76, vcc, s0, v76
	s_add_u32 s90, s90, 0x80
	s_nop 0
	v_addc_co_u32_e32 v77, vcc, 0, v77, vcc
	s_waitcnt lgkmcnt(0)
	global_store_dwordx4 v[76:77], v[72:75], off offset:3072
	s_addc_u32 s91, s91, 0
	s_waitcnt lgkmcnt(0)
	s_add_u32 s18, s18, 4
	s_addc_u32 s19, s19, 0
	s_add_i32 s6, s6, 1
	s_waitcnt vmcnt(2)
	s_cmpk_lg_i32 s90, 0x200
	s_cbranch_scc1 .LBB0_477
	v_readlane_b32 s76, v248, 47
	v_readlane_b32 s77, v248, 48
	v_readlane_b32 s78, v248, 49
	v_readlane_b32 s79, v248, 50
	v_readlane_b32 s80, v248, 51
	v_readlane_b32 s81, v248, 52
	v_readlane_b32 s82, v248, 53
	v_readlane_b32 s83, v248, 54
	v_readlane_b32 s84, v248, 55
	v_readlane_b32 s85, v248, 56
	v_readlane_b32 s86, v248, 57
	v_readlane_b32 s87, v248, 58
	v_readlane_b32 s88, v248, 59
	v_readlane_b32 s89, v248, 60
	v_readlane_b32 s90, v248, 61
	v_readlane_b32 s91, v248, 62
	s_movk_i32 s75, 0x900
	s_barrier
	s_branch .LBB0_428
